# speedup vs baseline: 1.0132x; 1.0045x over previous
; #define PG8_STAGE(bufoff, gbase, voff) do { _Pragma("unroll") for (int _i = 0; _i < 2; ++_i) \
;         __builtin_amdgcn_global_load_lds((const unsigned*)((const char*)(gbase) + (voff)[_i]), (PG8_LAS unsigned*)(lds + (bufoff) + ldsw + _i * 8192), 16, 0, 0); } while (0)
; #define PG8_LDA(dst, b, h) do { _Pragma("unroll") for (int m = 0; m < 4; ++m) _Pragma("unroll") for (int k = 0; k < 2; ++k) dst[m][k] = *(const PG8_LAS bf16x8*)(lds + PG8_SA(b, h) + aoff + m * 2048 + k * 1024); } while (0)
; #define PG8_LDB(dst, b, h) do { _Pragma("unroll") for (int n = 0; n < 2; ++n) _Pragma("unroll") for (int k = 0; k < 2; ++k) dst[n][k] = *(const PG8_LAS bf16x8*)(lds + PG8_SB(b, h) + boff + n * 2048 + k * 1024); } while (0)
; #define PG8_MMA(ai, bj, At, Bt) do { __builtin_amdgcn_s_setprio(3); _Pragma("unroll") for (int m = 0; m < 4; ++m) _Pragma("unroll") for (int n = 0; n < 2; ++n) _Pragma("unroll") for (int k = 0; k < 2; ++k) \
;         acc[ai][bj][m][n] = __builtin_amdgcn_mfma_f32_16x16x32_bf16(Bt[n][k], At[m][k], acc[ai][bj][m][n], 0, 0, 0); __builtin_amdgcn_s_setprio(0); } while (0)
; #define PG8_WAIT_V(n) asm volatile("s_waitcnt vmcnt(" #n ")" ::: "memory")
; #define PG8_WAIT_L(n) asm volatile("s_waitcnt lgkmcnt(" #n ")" ::: "memory")
; #define PG8_BAR __builtin_amdgcn_s_barrier()
; #define PG8_SCHED __builtin_amdgcn_sched_barrier(0)
; template <class Epi, class Sched, bool ALIGN_EPI = false, bool SP2 = false>
; __device__ __forceinline__ void gemm_phase(PG8_LAS unsigned char* lds, const Gemm g, const Sched& S, const Epi& E) {
;     ...
;             PG8_LDB(B0, 0, 0); PG8_LDB(B1, 0, 1); PG8_SCHED; PG8_LDA(At, 0, 0); PG8_STAGE(PG8_SA(1, 1), a1 + hstep, voffA);
;             PG8_WAIT_V(8); PG8_WAIT_L(0); PG8_BAR; PG8_MMA(0, 0, At, B0); PG8_MMA(0, 1, At, B1); PG8_BAR; PG8_SCHED;
;             PG8_LDA(At, 0, 1); PG8_STAGE(PG8_SB(0, 0), b2, voffB); PG8_STAGE(PG8_SB(0, 1), b2 + hstep, voffB); PG8_STAGE(PG8_SA(0, 0), a2, voffA);
;             PG8_WAIT_V(8); PG8_WAIT_L(0); PG8_BAR; PG8_MMA(1, 0, At, B0); PG8_MMA(1, 1, At, B1); PG8_BAR; PG8_SCHED;
.LBB0_70:
	ds_read_b128 v[148:151], v153
	ds_read_b128 v[156:159], v153 offset:1024
	ds_read_b128 v[160:163], v153 offset:2048
	ds_read_b128 v[168:171], v153 offset:3072
	ds_read_b128 v[172:175], v154
	ds_read_b128 v[176:179], v154 offset:1024
	ds_read_b128 v[180:183], v154 offset:2048
	ds_read_b128 v[184:187], v154 offset:3072
	s_add_u32 s50, s48, 0xfff80080
	s_addc_u32 s51, s49, -1
	s_cmp_eq_u32 s70, 28
	s_cselect_b32 s53, s29, s51
	s_cselect_b32 s52, s65, s50
	s_cselect_b32 s51, s27, s69
	s_cselect_b32 s50, s67, s68
	v_lshl_add_u64 v[164:165], s[48:49], 0, v[138:139]
	s_add_i32 m0, s43, 0xc000
	ds_read_b128 v[188:191], v155
	ds_read_b128 v[192:195], v155 offset:1024
	ds_read_b128 v[196:199], v155 offset:2048
	ds_read_b128 v[200:203], v155 offset:3072
	ds_read_b128 v[204:207], v155 offset:4096
	ds_read_b128 v[208:211], v155 offset:5120
	ds_read_b128 v[212:215], v155 offset:6144
	ds_read_b128 v[216:219], v155 offset:7168
	global_load_lds_dwordx4 v[164:165], off
	v_lshl_add_u64 v[164:165], s[48:49], 0, v[142:143]
	s_add_i32 m0, s43, 0xe000
	s_nop 0
	global_load_lds_dwordx4 v[164:165], off
	s_waitcnt vmcnt(8)
	s_waitcnt lgkmcnt(0)
	s_barrier
	s_setprio 3
	s_waitcnt lgkmcnt(0)
	v_mfma_f32_16x16x32_bf16 v[126:129], v[148:151], v[188:191], v[126:129]
	v_mfma_f32_16x16x32_bf16 v[118:121], v[160:163], v[188:191], v[118:121]
	v_mfma_f32_16x16x32_bf16 v[110:113], v[148:151], v[196:199], v[110:113]
	v_mfma_f32_16x16x32_bf16 v[102:105], v[160:163], v[196:199], v[102:105]
	v_mfma_f32_16x16x32_bf16 v[94:97], v[148:151], v[204:207], v[94:97]
	v_mfma_f32_16x16x32_bf16 v[86:89], v[160:163], v[204:207], v[86:89]
	v_mfma_f32_16x16x32_bf16 v[78:81], v[148:151], v[212:215], v[78:81]
	v_mfma_f32_16x16x32_bf16 v[70:73], v[160:163], v[212:215], v[70:73]
	v_mfma_f32_16x16x32_bf16 v[126:129], v[156:159], v[192:195], v[126:129]
	v_mfma_f32_16x16x32_bf16 v[118:121], v[168:171], v[192:195], v[118:121]
	v_mfma_f32_16x16x32_bf16 v[110:113], v[156:159], v[200:203], v[110:113]
	v_mfma_f32_16x16x32_bf16 v[102:105], v[168:171], v[200:203], v[102:105]
	v_mfma_f32_16x16x32_bf16 v[94:97], v[156:159], v[208:211], v[94:97]
	v_mfma_f32_16x16x32_bf16 v[86:89], v[168:171], v[208:211], v[86:89]
	v_mfma_f32_16x16x32_bf16 v[78:81], v[156:159], v[216:219], v[78:81]
	v_mfma_f32_16x16x32_bf16 v[70:73], v[168:171], v[216:219], v[70:73]
	s_setprio 0
	s_setprio 3
	v_mfma_f32_16x16x32_bf16 v[122:125], v[172:175], v[188:191], v[122:125]
	v_mfma_f32_16x16x32_bf16 v[114:117], v[180:183], v[188:191], v[114:117]
	v_mfma_f32_16x16x32_bf16 v[106:109], v[172:175], v[196:199], v[106:109]
	v_mfma_f32_16x16x32_bf16 v[98:101], v[180:183], v[196:199], v[98:101]
	v_mfma_f32_16x16x32_bf16 v[90:93], v[172:175], v[204:207], v[90:93]
	v_mfma_f32_16x16x32_bf16 v[82:85], v[180:183], v[204:207], v[82:85]
	v_mfma_f32_16x16x32_bf16 v[74:77], v[172:175], v[212:215], v[74:77]
	v_mfma_f32_16x16x32_bf16 v[66:69], v[180:183], v[212:215], v[66:69]
	v_mfma_f32_16x16x32_bf16 v[122:125], v[176:179], v[192:195], v[122:125]
	v_mfma_f32_16x16x32_bf16 v[114:117], v[184:187], v[192:195], v[114:117]
	v_mfma_f32_16x16x32_bf16 v[106:109], v[176:179], v[200:203], v[106:109]
	v_mfma_f32_16x16x32_bf16 v[98:101], v[184:187], v[200:203], v[98:101]
	v_mfma_f32_16x16x32_bf16 v[90:93], v[176:179], v[208:211], v[90:93]
	v_mfma_f32_16x16x32_bf16 v[82:85], v[184:187], v[208:211], v[82:85]
	v_mfma_f32_16x16x32_bf16 v[74:77], v[176:179], v[216:219], v[74:77]
	s_barrier
	v_mfma_f32_16x16x32_bf16 v[66:69], v[184:187], v[216:219], v[66:69]
	s_setprio 0
	s_add_i32 s71, s61, s37
	v_lshl_add_u64 v[164:165], s[50:51], 0, v[132:133]
	s_mov_b32 m0, s71
	ds_read_b128 v[188:191], v155 offset:16384
	ds_read_b128 v[192:195], v155 offset:17408
	ds_read_b128 v[196:199], v155 offset:18432
	ds_read_b128 v[200:203], v155 offset:19456
	ds_read_b128 v[204:207], v155 offset:20480
	ds_read_b128 v[208:211], v155 offset:21504
	ds_read_b128 v[212:215], v155 offset:22528
	ds_read_b128 v[216:219], v155 offset:23552
	global_load_lds_dwordx4 v[164:165], off
	s_add_i32 m0, s71, 0x2000
	s_add_u32 s72, s50, 0x80000
	v_lshl_add_u64 v[220:221], s[50:51], 0, v[136:137]
	s_addc_u32 s73, s51, 0
	s_add_i32 s71, s62, s37
	global_load_lds_dwordx4 v[220:221], off
	v_lshl_add_u64 v[222:223], s[72:73], 0, v[132:133]
	s_mov_b32 m0, s71
	v_lshl_add_u64 v[224:225], s[52:53], 0, v[134:135]
	global_load_lds_dwordx4 v[222:223], off
	v_lshl_add_u64 v[222:223], s[72:73], 0, v[136:137]
	s_add_i32 m0, s71, 0x2000
	s_nop 0
	global_load_lds_dwordx4 v[222:223], off
	v_lshl_add_u64 v[222:223], s[52:53], 0, v[130:131]
	s_mov_b32 m0, s43
	s_nop 0
	global_load_lds_dwordx4 v[222:223], off
	s_mov_b32 m0, s47
	s_nop 0
	global_load_lds_dwordx4 v[224:225], off
	s_waitcnt vmcnt(8)
	s_waitcnt lgkmcnt(0)
	s_barrier
; #define PG8_STAGE(bufoff, gbase, voff) do { _Pragma("unroll") for (int _i = 0; _i < 2; ++_i) \
;         __builtin_amdgcn_global_load_lds((const unsigned*)((const char*)(gbase) + (voff)[_i]), (PG8_LAS unsigned*)(lds + (bufoff) + ldsw + _i * 8192), 16, 0, 0); } while (0)
; #define PG8_LDA(dst, b, h) do { _Pragma("unroll") for (int m = 0; m < 4; ++m) _Pragma("unroll") for (int k = 0; k < 2; ++k) dst[m][k] = *(const PG8_LAS bf16x8*)(lds + PG8_SA(b, h) + aoff + m * 2048 + k * 1024); } while (0)
; #define PG8_LDB(dst, b, h) do { _Pragma("unroll") for (int n = 0; n < 2; ++n) _Pragma("unroll") for (int k = 0; k < 2; ++k) dst[n][k] = *(const PG8_LAS bf16x8*)(lds + PG8_SB(b, h) + boff + n * 2048 + k * 1024); } while (0)
; #define PG8_MMA(ai, bj, At, Bt) do { __builtin_amdgcn_s_setprio(3); _Pragma("unroll") for (int m = 0; m < 4; ++m) _Pragma("unroll") for (int n = 0; n < 2; ++n) _Pragma("unroll") for (int k = 0; k < 2; ++k) \
;         acc[ai][bj][m][n] = __builtin_amdgcn_mfma_f32_16x16x32_bf16(Bt[n][k], At[m][k], acc[ai][bj][m][n], 0, 0, 0); __builtin_amdgcn_s_setprio(0); } while (0)
; #define PG8_WAIT_V(n) asm volatile("s_waitcnt vmcnt(" #n ")" ::: "memory")
; #define PG8_WAIT_L(n) asm volatile("s_waitcnt lgkmcnt(" #n ")" ::: "memory")
; #define PG8_BAR __builtin_amdgcn_s_barrier()
; #define PG8_SCHED __builtin_amdgcn_sched_barrier(0)
; template <class Epi, class Sched, bool ALIGN_EPI = false, bool SP2 = false>
; __device__ __forceinline__ void gemm_phase(PG8_LAS unsigned char* lds, const Gemm g, const Sched& S, const Epi& E) {
;     ...
;             PG8_WAIT_V(8); PG8_WAIT_L(0); PG8_BAR; PG8_MMA(1, 0, At, B0); PG8_MMA(1, 1, At, B1); PG8_BAR; PG8_SCHED;
;             PG8_LDB(B0, 1, 0); PG8_LDB(B1, 1, 1); PG8_SCHED; PG8_LDA(At, 1, 0); PG8_STAGE(PG8_SA(0, 1), a2 + hstep, voffA);
;             PG8_WAIT_V(8); PG8_WAIT_L(0); PG8_BAR; PG8_MMA(0, 0, At, B0); PG8_MMA(0, 1, At, B1); PG8_BAR; PG8_SCHED;
	s_setprio 3
	s_waitcnt lgkmcnt(0)
	v_mfma_f32_16x16x32_bf16 v[62:65], v[148:151], v[188:191], v[62:65]
	v_mfma_f32_16x16x32_bf16 v[54:57], v[160:163], v[188:191], v[54:57]
	v_mfma_f32_16x16x32_bf16 v[46:49], v[148:151], v[196:199], v[46:49]
	v_mfma_f32_16x16x32_bf16 v[38:41], v[160:163], v[196:199], v[38:41]
	v_mfma_f32_16x16x32_bf16 v[30:33], v[148:151], v[204:207], v[30:33]
	v_mfma_f32_16x16x32_bf16 v[22:25], v[160:163], v[204:207], v[22:25]
	v_mfma_f32_16x16x32_bf16 v[14:17], v[148:151], v[212:215], v[14:17]
	v_mfma_f32_16x16x32_bf16 v[6:9], v[160:163], v[212:215], v[6:9]
	v_mfma_f32_16x16x32_bf16 v[62:65], v[156:159], v[192:195], v[62:65]
	v_mfma_f32_16x16x32_bf16 v[54:57], v[168:171], v[192:195], v[54:57]
	v_mfma_f32_16x16x32_bf16 v[46:49], v[156:159], v[200:203], v[46:49]
	v_mfma_f32_16x16x32_bf16 v[38:41], v[168:171], v[200:203], v[38:41]
	v_mfma_f32_16x16x32_bf16 v[30:33], v[156:159], v[208:211], v[30:33]
	v_mfma_f32_16x16x32_bf16 v[22:25], v[168:171], v[208:211], v[22:25]
	v_mfma_f32_16x16x32_bf16 v[14:17], v[156:159], v[216:219], v[14:17]
	v_mfma_f32_16x16x32_bf16 v[6:9], v[168:171], v[216:219], v[6:9]
	s_setprio 0
	s_setprio 3
	v_mfma_f32_16x16x32_bf16 v[58:61], v[172:175], v[188:191], v[58:61]
	v_mfma_f32_16x16x32_bf16 v[50:53], v[180:183], v[188:191], v[50:53]
	v_mfma_f32_16x16x32_bf16 v[42:45], v[172:175], v[196:199], v[42:45]
	v_mfma_f32_16x16x32_bf16 v[34:37], v[180:183], v[196:199], v[34:37]
	v_mfma_f32_16x16x32_bf16 v[26:29], v[172:175], v[204:207], v[26:29]
	v_mfma_f32_16x16x32_bf16 v[18:21], v[180:183], v[204:207], v[18:21]
	v_mfma_f32_16x16x32_bf16 v[10:13], v[172:175], v[212:215], v[10:13]
	v_mfma_f32_16x16x32_bf16 v[2:5], v[180:183], v[212:215], v[2:5]
	v_mfma_f32_16x16x32_bf16 v[58:61], v[176:179], v[192:195], v[58:61]
	v_mfma_f32_16x16x32_bf16 v[50:53], v[184:187], v[192:195], v[50:53]
	v_mfma_f32_16x16x32_bf16 v[42:45], v[176:179], v[200:203], v[42:45]
	v_mfma_f32_16x16x32_bf16 v[34:37], v[184:187], v[200:203], v[34:37]
	v_mfma_f32_16x16x32_bf16 v[26:29], v[176:179], v[208:211], v[26:29]
	v_mfma_f32_16x16x32_bf16 v[18:21], v[184:187], v[208:211], v[18:21]
	v_mfma_f32_16x16x32_bf16 v[10:13], v[176:179], v[216:219], v[10:13]
	s_barrier
	v_mfma_f32_16x16x32_bf16 v[2:5], v[184:187], v[216:219], v[2:5]
	s_setprio 0
	s_add_i32 s71, 0, 0x18000
	v_add_u32_e32 v167, s71, v141
	s_add_i32 s72, 0, 0x1c000
	ds_read_b128 v[148:151], v167
	ds_read_b128 v[156:159], v167 offset:1024
	ds_read_b128 v[160:163], v167 offset:2048
	ds_read_b128 v[168:171], v167 offset:3072
	v_add_u32_e32 v167, s72, v141
	ds_read_b128 v[172:175], v167
	ds_read_b128 v[176:179], v167 offset:1024
	ds_read_b128 v[180:183], v167 offset:2048
	ds_read_b128 v[184:187], v167 offset:3072
	s_add_u32 s52, s52, 0x80000
	s_addc_u32 s53, s53, 0
	s_mov_b32 m0, s54
	v_lshl_add_u64 v[226:227], s[52:53], 0, v[130:131]
	ds_read_b128 v[188:191], v155 offset:32768
	ds_read_b128 v[192:195], v155 offset:33792
	ds_read_b128 v[196:199], v155 offset:34816
	ds_read_b128 v[200:203], v155 offset:35840
	ds_read_b128 v[204:207], v155 offset:36864
	ds_read_b128 v[208:211], v155 offset:37888
	ds_read_b128 v[212:215], v155 offset:38912
	ds_read_b128 v[216:219], v155 offset:39936
	global_load_lds_dwordx4 v[226:227], off
	v_lshl_add_u64 v[226:227], s[52:53], 0, v[134:135]
	s_mov_b32 m0, s55
	s_nop 0
	global_load_lds_dwordx4 v[226:227], off
	s_waitcnt vmcnt(8)
	s_waitcnt lgkmcnt(0)
	s_barrier
	s_setprio 3
	s_waitcnt lgkmcnt(0)
	v_mfma_f32_16x16x32_bf16 v[126:129], v[148:151], v[188:191], v[126:129]
	v_mfma_f32_16x16x32_bf16 v[118:121], v[160:163], v[188:191], v[118:121]
	v_mfma_f32_16x16x32_bf16 v[110:113], v[148:151], v[196:199], v[110:113]
	v_mfma_f32_16x16x32_bf16 v[102:105], v[160:163], v[196:199], v[102:105]
	v_mfma_f32_16x16x32_bf16 v[94:97], v[148:151], v[204:207], v[94:97]
	v_mfma_f32_16x16x32_bf16 v[86:89], v[160:163], v[204:207], v[86:89]
	v_mfma_f32_16x16x32_bf16 v[78:81], v[148:151], v[212:215], v[78:81]
	v_mfma_f32_16x16x32_bf16 v[70:73], v[160:163], v[212:215], v[70:73]
	v_mfma_f32_16x16x32_bf16 v[126:129], v[156:159], v[192:195], v[126:129]
	v_mfma_f32_16x16x32_bf16 v[118:121], v[168:171], v[192:195], v[118:121]
	v_mfma_f32_16x16x32_bf16 v[110:113], v[156:159], v[200:203], v[110:113]
	v_mfma_f32_16x16x32_bf16 v[102:105], v[168:171], v[200:203], v[102:105]
	v_mfma_f32_16x16x32_bf16 v[94:97], v[156:159], v[208:211], v[94:97]
	v_mfma_f32_16x16x32_bf16 v[86:89], v[168:171], v[208:211], v[86:89]
	v_mfma_f32_16x16x32_bf16 v[78:81], v[156:159], v[216:219], v[78:81]
	v_mfma_f32_16x16x32_bf16 v[70:73], v[168:171], v[216:219], v[70:73]
	s_setprio 0
	s_setprio 3
	v_mfma_f32_16x16x32_bf16 v[122:125], v[172:175], v[188:191], v[122:125]
	v_mfma_f32_16x16x32_bf16 v[114:117], v[180:183], v[188:191], v[114:117]
	v_mfma_f32_16x16x32_bf16 v[106:109], v[172:175], v[196:199], v[106:109]
	v_mfma_f32_16x16x32_bf16 v[98:101], v[180:183], v[196:199], v[98:101]
	v_mfma_f32_16x16x32_bf16 v[90:93], v[172:175], v[204:207], v[90:93]
	v_mfma_f32_16x16x32_bf16 v[82:85], v[180:183], v[204:207], v[82:85]
	v_mfma_f32_16x16x32_bf16 v[74:77], v[172:175], v[212:215], v[74:77]
	v_mfma_f32_16x16x32_bf16 v[66:69], v[180:183], v[212:215], v[66:69]
	v_mfma_f32_16x16x32_bf16 v[122:125], v[176:179], v[192:195], v[122:125]
	v_mfma_f32_16x16x32_bf16 v[114:117], v[184:187], v[192:195], v[114:117]
	v_mfma_f32_16x16x32_bf16 v[106:109], v[176:179], v[200:203], v[106:109]
	v_mfma_f32_16x16x32_bf16 v[98:101], v[184:187], v[200:203], v[98:101]
	v_mfma_f32_16x16x32_bf16 v[90:93], v[176:179], v[208:211], v[90:93]
	v_mfma_f32_16x16x32_bf16 v[82:85], v[184:187], v[208:211], v[82:85]
	v_mfma_f32_16x16x32_bf16 v[74:77], v[176:179], v[216:219], v[74:77]
	s_barrier
; #define PG8_STAGE(bufoff, gbase, voff) do { _Pragma("unroll") for (int _i = 0; _i < 2; ++_i) \
;         __builtin_amdgcn_global_load_lds((const unsigned*)((const char*)(gbase) + (voff)[_i]), (PG8_LAS unsigned*)(lds + (bufoff) + ldsw + _i * 8192), 16, 0, 0); } while (0)
; #define PG8_LDA(dst, b, h) do { _Pragma("unroll") for (int m = 0; m < 4; ++m) _Pragma("unroll") for (int k = 0; k < 2; ++k) dst[m][k] = *(const PG8_LAS bf16x8*)(lds + PG8_SA(b, h) + aoff + m * 2048 + k * 1024); } while (0)
; #define PG8_MMA(ai, bj, At, Bt) do { __builtin_amdgcn_s_setprio(3); _Pragma("unroll") for (int m = 0; m < 4; ++m) _Pragma("unroll") for (int n = 0; n < 2; ++n) _Pragma("unroll") for (int k = 0; k < 2; ++k) \
;         acc[ai][bj][m][n] = __builtin_amdgcn_mfma_f32_16x16x32_bf16(Bt[n][k], At[m][k], acc[ai][bj][m][n], 0, 0, 0); __builtin_amdgcn_s_setprio(0); } while (0)
; #define PG8_WAIT_V(n) asm volatile("s_waitcnt vmcnt(" #n ")" ::: "memory")
; #define PG8_WAIT_L(n) asm volatile("s_waitcnt lgkmcnt(" #n ")" ::: "memory")
; #define PG8_BAR __builtin_amdgcn_s_barrier()
; #define PG8_SCHED __builtin_amdgcn_sched_barrier(0)
; template <class Epi, class Sched, bool ALIGN_EPI = false, bool SP2 = false>
; __device__ __forceinline__ void gemm_phase(PG8_LAS unsigned char* lds, const Gemm g, const Sched& S, const Epi& E) {
;     ...
;         for (int t = 0; t < nt; t += 2) {
;     ...
;             PG8_WAIT_V(8); PG8_WAIT_L(0); PG8_BAR; PG8_MMA(0, 0, At, B0); PG8_MMA(0, 1, At, B1); PG8_BAR; PG8_SCHED;
;             PG8_LDA(At, 1, 1); PG8_STAGE(PG8_SB(1, 0), b3, voffB); PG8_STAGE(PG8_SB(1, 1), b3 + hstep, voffB); PG8_STAGE(PG8_SA(1, 0), a3, voffA);
;             PG8_WAIT_V(8); PG8_WAIT_L(0); PG8_BAR; PG8_MMA(1, 0, At, B0); PG8_MMA(1, 1, At, B1); PG8_BAR; PG8_SCHED;
	v_mfma_f32_16x16x32_bf16 v[66:69], v[184:187], v[216:219], v[66:69]
	s_setprio 0
	s_add_i32 s52, s71, s37
	v_lshl_add_u64 v[164:165], v[164:165], 0, s[18:19]
	s_mov_b32 m0, s52
	ds_read_b128 v[188:191], v155 offset:49152
	ds_read_b128 v[192:195], v155 offset:50176
	ds_read_b128 v[196:199], v155 offset:51200
	ds_read_b128 v[200:203], v155 offset:52224
	ds_read_b128 v[204:207], v155 offset:53248
	ds_read_b128 v[208:211], v155 offset:54272
	ds_read_b128 v[212:215], v155 offset:55296
	ds_read_b128 v[216:219], v155 offset:56320
	global_load_lds_dwordx4 v[164:165], off
	s_add_i32 m0, s52, 0x2000
	s_add_u32 s50, s50, 0x80080
	v_lshl_add_u64 v[164:165], v[220:221], 0, s[18:19]
	s_addc_u32 s51, s51, 0
	s_add_i32 s52, s72, s37
	global_load_lds_dwordx4 v[164:165], off
	v_lshl_add_u64 v[164:165], s[50:51], 0, v[132:133]
	s_mov_b32 m0, s52
	s_nop 0
	global_load_lds_dwordx4 v[164:165], off
	v_lshl_add_u64 v[164:165], s[50:51], 0, v[136:137]
	s_add_i32 m0, s52, 0x2000
	s_nop 0
	global_load_lds_dwordx4 v[164:165], off
	v_lshl_add_u64 v[164:165], v[222:223], 0, s[18:19]
	s_mov_b32 m0, s58
	s_nop 0
	global_load_lds_dwordx4 v[164:165], off
	v_lshl_add_u64 v[164:165], v[224:225], 0, s[18:19]
	s_mov_b32 m0, s59
	s_nop 0
	global_load_lds_dwordx4 v[164:165], off
	s_waitcnt vmcnt(8)
	s_waitcnt lgkmcnt(0)
	s_barrier
	s_setprio 3
	s_waitcnt lgkmcnt(0)
	v_mfma_f32_16x16x32_bf16 v[62:65], v[148:151], v[188:191], v[62:65]
	v_mfma_f32_16x16x32_bf16 v[54:57], v[160:163], v[188:191], v[54:57]
	v_mfma_f32_16x16x32_bf16 v[46:49], v[148:151], v[196:199], v[46:49]
	v_mfma_f32_16x16x32_bf16 v[38:41], v[160:163], v[196:199], v[38:41]
	v_mfma_f32_16x16x32_bf16 v[30:33], v[148:151], v[204:207], v[30:33]
	v_mfma_f32_16x16x32_bf16 v[22:25], v[160:163], v[204:207], v[22:25]
	v_mfma_f32_16x16x32_bf16 v[14:17], v[148:151], v[212:215], v[14:17]
	v_mfma_f32_16x16x32_bf16 v[6:9], v[160:163], v[212:215], v[6:9]
	v_mfma_f32_16x16x32_bf16 v[62:65], v[156:159], v[192:195], v[62:65]
	v_mfma_f32_16x16x32_bf16 v[54:57], v[168:171], v[192:195], v[54:57]
	v_mfma_f32_16x16x32_bf16 v[46:49], v[156:159], v[200:203], v[46:49]
	v_mfma_f32_16x16x32_bf16 v[38:41], v[168:171], v[200:203], v[38:41]
	v_mfma_f32_16x16x32_bf16 v[30:33], v[156:159], v[208:211], v[30:33]
	v_mfma_f32_16x16x32_bf16 v[22:25], v[168:171], v[208:211], v[22:25]
	v_mfma_f32_16x16x32_bf16 v[14:17], v[156:159], v[216:219], v[14:17]
	v_mfma_f32_16x16x32_bf16 v[6:9], v[168:171], v[216:219], v[6:9]
	s_setprio 0
	s_setprio 3
	v_mfma_f32_16x16x32_bf16 v[58:61], v[172:175], v[188:191], v[58:61]
	v_mfma_f32_16x16x32_bf16 v[50:53], v[180:183], v[188:191], v[50:53]
	v_mfma_f32_16x16x32_bf16 v[42:45], v[172:175], v[196:199], v[42:45]
	v_mfma_f32_16x16x32_bf16 v[34:37], v[180:183], v[196:199], v[34:37]
	v_mfma_f32_16x16x32_bf16 v[26:29], v[172:175], v[204:207], v[26:29]
	v_mfma_f32_16x16x32_bf16 v[18:21], v[180:183], v[204:207], v[18:21]
	v_mfma_f32_16x16x32_bf16 v[10:13], v[172:175], v[212:215], v[10:13]
	v_mfma_f32_16x16x32_bf16 v[2:5], v[180:183], v[212:215], v[2:5]
	v_mfma_f32_16x16x32_bf16 v[58:61], v[176:179], v[192:195], v[58:61]
	v_mfma_f32_16x16x32_bf16 v[50:53], v[184:187], v[192:195], v[50:53]
	v_mfma_f32_16x16x32_bf16 v[42:45], v[176:179], v[200:203], v[42:45]
	v_mfma_f32_16x16x32_bf16 v[34:37], v[184:187], v[200:203], v[34:37]
	v_mfma_f32_16x16x32_bf16 v[26:29], v[176:179], v[208:211], v[26:29]
	v_mfma_f32_16x16x32_bf16 v[18:21], v[184:187], v[208:211], v[18:21]
	v_mfma_f32_16x16x32_bf16 v[10:13], v[176:179], v[216:219], v[10:13]
	s_barrier
	v_mfma_f32_16x16x32_bf16 v[2:5], v[184:187], v[216:219], v[2:5]
	s_setprio 0
	s_add_i32 s70, s70, 2
	s_add_u32 s48, s48, 0x100
	s_addc_u32 s49, s49, 0
	s_add_u32 s68, s68, 0x100
	s_addc_u32 s69, s69, 0
	s_cmp_gt_u32 s70, 29
	s_cbranch_scc0 .LBB0_70
	s_and_b64 vcc, exec, s[24:25]
	s_cbranch_vccz .LBB0_73
	s_barrier

; #define PG8_STAGE(bufoff, gbase, voff) do { _Pragma("unroll") for (int _i = 0; _i < 2; ++_i) \
;         __builtin_amdgcn_global_load_lds((const unsigned*)((const char*)(gbase) + (voff)[_i]), (PG8_LAS unsigned*)(lds + (bufoff) + ldsw + _i * 8192), 16, 0, 0); } while (0)
; #define PG8_LDA(dst, b, h) do { _Pragma("unroll") for (int m = 0; m < 4; ++m) _Pragma("unroll") for (int k = 0; k < 2; ++k) dst[m][k] = *(const PG8_LAS bf16x8*)(lds + PG8_SA(b, h) + aoff + m * 2048 + k * 1024); } while (0)
; #define PG8_LDB(dst, b, h) do { _Pragma("unroll") for (int n = 0; n < 2; ++n) _Pragma("unroll") for (int k = 0; k < 2; ++k) dst[n][k] = *(const PG8_LAS bf16x8*)(lds + PG8_SB(b, h) + boff + n * 2048 + k * 1024); } while (0)
; #define PG8_MMA(ai, bj, At, Bt) do { __builtin_amdgcn_s_setprio(3); _Pragma("unroll") for (int m = 0; m < 4; ++m) _Pragma("unroll") for (int n = 0; n < 2; ++n) _Pragma("unroll") for (int k = 0; k < 2; ++k) \
;         acc[ai][bj][m][n] = __builtin_amdgcn_mfma_f32_16x16x32_bf16(Bt[n][k], At[m][k], acc[ai][bj][m][n], 0, 0, 0); __builtin_amdgcn_s_setprio(0); } while (0)
; #define PG8_WAIT_V(n) asm volatile("s_waitcnt vmcnt(" #n ")" ::: "memory")
; #define PG8_WAIT_L(n) asm volatile("s_waitcnt lgkmcnt(" #n ")" ::: "memory")
; #define PG8_BAR __builtin_amdgcn_s_barrier()
; #define PG8_SCHED __builtin_amdgcn_sched_barrier(0)
; template <class Epi, class Sched, bool ALIGN_EPI = false, bool SP2 = false>
; __device__ __forceinline__ void gemm_phase(PG8_LAS unsigned char* lds, const Gemm g, const Sched& S, const Epi& E) {
;     ...
;             PG8_LDB(B0, 0, 0); PG8_LDB(B1, 0, 1); PG8_SCHED; PG8_LDA(At, 0, 0); PG8_STAGE(PG8_SA(1, 1), a1 + hstep, voffA);
;             PG8_WAIT_V(8); PG8_WAIT_L(0); PG8_BAR; PG8_MMA(0, 0, At, B0); PG8_MMA(0, 1, At, B1); PG8_BAR; PG8_SCHED;
;             PG8_LDA(At, 0, 1); PG8_STAGE(PG8_SB(0, 0), b2, voffB); PG8_STAGE(PG8_SB(0, 1), b2 + hstep, voffB); PG8_STAGE(PG8_SA(0, 0), a2, voffA);
;             PG8_WAIT_V(8); PG8_WAIT_L(0); PG8_BAR; PG8_MMA(1, 0, At, B0); PG8_MMA(1, 1, At, B1); PG8_BAR; PG8_SCHED;
.LBB0_179:
	ds_read_b128 v[148:151], v157
	ds_read_b128 v[152:155], v157 offset:1024
	ds_read_b128 v[160:163], v157 offset:2048
	ds_read_b128 v[168:171], v157 offset:3072
	ds_read_b128 v[172:175], v158
	ds_read_b128 v[176:179], v158 offset:1024
	ds_read_b128 v[180:183], v158 offset:2048
	ds_read_b128 v[184:187], v158 offset:3072
	s_add_i32 s79, s50, 2
	s_add_u32 s51, s8, 0xffea8080
	s_addc_u32 s52, s9, -1
	s_cmp_eq_u32 s76, s50
	s_cselect_b32 s50, s48, s77
	s_cselect_b32 s53, s47, s52
	s_cselect_b32 s52, s46, s51
	s_cselect_b32 s51, s49, s78
	v_lshl_add_u64 v[164:165], s[8:9], 0, v[138:139]
	s_add_i32 m0, s54, 0xc000
	ds_read_b128 v[188:191], v159
	ds_read_b128 v[192:195], v159 offset:1024
	ds_read_b128 v[196:199], v159 offset:2048
	ds_read_b128 v[200:203], v159 offset:3072
	ds_read_b128 v[204:207], v159 offset:4096
	ds_read_b128 v[208:211], v159 offset:5120
	ds_read_b128 v[212:215], v159 offset:6144
	ds_read_b128 v[216:219], v159 offset:7168
	global_load_lds_dwordx4 v[164:165], off
	v_lshl_add_u64 v[164:165], s[8:9], 0, v[142:143]
	s_add_i32 m0, s54, 0xe000
	s_nop 0
	global_load_lds_dwordx4 v[164:165], off
	s_waitcnt vmcnt(8)
	s_waitcnt lgkmcnt(0)
	s_barrier
	s_setprio 3
	s_waitcnt lgkmcnt(0)
	v_mfma_f32_16x16x32_bf16 v[126:129], v[148:151], v[188:191], v[126:129]
	v_mfma_f32_16x16x32_bf16 v[122:125], v[160:163], v[188:191], v[122:125]
	v_mfma_f32_16x16x32_bf16 v[114:117], v[148:151], v[196:199], v[114:117]
	v_mfma_f32_16x16x32_bf16 v[106:109], v[160:163], v[196:199], v[106:109]
	v_mfma_f32_16x16x32_bf16 v[98:101], v[148:151], v[204:207], v[98:101]
	v_mfma_f32_16x16x32_bf16 v[90:93], v[160:163], v[204:207], v[90:93]
	v_mfma_f32_16x16x32_bf16 v[82:85], v[148:151], v[212:215], v[82:85]
	v_mfma_f32_16x16x32_bf16 v[74:77], v[160:163], v[212:215], v[74:77]
	v_mfma_f32_16x16x32_bf16 v[126:129], v[152:155], v[192:195], v[126:129]
	v_mfma_f32_16x16x32_bf16 v[122:125], v[168:171], v[192:195], v[122:125]
	v_mfma_f32_16x16x32_bf16 v[114:117], v[152:155], v[200:203], v[114:117]
	v_mfma_f32_16x16x32_bf16 v[106:109], v[168:171], v[200:203], v[106:109]
	v_mfma_f32_16x16x32_bf16 v[98:101], v[152:155], v[208:211], v[98:101]
	v_mfma_f32_16x16x32_bf16 v[90:93], v[168:171], v[208:211], v[90:93]
	v_mfma_f32_16x16x32_bf16 v[82:85], v[152:155], v[216:219], v[82:85]
	v_mfma_f32_16x16x32_bf16 v[74:77], v[168:171], v[216:219], v[74:77]
	s_setprio 0
	s_setprio 3
	v_mfma_f32_16x16x32_bf16 v[118:121], v[172:175], v[188:191], v[118:121]
	v_mfma_f32_16x16x32_bf16 v[110:113], v[180:183], v[188:191], v[110:113]
	v_mfma_f32_16x16x32_bf16 v[102:105], v[172:175], v[196:199], v[102:105]
	v_mfma_f32_16x16x32_bf16 v[94:97], v[180:183], v[196:199], v[94:97]
	v_mfma_f32_16x16x32_bf16 v[86:89], v[172:175], v[204:207], v[86:89]
	v_mfma_f32_16x16x32_bf16 v[78:81], v[180:183], v[204:207], v[78:81]
	v_mfma_f32_16x16x32_bf16 v[70:73], v[172:175], v[212:215], v[70:73]
	v_mfma_f32_16x16x32_bf16 v[66:69], v[180:183], v[212:215], v[66:69]
	v_mfma_f32_16x16x32_bf16 v[118:121], v[176:179], v[192:195], v[118:121]
	v_mfma_f32_16x16x32_bf16 v[110:113], v[184:187], v[192:195], v[110:113]
	v_mfma_f32_16x16x32_bf16 v[102:105], v[176:179], v[200:203], v[102:105]
	v_mfma_f32_16x16x32_bf16 v[94:97], v[184:187], v[200:203], v[94:97]
	v_mfma_f32_16x16x32_bf16 v[86:89], v[176:179], v[208:211], v[86:89]
	v_mfma_f32_16x16x32_bf16 v[78:81], v[184:187], v[208:211], v[78:81]
	v_mfma_f32_16x16x32_bf16 v[70:73], v[176:179], v[216:219], v[70:73]
	s_barrier
	v_mfma_f32_16x16x32_bf16 v[66:69], v[184:187], v[216:219], v[66:69]
	s_setprio 0
	s_add_i32 s81, s65, s43
	v_lshl_add_u64 v[164:165], s[50:51], 0, v[132:133]
	s_mov_b32 m0, s81
	ds_read_b128 v[188:191], v159 offset:16384
	ds_read_b128 v[192:195], v159 offset:17408
	ds_read_b128 v[196:199], v159 offset:18432
	ds_read_b128 v[200:203], v159 offset:19456
	ds_read_b128 v[204:207], v159 offset:20480
	ds_read_b128 v[208:211], v159 offset:21504
	ds_read_b128 v[212:215], v159 offset:22528
	ds_read_b128 v[216:219], v159 offset:23552
	global_load_lds_dwordx4 v[164:165], off
	s_add_i32 m0, s81, 0x2000
	s_add_u32 s82, s50, 0x158000
	v_lshl_add_u64 v[220:221], s[50:51], 0, v[136:137]
	s_addc_u32 s83, s51, 0
	s_add_i32 s81, s67, s43
	global_load_lds_dwordx4 v[220:221], off
	v_lshl_add_u64 v[222:223], s[82:83], 0, v[132:133]
	s_mov_b32 m0, s81
	v_lshl_add_u64 v[224:225], s[52:53], 0, v[134:135]
	global_load_lds_dwordx4 v[222:223], off
	v_lshl_add_u64 v[222:223], s[82:83], 0, v[136:137]
	s_add_i32 m0, s81, 0x2000
	s_nop 0
	global_load_lds_dwordx4 v[222:223], off
	v_lshl_add_u64 v[222:223], s[52:53], 0, v[130:131]
	s_mov_b32 m0, s54
	s_nop 0
	global_load_lds_dwordx4 v[222:223], off
	s_mov_b32 m0, s55
	s_nop 0
	global_load_lds_dwordx4 v[224:225], off
	s_waitcnt vmcnt(8)
	s_waitcnt lgkmcnt(0)
	s_barrier
; #define PG8_STAGE(bufoff, gbase, voff) do { _Pragma("unroll") for (int _i = 0; _i < 2; ++_i) \
;         __builtin_amdgcn_global_load_lds((const unsigned*)((const char*)(gbase) + (voff)[_i]), (PG8_LAS unsigned*)(lds + (bufoff) + ldsw + _i * 8192), 16, 0, 0); } while (0)
; #define PG8_LDA(dst, b, h) do { _Pragma("unroll") for (int m = 0; m < 4; ++m) _Pragma("unroll") for (int k = 0; k < 2; ++k) dst[m][k] = *(const PG8_LAS bf16x8*)(lds + PG8_SA(b, h) + aoff + m * 2048 + k * 1024); } while (0)
; #define PG8_LDB(dst, b, h) do { _Pragma("unroll") for (int n = 0; n < 2; ++n) _Pragma("unroll") for (int k = 0; k < 2; ++k) dst[n][k] = *(const PG8_LAS bf16x8*)(lds + PG8_SB(b, h) + boff + n * 2048 + k * 1024); } while (0)
; #define PG8_MMA(ai, bj, At, Bt) do { __builtin_amdgcn_s_setprio(3); _Pragma("unroll") for (int m = 0; m < 4; ++m) _Pragma("unroll") for (int n = 0; n < 2; ++n) _Pragma("unroll") for (int k = 0; k < 2; ++k) \
;         acc[ai][bj][m][n] = __builtin_amdgcn_mfma_f32_16x16x32_bf16(Bt[n][k], At[m][k], acc[ai][bj][m][n], 0, 0, 0); __builtin_amdgcn_s_setprio(0); } while (0)
; #define PG8_WAIT_V(n) asm volatile("s_waitcnt vmcnt(" #n ")" ::: "memory")
; #define PG8_WAIT_L(n) asm volatile("s_waitcnt lgkmcnt(" #n ")" ::: "memory")
; #define PG8_BAR __builtin_amdgcn_s_barrier()
; #define PG8_SCHED __builtin_amdgcn_sched_barrier(0)
; template <class Epi, class Sched, bool ALIGN_EPI = false, bool SP2 = false>
; __device__ __forceinline__ void gemm_phase(PG8_LAS unsigned char* lds, const Gemm g, const Sched& S, const Epi& E) {
;     ...
;             PG8_WAIT_V(8); PG8_WAIT_L(0); PG8_BAR; PG8_MMA(1, 0, At, B0); PG8_MMA(1, 1, At, B1); PG8_BAR; PG8_SCHED;
;             PG8_LDB(B0, 1, 0); PG8_LDB(B1, 1, 1); PG8_SCHED; PG8_LDA(At, 1, 0); PG8_STAGE(PG8_SA(0, 1), a2 + hstep, voffA);
;             PG8_WAIT_V(8); PG8_WAIT_L(0); PG8_BAR; PG8_MMA(0, 0, At, B0); PG8_MMA(0, 1, At, B1); PG8_BAR; PG8_SCHED;
	s_setprio 3
	s_waitcnt lgkmcnt(0)
	v_mfma_f32_16x16x32_bf16 v[62:65], v[148:151], v[188:191], v[62:65]
	v_mfma_f32_16x16x32_bf16 v[58:61], v[160:163], v[188:191], v[58:61]
	v_mfma_f32_16x16x32_bf16 v[50:53], v[148:151], v[196:199], v[50:53]
	v_mfma_f32_16x16x32_bf16 v[42:45], v[160:163], v[196:199], v[42:45]
	v_mfma_f32_16x16x32_bf16 v[34:37], v[148:151], v[204:207], v[34:37]
	v_mfma_f32_16x16x32_bf16 v[26:29], v[160:163], v[204:207], v[26:29]
	v_mfma_f32_16x16x32_bf16 v[18:21], v[148:151], v[212:215], v[18:21]
	v_mfma_f32_16x16x32_bf16 v[10:13], v[160:163], v[212:215], v[10:13]
	v_mfma_f32_16x16x32_bf16 v[62:65], v[152:155], v[192:195], v[62:65]
	v_mfma_f32_16x16x32_bf16 v[58:61], v[168:171], v[192:195], v[58:61]
	v_mfma_f32_16x16x32_bf16 v[50:53], v[152:155], v[200:203], v[50:53]
	v_mfma_f32_16x16x32_bf16 v[42:45], v[168:171], v[200:203], v[42:45]
	v_mfma_f32_16x16x32_bf16 v[34:37], v[152:155], v[208:211], v[34:37]
	v_mfma_f32_16x16x32_bf16 v[26:29], v[168:171], v[208:211], v[26:29]
	v_mfma_f32_16x16x32_bf16 v[18:21], v[152:155], v[216:219], v[18:21]
	v_mfma_f32_16x16x32_bf16 v[10:13], v[168:171], v[216:219], v[10:13]
	s_setprio 0
	s_setprio 3
	v_mfma_f32_16x16x32_bf16 v[54:57], v[172:175], v[188:191], v[54:57]
	v_mfma_f32_16x16x32_bf16 v[46:49], v[180:183], v[188:191], v[46:49]
	v_mfma_f32_16x16x32_bf16 v[38:41], v[172:175], v[196:199], v[38:41]
	v_mfma_f32_16x16x32_bf16 v[30:33], v[180:183], v[196:199], v[30:33]
	v_mfma_f32_16x16x32_bf16 v[22:25], v[172:175], v[204:207], v[22:25]
	v_mfma_f32_16x16x32_bf16 v[14:17], v[180:183], v[204:207], v[14:17]
	v_mfma_f32_16x16x32_bf16 v[6:9], v[172:175], v[212:215], v[6:9]
	v_mfma_f32_16x16x32_bf16 v[2:5], v[180:183], v[212:215], v[2:5]
	v_mfma_f32_16x16x32_bf16 v[54:57], v[176:179], v[192:195], v[54:57]
	v_mfma_f32_16x16x32_bf16 v[46:49], v[184:187], v[192:195], v[46:49]
	v_mfma_f32_16x16x32_bf16 v[38:41], v[176:179], v[200:203], v[38:41]
	v_mfma_f32_16x16x32_bf16 v[30:33], v[184:187], v[200:203], v[30:33]
	v_mfma_f32_16x16x32_bf16 v[22:25], v[176:179], v[208:211], v[22:25]
	v_mfma_f32_16x16x32_bf16 v[14:17], v[184:187], v[208:211], v[14:17]
	v_mfma_f32_16x16x32_bf16 v[6:9], v[176:179], v[216:219], v[6:9]
	s_barrier
	v_mfma_f32_16x16x32_bf16 v[2:5], v[184:187], v[216:219], v[2:5]
	s_setprio 0
	s_add_i32 s81, 0, 0x18000
	v_add_u32_e32 v167, s81, v141
	s_add_i32 s82, 0, 0x1c000
	ds_read_b128 v[148:151], v167
	ds_read_b128 v[152:155], v167 offset:1024
	ds_read_b128 v[160:163], v167 offset:2048
	ds_read_b128 v[168:171], v167 offset:3072
	v_add_u32_e32 v167, s82, v141
	ds_read_b128 v[172:175], v167
	ds_read_b128 v[176:179], v167 offset:1024
	ds_read_b128 v[180:183], v167 offset:2048
	ds_read_b128 v[184:187], v167 offset:3072
	s_add_u32 s52, s52, 0x158000
	s_addc_u32 s53, s53, 0
	s_mov_b32 m0, s56
	v_lshl_add_u64 v[226:227], s[52:53], 0, v[130:131]
	ds_read_b128 v[188:191], v159 offset:32768
	ds_read_b128 v[192:195], v159 offset:33792
	ds_read_b128 v[196:199], v159 offset:34816
	ds_read_b128 v[200:203], v159 offset:35840
	ds_read_b128 v[204:207], v159 offset:36864
	ds_read_b128 v[208:211], v159 offset:37888
	ds_read_b128 v[212:215], v159 offset:38912
	ds_read_b128 v[216:219], v159 offset:39936
	global_load_lds_dwordx4 v[226:227], off
	v_lshl_add_u64 v[226:227], s[52:53], 0, v[134:135]
	s_mov_b32 m0, s57
	s_nop 0
	global_load_lds_dwordx4 v[226:227], off
	s_waitcnt vmcnt(8)
	s_waitcnt lgkmcnt(0)
	s_barrier
	s_setprio 3
	s_waitcnt lgkmcnt(0)
	v_mfma_f32_16x16x32_bf16 v[126:129], v[148:151], v[188:191], v[126:129]
	v_mfma_f32_16x16x32_bf16 v[122:125], v[160:163], v[188:191], v[122:125]
	v_mfma_f32_16x16x32_bf16 v[114:117], v[148:151], v[196:199], v[114:117]
	v_mfma_f32_16x16x32_bf16 v[106:109], v[160:163], v[196:199], v[106:109]
	v_mfma_f32_16x16x32_bf16 v[98:101], v[148:151], v[204:207], v[98:101]
	v_mfma_f32_16x16x32_bf16 v[90:93], v[160:163], v[204:207], v[90:93]
	v_mfma_f32_16x16x32_bf16 v[82:85], v[148:151], v[212:215], v[82:85]
	v_mfma_f32_16x16x32_bf16 v[74:77], v[160:163], v[212:215], v[74:77]
	v_mfma_f32_16x16x32_bf16 v[126:129], v[152:155], v[192:195], v[126:129]
	v_mfma_f32_16x16x32_bf16 v[122:125], v[168:171], v[192:195], v[122:125]
	v_mfma_f32_16x16x32_bf16 v[114:117], v[152:155], v[200:203], v[114:117]
	v_mfma_f32_16x16x32_bf16 v[106:109], v[168:171], v[200:203], v[106:109]
	v_mfma_f32_16x16x32_bf16 v[98:101], v[152:155], v[208:211], v[98:101]
	v_mfma_f32_16x16x32_bf16 v[90:93], v[168:171], v[208:211], v[90:93]
	v_mfma_f32_16x16x32_bf16 v[82:85], v[152:155], v[216:219], v[82:85]
	v_mfma_f32_16x16x32_bf16 v[74:77], v[168:171], v[216:219], v[74:77]
	s_setprio 0
	s_setprio 3
	v_mfma_f32_16x16x32_bf16 v[118:121], v[172:175], v[188:191], v[118:121]
	v_mfma_f32_16x16x32_bf16 v[110:113], v[180:183], v[188:191], v[110:113]
	v_mfma_f32_16x16x32_bf16 v[102:105], v[172:175], v[196:199], v[102:105]
	v_mfma_f32_16x16x32_bf16 v[94:97], v[180:183], v[196:199], v[94:97]
	v_mfma_f32_16x16x32_bf16 v[86:89], v[172:175], v[204:207], v[86:89]
	v_mfma_f32_16x16x32_bf16 v[78:81], v[180:183], v[204:207], v[78:81]
	v_mfma_f32_16x16x32_bf16 v[70:73], v[172:175], v[212:215], v[70:73]
	v_mfma_f32_16x16x32_bf16 v[66:69], v[180:183], v[212:215], v[66:69]
	v_mfma_f32_16x16x32_bf16 v[118:121], v[176:179], v[192:195], v[118:121]
	v_mfma_f32_16x16x32_bf16 v[110:113], v[184:187], v[192:195], v[110:113]
	v_mfma_f32_16x16x32_bf16 v[102:105], v[176:179], v[200:203], v[102:105]
	v_mfma_f32_16x16x32_bf16 v[94:97], v[184:187], v[200:203], v[94:97]
	v_mfma_f32_16x16x32_bf16 v[86:89], v[176:179], v[208:211], v[86:89]
	v_mfma_f32_16x16x32_bf16 v[78:81], v[184:187], v[208:211], v[78:81]
	v_mfma_f32_16x16x32_bf16 v[70:73], v[176:179], v[216:219], v[70:73]
	s_barrier
; #define PG8_STAGE(bufoff, gbase, voff) do { _Pragma("unroll") for (int _i = 0; _i < 2; ++_i) \
;         __builtin_amdgcn_global_load_lds((const unsigned*)((const char*)(gbase) + (voff)[_i]), (PG8_LAS unsigned*)(lds + (bufoff) + ldsw + _i * 8192), 16, 0, 0); } while (0)
; #define PG8_LDA(dst, b, h) do { _Pragma("unroll") for (int m = 0; m < 4; ++m) _Pragma("unroll") for (int k = 0; k < 2; ++k) dst[m][k] = *(const PG8_LAS bf16x8*)(lds + PG8_SA(b, h) + aoff + m * 2048 + k * 1024); } while (0)
; #define PG8_MMA(ai, bj, At, Bt) do { __builtin_amdgcn_s_setprio(3); _Pragma("unroll") for (int m = 0; m < 4; ++m) _Pragma("unroll") for (int n = 0; n < 2; ++n) _Pragma("unroll") for (int k = 0; k < 2; ++k) \
;         acc[ai][bj][m][n] = __builtin_amdgcn_mfma_f32_16x16x32_bf16(Bt[n][k], At[m][k], acc[ai][bj][m][n], 0, 0, 0); __builtin_amdgcn_s_setprio(0); } while (0)
; #define PG8_WAIT_V(n) asm volatile("s_waitcnt vmcnt(" #n ")" ::: "memory")
; #define PG8_WAIT_L(n) asm volatile("s_waitcnt lgkmcnt(" #n ")" ::: "memory")
; #define PG8_BAR __builtin_amdgcn_s_barrier()
; #define PG8_SCHED __builtin_amdgcn_sched_barrier(0)
; template <class Epi, class Sched, bool ALIGN_EPI = false, bool SP2 = false>
; __device__ __forceinline__ void gemm_phase(PG8_LAS unsigned char* lds, const Gemm g, const Sched& S, const Epi& E) {
;     ...
;         for (int t = 0; t < nt; t += 2) {
;     ...
;             PG8_WAIT_V(8); PG8_WAIT_L(0); PG8_BAR; PG8_MMA(0, 0, At, B0); PG8_MMA(0, 1, At, B1); PG8_BAR; PG8_SCHED;
;             PG8_LDA(At, 1, 1); PG8_STAGE(PG8_SB(1, 0), b3, voffB); PG8_STAGE(PG8_SB(1, 1), b3 + hstep, voffB); PG8_STAGE(PG8_SA(1, 0), a3, voffA);
;             PG8_WAIT_V(8); PG8_WAIT_L(0); PG8_BAR; PG8_MMA(1, 0, At, B0); PG8_MMA(1, 1, At, B1); PG8_BAR; PG8_SCHED;
	v_mfma_f32_16x16x32_bf16 v[66:69], v[184:187], v[216:219], v[66:69]
	s_setprio 0
	s_add_i32 s52, s81, s43
	v_lshl_add_u64 v[164:165], v[164:165], 0, s[18:19]
	s_mov_b32 m0, s52
	ds_read_b128 v[188:191], v159 offset:49152
	ds_read_b128 v[192:195], v159 offset:50176
	ds_read_b128 v[196:199], v159 offset:51200
	ds_read_b128 v[200:203], v159 offset:52224
	ds_read_b128 v[204:207], v159 offset:53248
	ds_read_b128 v[208:211], v159 offset:54272
	ds_read_b128 v[212:215], v159 offset:55296
	ds_read_b128 v[216:219], v159 offset:56320
	global_load_lds_dwordx4 v[164:165], off
	s_add_i32 m0, s52, 0x2000
	s_add_u32 s50, s50, 0x158080
	v_lshl_add_u64 v[164:165], v[220:221], 0, s[18:19]
	s_addc_u32 s51, s51, 0
	s_add_i32 s52, s82, s43
	global_load_lds_dwordx4 v[164:165], off
	v_lshl_add_u64 v[164:165], s[50:51], 0, v[132:133]
	s_mov_b32 m0, s52
	s_nop 0
	global_load_lds_dwordx4 v[164:165], off
	v_lshl_add_u64 v[164:165], s[50:51], 0, v[136:137]
	s_add_i32 m0, s52, 0x2000
	s_nop 0
	global_load_lds_dwordx4 v[164:165], off
	v_lshl_add_u64 v[164:165], v[222:223], 0, s[18:19]
	s_mov_b32 m0, s62
	s_nop 0
	global_load_lds_dwordx4 v[164:165], off
	v_lshl_add_u64 v[164:165], v[224:225], 0, s[18:19]
	s_mov_b32 m0, s63
	s_nop 0
	global_load_lds_dwordx4 v[164:165], off
	s_waitcnt vmcnt(8)
	s_waitcnt lgkmcnt(0)
	s_barrier
	s_setprio 3
	s_waitcnt lgkmcnt(0)
	v_mfma_f32_16x16x32_bf16 v[62:65], v[148:151], v[188:191], v[62:65]
	v_mfma_f32_16x16x32_bf16 v[58:61], v[160:163], v[188:191], v[58:61]
	v_mfma_f32_16x16x32_bf16 v[50:53], v[148:151], v[196:199], v[50:53]
	v_mfma_f32_16x16x32_bf16 v[42:45], v[160:163], v[196:199], v[42:45]
	v_mfma_f32_16x16x32_bf16 v[34:37], v[148:151], v[204:207], v[34:37]
	v_mfma_f32_16x16x32_bf16 v[26:29], v[160:163], v[204:207], v[26:29]
	v_mfma_f32_16x16x32_bf16 v[18:21], v[148:151], v[212:215], v[18:21]
	v_mfma_f32_16x16x32_bf16 v[10:13], v[160:163], v[212:215], v[10:13]
	v_mfma_f32_16x16x32_bf16 v[62:65], v[152:155], v[192:195], v[62:65]
	v_mfma_f32_16x16x32_bf16 v[58:61], v[168:171], v[192:195], v[58:61]
	v_mfma_f32_16x16x32_bf16 v[50:53], v[152:155], v[200:203], v[50:53]
	v_mfma_f32_16x16x32_bf16 v[42:45], v[168:171], v[200:203], v[42:45]
	v_mfma_f32_16x16x32_bf16 v[34:37], v[152:155], v[208:211], v[34:37]
	v_mfma_f32_16x16x32_bf16 v[26:29], v[168:171], v[208:211], v[26:29]
	v_mfma_f32_16x16x32_bf16 v[18:21], v[152:155], v[216:219], v[18:21]
	v_mfma_f32_16x16x32_bf16 v[10:13], v[168:171], v[216:219], v[10:13]
	s_setprio 0
	s_setprio 3
	v_mfma_f32_16x16x32_bf16 v[54:57], v[172:175], v[188:191], v[54:57]
	v_mfma_f32_16x16x32_bf16 v[46:49], v[180:183], v[188:191], v[46:49]
	v_mfma_f32_16x16x32_bf16 v[38:41], v[172:175], v[196:199], v[38:41]
	v_mfma_f32_16x16x32_bf16 v[30:33], v[180:183], v[196:199], v[30:33]
	v_mfma_f32_16x16x32_bf16 v[22:25], v[172:175], v[204:207], v[22:25]
	v_mfma_f32_16x16x32_bf16 v[14:17], v[180:183], v[204:207], v[14:17]
	v_mfma_f32_16x16x32_bf16 v[6:9], v[172:175], v[212:215], v[6:9]
	v_mfma_f32_16x16x32_bf16 v[2:5], v[180:183], v[212:215], v[2:5]
	v_mfma_f32_16x16x32_bf16 v[54:57], v[176:179], v[192:195], v[54:57]
	v_mfma_f32_16x16x32_bf16 v[46:49], v[184:187], v[192:195], v[46:49]
	v_mfma_f32_16x16x32_bf16 v[38:41], v[176:179], v[200:203], v[38:41]
	v_mfma_f32_16x16x32_bf16 v[30:33], v[184:187], v[200:203], v[30:33]
	v_mfma_f32_16x16x32_bf16 v[22:25], v[176:179], v[208:211], v[22:25]
	v_mfma_f32_16x16x32_bf16 v[14:17], v[184:187], v[208:211], v[14:17]
	v_mfma_f32_16x16x32_bf16 v[6:9], v[176:179], v[216:219], v[6:9]
	s_barrier
	v_mfma_f32_16x16x32_bf16 v[2:5], v[184:187], v[216:219], v[2:5]
	s_setprio 0
	s_add_u32 s8, s8, 0x100
	s_addc_u32 s9, s9, 0
	s_add_u32 s77, s77, 0x100
	s_addc_u32 s78, s78, 0
	s_cmp_ge_u32 s79, s75
	s_mov_b32 s50, s79
	s_cbranch_scc0 .LBB0_179
	s_and_b64 vcc, exec, s[24:25]
	s_cbranch_vccz .LBB0_182
	s_barrier

; #define PG8_STAGE(bufoff, gbase, voff) do { _Pragma("unroll") for (int _i = 0; _i < 2; ++_i) \
;         __builtin_amdgcn_global_load_lds((const unsigned*)((const char*)(gbase) + (voff)[_i]), (PG8_LAS unsigned*)(lds + (bufoff) + ldsw + _i * 8192), 16, 0, 0); } while (0)
; #define PG8_LDA(dst, b, h) do { _Pragma("unroll") for (int m = 0; m < 4; ++m) _Pragma("unroll") for (int k = 0; k < 2; ++k) dst[m][k] = *(const PG8_LAS bf16x8*)(lds + PG8_SA(b, h) + aoff + m * 2048 + k * 1024); } while (0)
; #define PG8_LDB(dst, b, h) do { _Pragma("unroll") for (int n = 0; n < 2; ++n) _Pragma("unroll") for (int k = 0; k < 2; ++k) dst[n][k] = *(const PG8_LAS bf16x8*)(lds + PG8_SB(b, h) + boff + n * 2048 + k * 1024); } while (0)
; #define PG8_MMA(ai, bj, At, Bt) do { __builtin_amdgcn_s_setprio(3); _Pragma("unroll") for (int m = 0; m < 4; ++m) _Pragma("unroll") for (int n = 0; n < 2; ++n) _Pragma("unroll") for (int k = 0; k < 2; ++k) \
;         acc[ai][bj][m][n] = __builtin_amdgcn_mfma_f32_16x16x32_bf16(Bt[n][k], At[m][k], acc[ai][bj][m][n], 0, 0, 0); __builtin_amdgcn_s_setprio(0); } while (0)
; #define PG8_WAIT_V(n) asm volatile("s_waitcnt vmcnt(" #n ")" ::: "memory")
; #define PG8_WAIT_L(n) asm volatile("s_waitcnt lgkmcnt(" #n ")" ::: "memory")
; #define PG8_BAR __builtin_amdgcn_s_barrier()
; #define PG8_SCHED __builtin_amdgcn_sched_barrier(0)
; template <class Epi, class Sched, bool ALIGN_EPI = false, bool SP2 = false>
; __device__ __forceinline__ void gemm_phase(PG8_LAS unsigned char* lds, const Gemm g, const Sched& S, const Epi& E) {
;     ...
;             PG8_LDB(B0, 0, 0); PG8_LDB(B1, 0, 1); PG8_SCHED; PG8_LDA(At, 0, 0); PG8_STAGE(PG8_SA(1, 1), a1 + hstep, voffA);
;             PG8_WAIT_V(8); PG8_WAIT_L(0); PG8_BAR; PG8_MMA(0, 0, At, B0); PG8_MMA(0, 1, At, B1); PG8_BAR; PG8_SCHED;
;             PG8_LDA(At, 0, 1); PG8_STAGE(PG8_SB(0, 0), b2, voffB); PG8_STAGE(PG8_SB(0, 1), b2 + hstep, voffB); PG8_STAGE(PG8_SA(0, 0), a2, voffA);
;             PG8_WAIT_V(8); PG8_WAIT_L(0); PG8_BAR; PG8_MMA(1, 0, At, B0); PG8_MMA(1, 1, At, B1); PG8_BAR; PG8_SCHED;
.LBB0_394:
	ds_read_b128 v[148:151], v155
	ds_read_b128 v[158:161], v155 offset:1024
	ds_read_b128 v[162:165], v155 offset:2048
	ds_read_b128 v[168:171], v155 offset:3072
	ds_read_b128 v[172:175], v156
	ds_read_b128 v[176:179], v156 offset:1024
	ds_read_b128 v[180:183], v156 offset:2048
	ds_read_b128 v[184:187], v156 offset:3072
	s_add_u32 s48, s46, 0xfff80080
	s_addc_u32 s49, s47, -1
	s_cmp_eq_u32 s70, 28
	s_cselect_b32 s51, s7, s49
	s_cselect_b32 s50, s27, s48
	s_cselect_b32 s49, s25, s69
	s_cselect_b32 s48, s45, s68
	v_lshl_add_u64 v[152:153], s[46:47], 0, v[138:139]
	s_add_i32 m0, s52, 0xc000
	ds_read_b128 v[188:191], v157
	ds_read_b128 v[192:195], v157 offset:1024
	ds_read_b128 v[196:199], v157 offset:2048
	ds_read_b128 v[200:203], v157 offset:3072
	ds_read_b128 v[204:207], v157 offset:4096
	ds_read_b128 v[208:211], v157 offset:5120
	ds_read_b128 v[212:215], v157 offset:6144
	ds_read_b128 v[216:219], v157 offset:7168
	global_load_lds_dwordx4 v[152:153], off
	v_lshl_add_u64 v[152:153], s[46:47], 0, v[142:143]
	s_add_i32 m0, s52, 0xe000
	s_nop 0
	global_load_lds_dwordx4 v[152:153], off
	s_waitcnt vmcnt(8)
	s_waitcnt lgkmcnt(0)
	s_barrier
	s_setprio 3
	s_waitcnt lgkmcnt(0)
	v_mfma_f32_16x16x32_bf16 v[126:129], v[148:151], v[188:191], v[126:129]
	v_mfma_f32_16x16x32_bf16 v[122:125], v[162:165], v[188:191], v[122:125]
	v_mfma_f32_16x16x32_bf16 v[114:117], v[148:151], v[196:199], v[114:117]
	v_mfma_f32_16x16x32_bf16 v[106:109], v[162:165], v[196:199], v[106:109]
	v_mfma_f32_16x16x32_bf16 v[98:101], v[148:151], v[204:207], v[98:101]
	v_mfma_f32_16x16x32_bf16 v[90:93], v[162:165], v[204:207], v[90:93]
	v_mfma_f32_16x16x32_bf16 v[82:85], v[148:151], v[212:215], v[82:85]
	v_mfma_f32_16x16x32_bf16 v[74:77], v[162:165], v[212:215], v[74:77]
	v_mfma_f32_16x16x32_bf16 v[126:129], v[158:161], v[192:195], v[126:129]
	v_mfma_f32_16x16x32_bf16 v[122:125], v[168:171], v[192:195], v[122:125]
	v_mfma_f32_16x16x32_bf16 v[114:117], v[158:161], v[200:203], v[114:117]
	v_mfma_f32_16x16x32_bf16 v[106:109], v[168:171], v[200:203], v[106:109]
	v_mfma_f32_16x16x32_bf16 v[98:101], v[158:161], v[208:211], v[98:101]
	v_mfma_f32_16x16x32_bf16 v[90:93], v[168:171], v[208:211], v[90:93]
	v_mfma_f32_16x16x32_bf16 v[82:85], v[158:161], v[216:219], v[82:85]
	v_mfma_f32_16x16x32_bf16 v[74:77], v[168:171], v[216:219], v[74:77]
	s_setprio 0
	s_setprio 3
	v_mfma_f32_16x16x32_bf16 v[118:121], v[172:175], v[188:191], v[118:121]
	v_mfma_f32_16x16x32_bf16 v[110:113], v[180:183], v[188:191], v[110:113]
	v_mfma_f32_16x16x32_bf16 v[102:105], v[172:175], v[196:199], v[102:105]
	v_mfma_f32_16x16x32_bf16 v[94:97], v[180:183], v[196:199], v[94:97]
	v_mfma_f32_16x16x32_bf16 v[86:89], v[172:175], v[204:207], v[86:89]
	v_mfma_f32_16x16x32_bf16 v[78:81], v[180:183], v[204:207], v[78:81]
	v_mfma_f32_16x16x32_bf16 v[70:73], v[172:175], v[212:215], v[70:73]
	v_mfma_f32_16x16x32_bf16 v[66:69], v[180:183], v[212:215], v[66:69]
	v_mfma_f32_16x16x32_bf16 v[118:121], v[176:179], v[192:195], v[118:121]
	v_mfma_f32_16x16x32_bf16 v[110:113], v[184:187], v[192:195], v[110:113]
	v_mfma_f32_16x16x32_bf16 v[102:105], v[176:179], v[200:203], v[102:105]
	v_mfma_f32_16x16x32_bf16 v[94:97], v[184:187], v[200:203], v[94:97]
	v_mfma_f32_16x16x32_bf16 v[86:89], v[176:179], v[208:211], v[86:89]
	v_mfma_f32_16x16x32_bf16 v[78:81], v[184:187], v[208:211], v[78:81]
	v_mfma_f32_16x16x32_bf16 v[70:73], v[176:179], v[216:219], v[70:73]
	s_barrier
	v_mfma_f32_16x16x32_bf16 v[66:69], v[184:187], v[216:219], v[66:69]
	s_setprio 0
	s_add_i32 s71, s63, s43
	v_lshl_add_u64 v[152:153], s[48:49], 0, v[132:133]
	s_mov_b32 m0, s71
	ds_read_b128 v[188:191], v157 offset:16384
	ds_read_b128 v[192:195], v157 offset:17408
	ds_read_b128 v[196:199], v157 offset:18432
	ds_read_b128 v[200:203], v157 offset:19456
	ds_read_b128 v[204:207], v157 offset:20480
	ds_read_b128 v[208:211], v157 offset:21504
	ds_read_b128 v[212:215], v157 offset:22528
	ds_read_b128 v[216:219], v157 offset:23552
	global_load_lds_dwordx4 v[152:153], off
	s_add_i32 m0, s71, 0x2000
	s_add_u32 s72, s48, 0x80000
	v_lshl_add_u64 v[220:221], s[48:49], 0, v[136:137]
	s_addc_u32 s73, s49, 0
	s_add_i32 s71, s64, s43
	global_load_lds_dwordx4 v[220:221], off
	v_lshl_add_u64 v[222:223], s[72:73], 0, v[132:133]
	s_mov_b32 m0, s71
	v_lshl_add_u64 v[224:225], s[50:51], 0, v[134:135]
	global_load_lds_dwordx4 v[222:223], off
	v_lshl_add_u64 v[222:223], s[72:73], 0, v[136:137]
	s_add_i32 m0, s71, 0x2000
	s_nop 0
	global_load_lds_dwordx4 v[222:223], off
	v_lshl_add_u64 v[222:223], s[50:51], 0, v[130:131]
	s_mov_b32 m0, s52
	s_nop 0
	global_load_lds_dwordx4 v[222:223], off
	s_mov_b32 m0, s53
	s_nop 0
	global_load_lds_dwordx4 v[224:225], off
	s_waitcnt vmcnt(8)
	s_waitcnt lgkmcnt(0)
	s_barrier
; #define PG8_STAGE(bufoff, gbase, voff) do { _Pragma("unroll") for (int _i = 0; _i < 2; ++_i) \
;         __builtin_amdgcn_global_load_lds((const unsigned*)((const char*)(gbase) + (voff)[_i]), (PG8_LAS unsigned*)(lds + (bufoff) + ldsw + _i * 8192), 16, 0, 0); } while (0)
; #define PG8_LDA(dst, b, h) do { _Pragma("unroll") for (int m = 0; m < 4; ++m) _Pragma("unroll") for (int k = 0; k < 2; ++k) dst[m][k] = *(const PG8_LAS bf16x8*)(lds + PG8_SA(b, h) + aoff + m * 2048 + k * 1024); } while (0)
; #define PG8_LDB(dst, b, h) do { _Pragma("unroll") for (int n = 0; n < 2; ++n) _Pragma("unroll") for (int k = 0; k < 2; ++k) dst[n][k] = *(const PG8_LAS bf16x8*)(lds + PG8_SB(b, h) + boff + n * 2048 + k * 1024); } while (0)
; #define PG8_MMA(ai, bj, At, Bt) do { __builtin_amdgcn_s_setprio(3); _Pragma("unroll") for (int m = 0; m < 4; ++m) _Pragma("unroll") for (int n = 0; n < 2; ++n) _Pragma("unroll") for (int k = 0; k < 2; ++k) \
;         acc[ai][bj][m][n] = __builtin_amdgcn_mfma_f32_16x16x32_bf16(Bt[n][k], At[m][k], acc[ai][bj][m][n], 0, 0, 0); __builtin_amdgcn_s_setprio(0); } while (0)
; #define PG8_WAIT_V(n) asm volatile("s_waitcnt vmcnt(" #n ")" ::: "memory")
; #define PG8_WAIT_L(n) asm volatile("s_waitcnt lgkmcnt(" #n ")" ::: "memory")
; #define PG8_BAR __builtin_amdgcn_s_barrier()
; #define PG8_SCHED __builtin_amdgcn_sched_barrier(0)
; template <class Epi, class Sched, bool ALIGN_EPI = false, bool SP2 = false>
; __device__ __forceinline__ void gemm_phase(PG8_LAS unsigned char* lds, const Gemm g, const Sched& S, const Epi& E) {
;     ...
;             PG8_WAIT_V(8); PG8_WAIT_L(0); PG8_BAR; PG8_MMA(1, 0, At, B0); PG8_MMA(1, 1, At, B1); PG8_BAR; PG8_SCHED;
;             PG8_LDB(B0, 1, 0); PG8_LDB(B1, 1, 1); PG8_SCHED; PG8_LDA(At, 1, 0); PG8_STAGE(PG8_SA(0, 1), a2 + hstep, voffA);
;             PG8_WAIT_V(8); PG8_WAIT_L(0); PG8_BAR; PG8_MMA(0, 0, At, B0); PG8_MMA(0, 1, At, B1); PG8_BAR; PG8_SCHED;
	s_setprio 3
	s_waitcnt lgkmcnt(0)
	v_mfma_f32_16x16x32_bf16 v[62:65], v[148:151], v[188:191], v[62:65]
	v_mfma_f32_16x16x32_bf16 v[58:61], v[162:165], v[188:191], v[58:61]
	v_mfma_f32_16x16x32_bf16 v[50:53], v[148:151], v[196:199], v[50:53]
	v_mfma_f32_16x16x32_bf16 v[42:45], v[162:165], v[196:199], v[42:45]
	v_mfma_f32_16x16x32_bf16 v[34:37], v[148:151], v[204:207], v[34:37]
	v_mfma_f32_16x16x32_bf16 v[26:29], v[162:165], v[204:207], v[26:29]
	v_mfma_f32_16x16x32_bf16 v[18:21], v[148:151], v[212:215], v[18:21]
	v_mfma_f32_16x16x32_bf16 v[10:13], v[162:165], v[212:215], v[10:13]
	v_mfma_f32_16x16x32_bf16 v[62:65], v[158:161], v[192:195], v[62:65]
	v_mfma_f32_16x16x32_bf16 v[58:61], v[168:171], v[192:195], v[58:61]
	v_mfma_f32_16x16x32_bf16 v[50:53], v[158:161], v[200:203], v[50:53]
	v_mfma_f32_16x16x32_bf16 v[42:45], v[168:171], v[200:203], v[42:45]
	v_mfma_f32_16x16x32_bf16 v[34:37], v[158:161], v[208:211], v[34:37]
	v_mfma_f32_16x16x32_bf16 v[26:29], v[168:171], v[208:211], v[26:29]
	v_mfma_f32_16x16x32_bf16 v[18:21], v[158:161], v[216:219], v[18:21]
	v_mfma_f32_16x16x32_bf16 v[10:13], v[168:171], v[216:219], v[10:13]
	s_setprio 0
	s_setprio 3
	v_mfma_f32_16x16x32_bf16 v[54:57], v[172:175], v[188:191], v[54:57]
	v_mfma_f32_16x16x32_bf16 v[46:49], v[180:183], v[188:191], v[46:49]
	v_mfma_f32_16x16x32_bf16 v[38:41], v[172:175], v[196:199], v[38:41]
	v_mfma_f32_16x16x32_bf16 v[30:33], v[180:183], v[196:199], v[30:33]
	v_mfma_f32_16x16x32_bf16 v[22:25], v[172:175], v[204:207], v[22:25]
	v_mfma_f32_16x16x32_bf16 v[14:17], v[180:183], v[204:207], v[14:17]
	v_mfma_f32_16x16x32_bf16 v[6:9], v[172:175], v[212:215], v[6:9]
	v_mfma_f32_16x16x32_bf16 v[2:5], v[180:183], v[212:215], v[2:5]
	v_mfma_f32_16x16x32_bf16 v[54:57], v[176:179], v[192:195], v[54:57]
	v_mfma_f32_16x16x32_bf16 v[46:49], v[184:187], v[192:195], v[46:49]
	v_mfma_f32_16x16x32_bf16 v[38:41], v[176:179], v[200:203], v[38:41]
	v_mfma_f32_16x16x32_bf16 v[30:33], v[184:187], v[200:203], v[30:33]
	v_mfma_f32_16x16x32_bf16 v[22:25], v[176:179], v[208:211], v[22:25]
	v_mfma_f32_16x16x32_bf16 v[14:17], v[184:187], v[208:211], v[14:17]
	v_mfma_f32_16x16x32_bf16 v[6:9], v[176:179], v[216:219], v[6:9]
	s_barrier
	v_mfma_f32_16x16x32_bf16 v[2:5], v[184:187], v[216:219], v[2:5]
	s_setprio 0
	s_add_i32 s71, 0, 0x18000
	v_add_u32_e32 v167, s71, v141
	s_add_i32 s72, 0, 0x1c000
	ds_read_b128 v[148:151], v167
	ds_read_b128 v[158:161], v167 offset:1024
	ds_read_b128 v[162:165], v167 offset:2048
	ds_read_b128 v[168:171], v167 offset:3072
	v_add_u32_e32 v167, s72, v141
	ds_read_b128 v[172:175], v167
	ds_read_b128 v[176:179], v167 offset:1024
	ds_read_b128 v[180:183], v167 offset:2048
	ds_read_b128 v[184:187], v167 offset:3072
	s_add_u32 s50, s50, 0x80000
	s_addc_u32 s51, s51, 0
	s_mov_b32 m0, s54
	v_lshl_add_u64 v[226:227], s[50:51], 0, v[130:131]
	ds_read_b128 v[188:191], v157 offset:32768
	ds_read_b128 v[192:195], v157 offset:33792
	ds_read_b128 v[196:199], v157 offset:34816
	ds_read_b128 v[200:203], v157 offset:35840
	ds_read_b128 v[204:207], v157 offset:36864
	ds_read_b128 v[208:211], v157 offset:37888
	ds_read_b128 v[212:215], v157 offset:38912
	ds_read_b128 v[216:219], v157 offset:39936
	global_load_lds_dwordx4 v[226:227], off
	v_lshl_add_u64 v[226:227], s[50:51], 0, v[134:135]
	s_mov_b32 m0, s55
	s_nop 0
	global_load_lds_dwordx4 v[226:227], off
	s_waitcnt vmcnt(8)
	s_waitcnt lgkmcnt(0)
	s_barrier
	s_setprio 3
	s_waitcnt lgkmcnt(0)
	v_mfma_f32_16x16x32_bf16 v[126:129], v[148:151], v[188:191], v[126:129]
	v_mfma_f32_16x16x32_bf16 v[122:125], v[162:165], v[188:191], v[122:125]
	v_mfma_f32_16x16x32_bf16 v[114:117], v[148:151], v[196:199], v[114:117]
	v_mfma_f32_16x16x32_bf16 v[106:109], v[162:165], v[196:199], v[106:109]
	v_mfma_f32_16x16x32_bf16 v[98:101], v[148:151], v[204:207], v[98:101]
	v_mfma_f32_16x16x32_bf16 v[90:93], v[162:165], v[204:207], v[90:93]
	v_mfma_f32_16x16x32_bf16 v[82:85], v[148:151], v[212:215], v[82:85]
	v_mfma_f32_16x16x32_bf16 v[74:77], v[162:165], v[212:215], v[74:77]
	v_mfma_f32_16x16x32_bf16 v[126:129], v[158:161], v[192:195], v[126:129]
	v_mfma_f32_16x16x32_bf16 v[122:125], v[168:171], v[192:195], v[122:125]
	v_mfma_f32_16x16x32_bf16 v[114:117], v[158:161], v[200:203], v[114:117]
	v_mfma_f32_16x16x32_bf16 v[106:109], v[168:171], v[200:203], v[106:109]
	v_mfma_f32_16x16x32_bf16 v[98:101], v[158:161], v[208:211], v[98:101]
	v_mfma_f32_16x16x32_bf16 v[90:93], v[168:171], v[208:211], v[90:93]
	v_mfma_f32_16x16x32_bf16 v[82:85], v[158:161], v[216:219], v[82:85]
	v_mfma_f32_16x16x32_bf16 v[74:77], v[168:171], v[216:219], v[74:77]
	s_setprio 0
	s_setprio 3
	v_mfma_f32_16x16x32_bf16 v[118:121], v[172:175], v[188:191], v[118:121]
	v_mfma_f32_16x16x32_bf16 v[110:113], v[180:183], v[188:191], v[110:113]
	v_mfma_f32_16x16x32_bf16 v[102:105], v[172:175], v[196:199], v[102:105]
	v_mfma_f32_16x16x32_bf16 v[94:97], v[180:183], v[196:199], v[94:97]
	v_mfma_f32_16x16x32_bf16 v[86:89], v[172:175], v[204:207], v[86:89]
	v_mfma_f32_16x16x32_bf16 v[78:81], v[180:183], v[204:207], v[78:81]
	v_mfma_f32_16x16x32_bf16 v[70:73], v[172:175], v[212:215], v[70:73]
	v_mfma_f32_16x16x32_bf16 v[66:69], v[180:183], v[212:215], v[66:69]
	v_mfma_f32_16x16x32_bf16 v[118:121], v[176:179], v[192:195], v[118:121]
	v_mfma_f32_16x16x32_bf16 v[110:113], v[184:187], v[192:195], v[110:113]
	v_mfma_f32_16x16x32_bf16 v[102:105], v[176:179], v[200:203], v[102:105]
	v_mfma_f32_16x16x32_bf16 v[94:97], v[184:187], v[200:203], v[94:97]
	v_mfma_f32_16x16x32_bf16 v[86:89], v[176:179], v[208:211], v[86:89]
	v_mfma_f32_16x16x32_bf16 v[78:81], v[184:187], v[208:211], v[78:81]
	v_mfma_f32_16x16x32_bf16 v[70:73], v[176:179], v[216:219], v[70:73]
	s_barrier
; #define PG8_STAGE(bufoff, gbase, voff) do { _Pragma("unroll") for (int _i = 0; _i < 2; ++_i) \
;         __builtin_amdgcn_global_load_lds((const unsigned*)((const char*)(gbase) + (voff)[_i]), (PG8_LAS unsigned*)(lds + (bufoff) + ldsw + _i * 8192), 16, 0, 0); } while (0)
; #define PG8_LDA(dst, b, h) do { _Pragma("unroll") for (int m = 0; m < 4; ++m) _Pragma("unroll") for (int k = 0; k < 2; ++k) dst[m][k] = *(const PG8_LAS bf16x8*)(lds + PG8_SA(b, h) + aoff + m * 2048 + k * 1024); } while (0)
; #define PG8_MMA(ai, bj, At, Bt) do { __builtin_amdgcn_s_setprio(3); _Pragma("unroll") for (int m = 0; m < 4; ++m) _Pragma("unroll") for (int n = 0; n < 2; ++n) _Pragma("unroll") for (int k = 0; k < 2; ++k) \
;         acc[ai][bj][m][n] = __builtin_amdgcn_mfma_f32_16x16x32_bf16(Bt[n][k], At[m][k], acc[ai][bj][m][n], 0, 0, 0); __builtin_amdgcn_s_setprio(0); } while (0)
; #define PG8_WAIT_V(n) asm volatile("s_waitcnt vmcnt(" #n ")" ::: "memory")
; #define PG8_WAIT_L(n) asm volatile("s_waitcnt lgkmcnt(" #n ")" ::: "memory")
; #define PG8_BAR __builtin_amdgcn_s_barrier()
; #define PG8_SCHED __builtin_amdgcn_sched_barrier(0)
; template <class Epi, class Sched, bool ALIGN_EPI = false, bool SP2 = false>
; __device__ __forceinline__ void gemm_phase(PG8_LAS unsigned char* lds, const Gemm g, const Sched& S, const Epi& E) {
;     ...
;         for (int t = 0; t < nt; t += 2) {
;     ...
;             PG8_WAIT_V(8); PG8_WAIT_L(0); PG8_BAR; PG8_MMA(0, 0, At, B0); PG8_MMA(0, 1, At, B1); PG8_BAR; PG8_SCHED;
;             PG8_LDA(At, 1, 1); PG8_STAGE(PG8_SB(1, 0), b3, voffB); PG8_STAGE(PG8_SB(1, 1), b3 + hstep, voffB); PG8_STAGE(PG8_SA(1, 0), a3, voffA);
;             PG8_WAIT_V(8); PG8_WAIT_L(0); PG8_BAR; PG8_MMA(1, 0, At, B0); PG8_MMA(1, 1, At, B1); PG8_BAR; PG8_SCHED;
	v_mfma_f32_16x16x32_bf16 v[66:69], v[184:187], v[216:219], v[66:69]
	s_setprio 0
	s_add_i32 s50, s71, s43
	v_lshl_add_u64 v[152:153], v[152:153], 0, s[16:17]
	s_mov_b32 m0, s50
	ds_read_b128 v[188:191], v157 offset:49152
	ds_read_b128 v[192:195], v157 offset:50176
	ds_read_b128 v[196:199], v157 offset:51200
	ds_read_b128 v[200:203], v157 offset:52224
	ds_read_b128 v[204:207], v157 offset:53248
	ds_read_b128 v[208:211], v157 offset:54272
	ds_read_b128 v[212:215], v157 offset:55296
	ds_read_b128 v[216:219], v157 offset:56320
	global_load_lds_dwordx4 v[152:153], off
	s_add_i32 m0, s50, 0x2000
	s_add_u32 s48, s48, 0x80080
	v_lshl_add_u64 v[152:153], v[220:221], 0, s[16:17]
	s_addc_u32 s49, s49, 0
	s_add_i32 s50, s72, s43
	global_load_lds_dwordx4 v[152:153], off
	v_lshl_add_u64 v[152:153], s[48:49], 0, v[132:133]
	s_mov_b32 m0, s50
	s_nop 0
	global_load_lds_dwordx4 v[152:153], off
	v_lshl_add_u64 v[152:153], s[48:49], 0, v[136:137]
	s_add_i32 m0, s50, 0x2000
	s_nop 0
	global_load_lds_dwordx4 v[152:153], off
	v_lshl_add_u64 v[152:153], v[222:223], 0, s[16:17]
	s_mov_b32 m0, s59
	s_nop 0
	global_load_lds_dwordx4 v[152:153], off
	v_lshl_add_u64 v[152:153], v[224:225], 0, s[16:17]
	s_mov_b32 m0, s60
	s_nop 0
	global_load_lds_dwordx4 v[152:153], off
	s_waitcnt vmcnt(8)
	s_waitcnt lgkmcnt(0)
	s_barrier
	s_setprio 3
	s_waitcnt lgkmcnt(0)
	v_mfma_f32_16x16x32_bf16 v[62:65], v[148:151], v[188:191], v[62:65]
	v_mfma_f32_16x16x32_bf16 v[58:61], v[162:165], v[188:191], v[58:61]
	v_mfma_f32_16x16x32_bf16 v[50:53], v[148:151], v[196:199], v[50:53]
	v_mfma_f32_16x16x32_bf16 v[42:45], v[162:165], v[196:199], v[42:45]
	v_mfma_f32_16x16x32_bf16 v[34:37], v[148:151], v[204:207], v[34:37]
	v_mfma_f32_16x16x32_bf16 v[26:29], v[162:165], v[204:207], v[26:29]
	v_mfma_f32_16x16x32_bf16 v[18:21], v[148:151], v[212:215], v[18:21]
	v_mfma_f32_16x16x32_bf16 v[10:13], v[162:165], v[212:215], v[10:13]
	v_mfma_f32_16x16x32_bf16 v[62:65], v[158:161], v[192:195], v[62:65]
	v_mfma_f32_16x16x32_bf16 v[58:61], v[168:171], v[192:195], v[58:61]
	v_mfma_f32_16x16x32_bf16 v[50:53], v[158:161], v[200:203], v[50:53]
	v_mfma_f32_16x16x32_bf16 v[42:45], v[168:171], v[200:203], v[42:45]
	v_mfma_f32_16x16x32_bf16 v[34:37], v[158:161], v[208:211], v[34:37]
	v_mfma_f32_16x16x32_bf16 v[26:29], v[168:171], v[208:211], v[26:29]
	v_mfma_f32_16x16x32_bf16 v[18:21], v[158:161], v[216:219], v[18:21]
	v_mfma_f32_16x16x32_bf16 v[10:13], v[168:171], v[216:219], v[10:13]
	s_setprio 0
	s_setprio 3
	v_mfma_f32_16x16x32_bf16 v[54:57], v[172:175], v[188:191], v[54:57]
	v_mfma_f32_16x16x32_bf16 v[46:49], v[180:183], v[188:191], v[46:49]
	v_mfma_f32_16x16x32_bf16 v[38:41], v[172:175], v[196:199], v[38:41]
	v_mfma_f32_16x16x32_bf16 v[30:33], v[180:183], v[196:199], v[30:33]
	v_mfma_f32_16x16x32_bf16 v[22:25], v[172:175], v[204:207], v[22:25]
	v_mfma_f32_16x16x32_bf16 v[14:17], v[180:183], v[204:207], v[14:17]
	v_mfma_f32_16x16x32_bf16 v[6:9], v[172:175], v[212:215], v[6:9]
	v_mfma_f32_16x16x32_bf16 v[2:5], v[180:183], v[212:215], v[2:5]
	v_mfma_f32_16x16x32_bf16 v[54:57], v[176:179], v[192:195], v[54:57]
	v_mfma_f32_16x16x32_bf16 v[46:49], v[184:187], v[192:195], v[46:49]
	v_mfma_f32_16x16x32_bf16 v[38:41], v[176:179], v[200:203], v[38:41]
	v_mfma_f32_16x16x32_bf16 v[30:33], v[184:187], v[200:203], v[30:33]
	v_mfma_f32_16x16x32_bf16 v[22:25], v[176:179], v[208:211], v[22:25]
	v_mfma_f32_16x16x32_bf16 v[14:17], v[184:187], v[208:211], v[14:17]
	v_mfma_f32_16x16x32_bf16 v[6:9], v[176:179], v[216:219], v[6:9]
	s_barrier
	v_mfma_f32_16x16x32_bf16 v[2:5], v[184:187], v[216:219], v[2:5]
	s_setprio 0
	s_add_i32 s70, s70, 2
	s_add_u32 s46, s46, 0x100
	s_addc_u32 s47, s47, 0
	s_add_u32 s68, s68, 0x100
	s_addc_u32 s69, s69, 0
	s_cmp_gt_u32 s70, 29
	s_cbranch_scc0 .LBB0_394
	s_and_b64 vcc, exec, s[18:19]
	s_cbranch_vccz .LBB0_397
	s_barrier

; #define PG8_STAGE(bufoff, gbase, voff) do { _Pragma("unroll") for (int _i = 0; _i < 2; ++_i) \
;         __builtin_amdgcn_global_load_lds((const unsigned*)((const char*)(gbase) + (voff)[_i]), (PG8_LAS unsigned*)(lds + (bufoff) + ldsw + _i * 8192), 16, 0, 0); } while (0)
; #define PG8_LDA(dst, b, h) do { _Pragma("unroll") for (int m = 0; m < 4; ++m) _Pragma("unroll") for (int k = 0; k < 2; ++k) dst[m][k] = *(const PG8_LAS bf16x8*)(lds + PG8_SA(b, h) + aoff + m * 2048 + k * 1024); } while (0)
; #define PG8_LDB(dst, b, h) do { _Pragma("unroll") for (int n = 0; n < 2; ++n) _Pragma("unroll") for (int k = 0; k < 2; ++k) dst[n][k] = *(const PG8_LAS bf16x8*)(lds + PG8_SB(b, h) + boff + n * 2048 + k * 1024); } while (0)
; #define PG8_MMA(ai, bj, At, Bt) do { __builtin_amdgcn_s_setprio(3); _Pragma("unroll") for (int m = 0; m < 4; ++m) _Pragma("unroll") for (int n = 0; n < 2; ++n) _Pragma("unroll") for (int k = 0; k < 2; ++k) \
;         acc[ai][bj][m][n] = __builtin_amdgcn_mfma_f32_16x16x32_bf16(Bt[n][k], At[m][k], acc[ai][bj][m][n], 0, 0, 0); __builtin_amdgcn_s_setprio(0); } while (0)
; #define PG8_WAIT_V(n) asm volatile("s_waitcnt vmcnt(" #n ")" ::: "memory")
; #define PG8_WAIT_L(n) asm volatile("s_waitcnt lgkmcnt(" #n ")" ::: "memory")
; #define PG8_BAR __builtin_amdgcn_s_barrier()
; #define PG8_SCHED __builtin_amdgcn_sched_barrier(0)
; template <class Epi, class Sched, bool ALIGN_EPI = false, bool SP2 = false>
; __device__ __forceinline__ void gemm_phase(PG8_LAS unsigned char* lds, const Gemm g, const Sched& S, const Epi& E) {
;     ...
;             PG8_LDB(B0, 0, 0); PG8_LDB(B1, 0, 1); PG8_SCHED; PG8_LDA(At, 0, 0); PG8_STAGE(PG8_SA(1, 1), a1 + hstep, voffA);
;             PG8_WAIT_V(8); PG8_WAIT_L(0); PG8_BAR; PG8_MMA(0, 0, At, B0); PG8_MMA(0, 1, At, B1); PG8_BAR; PG8_SCHED;
;             PG8_LDA(At, 0, 1); PG8_STAGE(PG8_SB(0, 0), b2, voffB); PG8_STAGE(PG8_SB(0, 1), b2 + hstep, voffB); PG8_STAGE(PG8_SA(0, 0), a2, voffA);
;             PG8_WAIT_V(8); PG8_WAIT_L(0); PG8_BAR; PG8_MMA(1, 0, At, B0); PG8_MMA(1, 1, At, B1); PG8_BAR; PG8_SCHED;
.LBB0_677:
	ds_read_b128 v[132:135], v168
	ds_read_b128 v[136:139], v168 offset:1024
	ds_read_b128 v[158:161], v168 offset:2048
	ds_read_b128 v[162:165], v168 offset:3072
	ds_read_b128 v[172:175], v169
	ds_read_b128 v[176:179], v169 offset:1024
	ds_read_b128 v[180:183], v169 offset:2048
	ds_read_b128 v[184:187], v169 offset:3072
	s_add_i32 s74, s48, 2
	s_add_u32 s75, s6, 0x80
	s_addc_u32 s49, s7, 0
	s_cmp_eq_u32 s73, s48
	s_cselect_b32 s48, s44, s75
	s_cselect_b32 s49, s45, s49
	s_cselect_b32 s77, s47, s51
	s_cselect_b32 s76, s46, s50
	v_lshl_add_u64 v[74:75], s[6:7], 0, v[150:151]
	s_add_i32 m0, s54, 0xc000
	ds_read_b128 v[188:191], v170
	ds_read_b128 v[192:195], v170 offset:1024
	ds_read_b128 v[196:199], v170 offset:2048
	ds_read_b128 v[200:203], v170 offset:3072
	ds_read_b128 v[204:207], v170 offset:4096
	ds_read_b128 v[208:211], v170 offset:5120
	ds_read_b128 v[212:215], v170 offset:6144
	ds_read_b128 v[216:219], v170 offset:7168
	global_load_lds_dwordx4 v[74:75], off
	v_lshl_add_u64 v[74:75], s[6:7], 0, v[152:153]
	s_add_i32 m0, s54, 0xe000
	s_nop 0
	global_load_lds_dwordx4 v[74:75], off
	s_waitcnt vmcnt(8)
	s_waitcnt lgkmcnt(0)
	s_barrier
	s_setprio 3
	s_waitcnt lgkmcnt(0)
	v_mfma_f32_16x16x32_bf16 v[128:131], v[132:135], v[188:191], v[128:131]
	v_mfma_f32_16x16x32_bf16 v[124:127], v[158:161], v[188:191], v[124:127]
	v_mfma_f32_16x16x32_bf16 v[120:123], v[132:135], v[196:199], v[120:123]
	v_mfma_f32_16x16x32_bf16 v[116:119], v[158:161], v[196:199], v[116:119]
	v_mfma_f32_16x16x32_bf16 v[112:115], v[132:135], v[204:207], v[112:115]
	v_mfma_f32_16x16x32_bf16 v[108:111], v[158:161], v[204:207], v[108:111]
	v_mfma_f32_16x16x32_bf16 v[104:107], v[132:135], v[212:215], v[104:107]
	v_mfma_f32_16x16x32_bf16 v[100:103], v[158:161], v[212:215], v[100:103]
	v_mfma_f32_16x16x32_bf16 v[128:131], v[136:139], v[192:195], v[128:131]
	v_mfma_f32_16x16x32_bf16 v[124:127], v[162:165], v[192:195], v[124:127]
	v_mfma_f32_16x16x32_bf16 v[120:123], v[136:139], v[200:203], v[120:123]
	v_mfma_f32_16x16x32_bf16 v[116:119], v[162:165], v[200:203], v[116:119]
	v_mfma_f32_16x16x32_bf16 v[112:115], v[136:139], v[208:211], v[112:115]
	v_mfma_f32_16x16x32_bf16 v[108:111], v[162:165], v[208:211], v[108:111]
	v_mfma_f32_16x16x32_bf16 v[104:107], v[136:139], v[216:219], v[104:107]
	v_mfma_f32_16x16x32_bf16 v[100:103], v[162:165], v[216:219], v[100:103]
	s_setprio 0
	s_setprio 3
	v_mfma_f32_16x16x32_bf16 v[62:65], v[172:175], v[188:191], v[62:65]
	v_mfma_f32_16x16x32_bf16 v[58:61], v[180:183], v[188:191], v[58:61]
	v_mfma_f32_16x16x32_bf16 v[54:57], v[172:175], v[196:199], v[54:57]
	v_mfma_f32_16x16x32_bf16 v[50:53], v[180:183], v[196:199], v[50:53]
	v_mfma_f32_16x16x32_bf16 v[46:49], v[172:175], v[204:207], v[46:49]
	v_mfma_f32_16x16x32_bf16 v[42:45], v[180:183], v[204:207], v[42:45]
	v_mfma_f32_16x16x32_bf16 v[38:41], v[172:175], v[212:215], v[38:41]
	v_mfma_f32_16x16x32_bf16 v[34:37], v[180:183], v[212:215], v[34:37]
	v_mfma_f32_16x16x32_bf16 v[62:65], v[176:179], v[192:195], v[62:65]
	v_mfma_f32_16x16x32_bf16 v[58:61], v[184:187], v[192:195], v[58:61]
	v_mfma_f32_16x16x32_bf16 v[54:57], v[176:179], v[200:203], v[54:57]
	v_mfma_f32_16x16x32_bf16 v[50:53], v[184:187], v[200:203], v[50:53]
	v_mfma_f32_16x16x32_bf16 v[46:49], v[176:179], v[208:211], v[46:49]
	v_mfma_f32_16x16x32_bf16 v[42:45], v[184:187], v[208:211], v[42:45]
	v_mfma_f32_16x16x32_bf16 v[38:41], v[176:179], v[216:219], v[38:41]
	s_barrier
	v_mfma_f32_16x16x32_bf16 v[34:37], v[184:187], v[216:219], v[34:37]
	s_setprio 0
	s_add_i32 s75, s63, s43
	v_lshl_add_u64 v[220:221], s[76:77], 0, v[146:147]
	s_mov_b32 m0, s75
	ds_read_b128 v[188:191], v170 offset:16384
	ds_read_b128 v[192:195], v170 offset:17408
	ds_read_b128 v[196:199], v170 offset:18432
	ds_read_b128 v[200:203], v170 offset:19456
	ds_read_b128 v[204:207], v170 offset:20480
	ds_read_b128 v[208:211], v170 offset:21504
	ds_read_b128 v[212:215], v170 offset:22528
	ds_read_b128 v[216:219], v170 offset:23552
	global_load_lds_dwordx4 v[220:221], off
	s_add_i32 m0, s75, 0x2000
	v_lshl_add_u64 v[222:223], s[76:77], 0, v[142:143]
	s_add_u32 s76, s76, s14
	s_addc_u32 s77, s77, s15
	s_add_i32 s75, s64, s43
	global_load_lds_dwordx4 v[222:223], off
	v_lshl_add_u64 v[224:225], s[76:77], 0, v[146:147]
	s_mov_b32 m0, s75
	v_lshl_add_u64 v[226:227], s[76:77], 0, v[142:143]
	global_load_lds_dwordx4 v[224:225], off
	s_add_i32 m0, s75, 0x2000
	v_lshl_add_u64 v[228:229], s[48:49], 0, v[148:149]
	global_load_lds_dwordx4 v[226:227], off
	s_mov_b32 m0, s54
	v_lshl_add_u64 v[230:231], s[48:49], 0, v[144:145]
	global_load_lds_dwordx4 v[228:229], off
	s_mov_b32 m0, s55
	s_nop 0
	global_load_lds_dwordx4 v[230:231], off
	s_waitcnt vmcnt(8)
	s_waitcnt lgkmcnt(0)
	s_barrier
; #define PG8_STAGE(bufoff, gbase, voff) do { _Pragma("unroll") for (int _i = 0; _i < 2; ++_i) \
;         __builtin_amdgcn_global_load_lds((const unsigned*)((const char*)(gbase) + (voff)[_i]), (PG8_LAS unsigned*)(lds + (bufoff) + ldsw + _i * 8192), 16, 0, 0); } while (0)
; #define PG8_LDA(dst, b, h) do { _Pragma("unroll") for (int m = 0; m < 4; ++m) _Pragma("unroll") for (int k = 0; k < 2; ++k) dst[m][k] = *(const PG8_LAS bf16x8*)(lds + PG8_SA(b, h) + aoff + m * 2048 + k * 1024); } while (0)
; #define PG8_LDB(dst, b, h) do { _Pragma("unroll") for (int n = 0; n < 2; ++n) _Pragma("unroll") for (int k = 0; k < 2; ++k) dst[n][k] = *(const PG8_LAS bf16x8*)(lds + PG8_SB(b, h) + boff + n * 2048 + k * 1024); } while (0)
; #define PG8_MMA(ai, bj, At, Bt) do { __builtin_amdgcn_s_setprio(3); _Pragma("unroll") for (int m = 0; m < 4; ++m) _Pragma("unroll") for (int n = 0; n < 2; ++n) _Pragma("unroll") for (int k = 0; k < 2; ++k) \
;         acc[ai][bj][m][n] = __builtin_amdgcn_mfma_f32_16x16x32_bf16(Bt[n][k], At[m][k], acc[ai][bj][m][n], 0, 0, 0); __builtin_amdgcn_s_setprio(0); } while (0)
; #define PG8_WAIT_V(n) asm volatile("s_waitcnt vmcnt(" #n ")" ::: "memory")
; #define PG8_WAIT_L(n) asm volatile("s_waitcnt lgkmcnt(" #n ")" ::: "memory")
; #define PG8_BAR __builtin_amdgcn_s_barrier()
; #define PG8_SCHED __builtin_amdgcn_sched_barrier(0)
; template <class Epi, class Sched, bool ALIGN_EPI = false, bool SP2 = false>
; __device__ __forceinline__ void gemm_phase(PG8_LAS unsigned char* lds, const Gemm g, const Sched& S, const Epi& E) {
;     ...
;             PG8_WAIT_V(8); PG8_WAIT_L(0); PG8_BAR; PG8_MMA(1, 0, At, B0); PG8_MMA(1, 1, At, B1); PG8_BAR; PG8_SCHED;
;             PG8_LDB(B0, 1, 0); PG8_LDB(B1, 1, 1); PG8_SCHED; PG8_LDA(At, 1, 0); PG8_STAGE(PG8_SA(0, 1), a2 + hstep, voffA);
;             PG8_WAIT_V(8); PG8_WAIT_L(0); PG8_BAR; PG8_MMA(0, 0, At, B0); PG8_MMA(0, 1, At, B1); PG8_BAR; PG8_SCHED;
	s_setprio 3
	s_waitcnt lgkmcnt(0)
	v_mfma_f32_16x16x32_bf16 v[96:99], v[132:135], v[188:191], v[96:99]
	v_mfma_f32_16x16x32_bf16 v[92:95], v[158:161], v[188:191], v[92:95]
	v_mfma_f32_16x16x32_bf16 v[88:91], v[132:135], v[196:199], v[88:91]
	v_mfma_f32_16x16x32_bf16 v[84:87], v[158:161], v[196:199], v[84:87]
	v_mfma_f32_16x16x32_bf16 v[80:83], v[132:135], v[204:207], v[80:83]
	v_mfma_f32_16x16x32_bf16 v[74:77], v[158:161], v[204:207], v[76:79]
	v_mfma_f32_16x16x32_bf16 v[70:73], v[132:135], v[212:215], v[70:73]
	v_mfma_f32_16x16x32_bf16 v[66:69], v[158:161], v[212:215], v[66:69]
	v_mfma_f32_16x16x32_bf16 v[96:99], v[136:139], v[192:195], v[96:99]
	v_mfma_f32_16x16x32_bf16 v[92:95], v[162:165], v[192:195], v[92:95]
	v_mfma_f32_16x16x32_bf16 v[88:91], v[136:139], v[200:203], v[88:91]
	v_mfma_f32_16x16x32_bf16 v[84:87], v[162:165], v[200:203], v[84:87]
	v_mfma_f32_16x16x32_bf16 v[80:83], v[136:139], v[208:211], v[80:83]
	v_mfma_f32_16x16x32_bf16 v[74:77], v[162:165], v[208:211], v[74:77]
	v_mfma_f32_16x16x32_bf16 v[70:73], v[136:139], v[216:219], v[70:73]
	v_mfma_f32_16x16x32_bf16 v[66:69], v[162:165], v[216:219], v[66:69]
	s_setprio 0
	s_setprio 3
	v_mfma_f32_16x16x32_bf16 v[30:33], v[172:175], v[188:191], v[30:33]
	v_mfma_f32_16x16x32_bf16 v[26:29], v[180:183], v[188:191], v[26:29]
	v_mfma_f32_16x16x32_bf16 v[22:25], v[172:175], v[196:199], v[22:25]
	v_mfma_f32_16x16x32_bf16 v[18:21], v[180:183], v[196:199], v[18:21]
	v_mfma_f32_16x16x32_bf16 v[14:17], v[172:175], v[204:207], v[14:17]
	v_mfma_f32_16x16x32_bf16 v[10:13], v[180:183], v[204:207], v[10:13]
	v_mfma_f32_16x16x32_bf16 v[6:9], v[172:175], v[212:215], v[6:9]
	v_mfma_f32_16x16x32_bf16 v[2:5], v[180:183], v[212:215], v[2:5]
	v_mfma_f32_16x16x32_bf16 v[30:33], v[176:179], v[192:195], v[30:33]
	v_mfma_f32_16x16x32_bf16 v[26:29], v[184:187], v[192:195], v[26:29]
	v_mfma_f32_16x16x32_bf16 v[22:25], v[176:179], v[200:203], v[22:25]
	v_mfma_f32_16x16x32_bf16 v[18:21], v[184:187], v[200:203], v[18:21]
	v_mfma_f32_16x16x32_bf16 v[14:17], v[176:179], v[208:211], v[14:17]
	v_mfma_f32_16x16x32_bf16 v[10:13], v[184:187], v[208:211], v[10:13]
	v_mfma_f32_16x16x32_bf16 v[6:9], v[176:179], v[216:219], v[6:9]
	s_barrier
	v_mfma_f32_16x16x32_bf16 v[2:5], v[184:187], v[216:219], v[2:5]
	s_setprio 0
	s_add_i32 s75, 0, 0x18000
	v_add_u32_e32 v78, s75, v141
	s_add_i32 s76, 0, 0x1c000
	ds_read_b128 v[132:135], v78
	ds_read_b128 v[136:139], v78 offset:1024
	ds_read_b128 v[158:161], v78 offset:2048
	ds_read_b128 v[162:165], v78 offset:3072
	v_add_u32_e32 v78, s76, v141
	ds_read_b128 v[172:175], v78
	ds_read_b128 v[176:179], v78 offset:1024
	ds_read_b128 v[180:183], v78 offset:2048
	ds_read_b128 v[184:187], v78 offset:3072
	s_add_u32 s48, s48, s14
	s_addc_u32 s49, s49, s15
	s_mov_b32 m0, s56
	v_lshl_add_u64 v[78:79], s[48:49], 0, v[148:149]
	ds_read_b128 v[188:191], v170 offset:32768
	ds_read_b128 v[192:195], v170 offset:33792
	ds_read_b128 v[196:199], v170 offset:34816
	ds_read_b128 v[200:203], v170 offset:35840
	ds_read_b128 v[204:207], v170 offset:36864
	ds_read_b128 v[208:211], v170 offset:37888
	ds_read_b128 v[212:215], v170 offset:38912
	ds_read_b128 v[216:219], v170 offset:39936
	global_load_lds_dwordx4 v[78:79], off
	v_lshl_add_u64 v[78:79], s[48:49], 0, v[144:145]
	s_mov_b32 m0, s57
	s_nop 0
	global_load_lds_dwordx4 v[78:79], off
	s_waitcnt vmcnt(8)
	s_waitcnt lgkmcnt(0)
	s_barrier
	s_setprio 3
	s_waitcnt lgkmcnt(0)
	v_mfma_f32_16x16x32_bf16 v[128:131], v[132:135], v[188:191], v[128:131]
	v_mfma_f32_16x16x32_bf16 v[124:127], v[158:161], v[188:191], v[124:127]
	v_mfma_f32_16x16x32_bf16 v[120:123], v[132:135], v[196:199], v[120:123]
	v_mfma_f32_16x16x32_bf16 v[116:119], v[158:161], v[196:199], v[116:119]
	v_mfma_f32_16x16x32_bf16 v[112:115], v[132:135], v[204:207], v[112:115]
	v_mfma_f32_16x16x32_bf16 v[108:111], v[158:161], v[204:207], v[108:111]
	v_mfma_f32_16x16x32_bf16 v[104:107], v[132:135], v[212:215], v[104:107]
	v_mfma_f32_16x16x32_bf16 v[100:103], v[158:161], v[212:215], v[100:103]
	v_mfma_f32_16x16x32_bf16 v[128:131], v[136:139], v[192:195], v[128:131]
	v_mfma_f32_16x16x32_bf16 v[124:127], v[162:165], v[192:195], v[124:127]
	v_mfma_f32_16x16x32_bf16 v[120:123], v[136:139], v[200:203], v[120:123]
	v_mfma_f32_16x16x32_bf16 v[116:119], v[162:165], v[200:203], v[116:119]
	v_mfma_f32_16x16x32_bf16 v[112:115], v[136:139], v[208:211], v[112:115]
	v_mfma_f32_16x16x32_bf16 v[108:111], v[162:165], v[208:211], v[108:111]
	v_mfma_f32_16x16x32_bf16 v[104:107], v[136:139], v[216:219], v[104:107]
	v_mfma_f32_16x16x32_bf16 v[100:103], v[162:165], v[216:219], v[100:103]
	s_setprio 0
	s_setprio 3
	v_mfma_f32_16x16x32_bf16 v[62:65], v[172:175], v[188:191], v[62:65]
	v_mfma_f32_16x16x32_bf16 v[58:61], v[180:183], v[188:191], v[58:61]
	v_mfma_f32_16x16x32_bf16 v[54:57], v[172:175], v[196:199], v[54:57]
	v_mfma_f32_16x16x32_bf16 v[50:53], v[180:183], v[196:199], v[50:53]
	v_mfma_f32_16x16x32_bf16 v[46:49], v[172:175], v[204:207], v[46:49]
	v_mfma_f32_16x16x32_bf16 v[42:45], v[180:183], v[204:207], v[42:45]
	v_mfma_f32_16x16x32_bf16 v[38:41], v[172:175], v[212:215], v[38:41]
	v_mfma_f32_16x16x32_bf16 v[34:37], v[180:183], v[212:215], v[34:37]
	v_mfma_f32_16x16x32_bf16 v[62:65], v[176:179], v[192:195], v[62:65]
	v_mfma_f32_16x16x32_bf16 v[58:61], v[184:187], v[192:195], v[58:61]
	v_mfma_f32_16x16x32_bf16 v[54:57], v[176:179], v[200:203], v[54:57]
	v_mfma_f32_16x16x32_bf16 v[50:53], v[184:187], v[200:203], v[50:53]
	v_mfma_f32_16x16x32_bf16 v[46:49], v[176:179], v[208:211], v[46:49]
	v_mfma_f32_16x16x32_bf16 v[42:45], v[184:187], v[208:211], v[42:45]
	v_mfma_f32_16x16x32_bf16 v[38:41], v[176:179], v[216:219], v[38:41]
	s_barrier
; #define PG8_STAGE(bufoff, gbase, voff) do { _Pragma("unroll") for (int _i = 0; _i < 2; ++_i) \
;         __builtin_amdgcn_global_load_lds((const unsigned*)((const char*)(gbase) + (voff)[_i]), (PG8_LAS unsigned*)(lds + (bufoff) + ldsw + _i * 8192), 16, 0, 0); } while (0)
; #define PG8_LDA(dst, b, h) do { _Pragma("unroll") for (int m = 0; m < 4; ++m) _Pragma("unroll") for (int k = 0; k < 2; ++k) dst[m][k] = *(const PG8_LAS bf16x8*)(lds + PG8_SA(b, h) + aoff + m * 2048 + k * 1024); } while (0)
; #define PG8_MMA(ai, bj, At, Bt) do { __builtin_amdgcn_s_setprio(3); _Pragma("unroll") for (int m = 0; m < 4; ++m) _Pragma("unroll") for (int n = 0; n < 2; ++n) _Pragma("unroll") for (int k = 0; k < 2; ++k) \
;         acc[ai][bj][m][n] = __builtin_amdgcn_mfma_f32_16x16x32_bf16(Bt[n][k], At[m][k], acc[ai][bj][m][n], 0, 0, 0); __builtin_amdgcn_s_setprio(0); } while (0)
; #define PG8_WAIT_V(n) asm volatile("s_waitcnt vmcnt(" #n ")" ::: "memory")
; #define PG8_WAIT_L(n) asm volatile("s_waitcnt lgkmcnt(" #n ")" ::: "memory")
; #define PG8_BAR __builtin_amdgcn_s_barrier()
; #define PG8_SCHED __builtin_amdgcn_sched_barrier(0)
; template <class Epi, class Sched, bool ALIGN_EPI = false, bool SP2 = false>
; __device__ __forceinline__ void gemm_phase(PG8_LAS unsigned char* lds, const Gemm g, const Sched& S, const Epi& E) {
;     ...
;         for (int t = 0; t < nt; t += 2) {
;     ...
;             PG8_WAIT_V(8); PG8_WAIT_L(0); PG8_BAR; PG8_MMA(0, 0, At, B0); PG8_MMA(0, 1, At, B1); PG8_BAR; PG8_SCHED;
;             PG8_LDA(At, 1, 1); PG8_STAGE(PG8_SB(1, 0), b3, voffB); PG8_STAGE(PG8_SB(1, 1), b3 + hstep, voffB); PG8_STAGE(PG8_SA(1, 0), a3, voffA);
;             PG8_WAIT_V(8); PG8_WAIT_L(0); PG8_BAR; PG8_MMA(1, 0, At, B0); PG8_MMA(1, 1, At, B1); PG8_BAR; PG8_SCHED;
	v_mfma_f32_16x16x32_bf16 v[34:37], v[184:187], v[216:219], v[34:37]
	s_setprio 0
	s_add_i32 s48, s75, s43
	v_lshl_add_u64 v[78:79], v[220:221], 0, s[28:29]
	s_mov_b32 m0, s48
	ds_read_b128 v[188:191], v170 offset:49152
	ds_read_b128 v[192:195], v170 offset:50176
	ds_read_b128 v[196:199], v170 offset:51200
	ds_read_b128 v[200:203], v170 offset:52224
	ds_read_b128 v[204:207], v170 offset:53248
	ds_read_b128 v[208:211], v170 offset:54272
	ds_read_b128 v[212:215], v170 offset:55296
	ds_read_b128 v[216:219], v170 offset:56320
	global_load_lds_dwordx4 v[78:79], off
	v_lshl_add_u64 v[78:79], v[222:223], 0, s[28:29]
	s_add_i32 m0, s48, 0x2000
	s_add_i32 s48, s76, s43
	global_load_lds_dwordx4 v[78:79], off
	v_lshl_add_u64 v[78:79], v[224:225], 0, s[28:29]
	s_mov_b32 m0, s48
	s_nop 0
	global_load_lds_dwordx4 v[78:79], off
	v_lshl_add_u64 v[78:79], v[226:227], 0, s[28:29]
	s_add_i32 m0, s48, 0x2000
	s_nop 0
	global_load_lds_dwordx4 v[78:79], off
	v_lshl_add_u64 v[78:79], v[228:229], 0, s[28:29]
	s_mov_b32 m0, s60
	s_nop 0
	global_load_lds_dwordx4 v[78:79], off
	v_lshl_add_u64 v[78:79], v[230:231], 0, s[28:29]
	s_mov_b32 m0, s61
	s_nop 0
	global_load_lds_dwordx4 v[78:79], off
	s_waitcnt vmcnt(8)
	s_waitcnt lgkmcnt(0)
	s_barrier
	s_setprio 3
	s_waitcnt lgkmcnt(0)
	v_mfma_f32_16x16x32_bf16 v[96:99], v[132:135], v[188:191], v[96:99]
	v_mfma_f32_16x16x32_bf16 v[92:95], v[158:161], v[188:191], v[92:95]
	v_mfma_f32_16x16x32_bf16 v[88:91], v[132:135], v[196:199], v[88:91]
	v_mfma_f32_16x16x32_bf16 v[84:87], v[158:161], v[196:199], v[84:87]
	v_mfma_f32_16x16x32_bf16 v[78:81], v[132:135], v[204:207], v[80:83]
	v_mfma_f32_16x16x32_bf16 v[74:77], v[158:161], v[204:207], v[74:77]
	v_mfma_f32_16x16x32_bf16 v[70:73], v[132:135], v[212:215], v[70:73]
	v_mfma_f32_16x16x32_bf16 v[66:69], v[158:161], v[212:215], v[66:69]
	v_mfma_f32_16x16x32_bf16 v[96:99], v[136:139], v[192:195], v[96:99]
	v_mfma_f32_16x16x32_bf16 v[92:95], v[162:165], v[192:195], v[92:95]
	v_mfma_f32_16x16x32_bf16 v[88:91], v[136:139], v[200:203], v[88:91]
	v_mfma_f32_16x16x32_bf16 v[84:87], v[162:165], v[200:203], v[84:87]
	v_mfma_f32_16x16x32_bf16 v[80:83], v[136:139], v[208:211], v[78:81]
	v_mfma_f32_16x16x32_bf16 v[76:79], v[162:165], v[208:211], v[74:77]
	v_mfma_f32_16x16x32_bf16 v[70:73], v[136:139], v[216:219], v[70:73]
	v_mfma_f32_16x16x32_bf16 v[66:69], v[162:165], v[216:219], v[66:69]
	s_setprio 0
	s_setprio 3
	v_mfma_f32_16x16x32_bf16 v[30:33], v[172:175], v[188:191], v[30:33]
	v_mfma_f32_16x16x32_bf16 v[26:29], v[180:183], v[188:191], v[26:29]
	v_mfma_f32_16x16x32_bf16 v[22:25], v[172:175], v[196:199], v[22:25]
	v_mfma_f32_16x16x32_bf16 v[18:21], v[180:183], v[196:199], v[18:21]
	v_mfma_f32_16x16x32_bf16 v[14:17], v[172:175], v[204:207], v[14:17]
	v_mfma_f32_16x16x32_bf16 v[10:13], v[180:183], v[204:207], v[10:13]
	v_mfma_f32_16x16x32_bf16 v[6:9], v[172:175], v[212:215], v[6:9]
	v_mfma_f32_16x16x32_bf16 v[2:5], v[180:183], v[212:215], v[2:5]
	v_mfma_f32_16x16x32_bf16 v[30:33], v[176:179], v[192:195], v[30:33]
	v_mfma_f32_16x16x32_bf16 v[26:29], v[184:187], v[192:195], v[26:29]
	v_mfma_f32_16x16x32_bf16 v[22:25], v[176:179], v[200:203], v[22:25]
	v_mfma_f32_16x16x32_bf16 v[18:21], v[184:187], v[200:203], v[18:21]
	v_mfma_f32_16x16x32_bf16 v[14:17], v[176:179], v[208:211], v[14:17]
	v_mfma_f32_16x16x32_bf16 v[10:13], v[184:187], v[208:211], v[10:13]
	v_mfma_f32_16x16x32_bf16 v[6:9], v[176:179], v[216:219], v[6:9]
	s_barrier
	v_mfma_f32_16x16x32_bf16 v[2:5], v[184:187], v[216:219], v[2:5]
	s_setprio 0
	s_add_u32 s6, s6, 0x100
	s_addc_u32 s7, s7, 0
	s_add_u32 s50, s50, 0x100
	s_addc_u32 s51, s51, 0
	s_cmp_ge_u32 s74, s72
	s_mov_b32 s48, s74
	s_cbranch_scc0 .LBB0_677
	s_and_b64 vcc, exec, s[30:31]
	s_cbranch_vccz .LBB0_680
	s_barrier

; #define PG8_STAGE(bufoff, gbase, voff) do { _Pragma("unroll") for (int _i = 0; _i < 2; ++_i) \
;         __builtin_amdgcn_global_load_lds((const unsigned*)((const char*)(gbase) + (voff)[_i]), (PG8_LAS unsigned*)(lds + (bufoff) + ldsw + _i * 8192), 16, 0, 0); } while (0)
; #define PG8_LDA(dst, b, h) do { _Pragma("unroll") for (int m = 0; m < 4; ++m) _Pragma("unroll") for (int k = 0; k < 2; ++k) dst[m][k] = *(const PG8_LAS bf16x8*)(lds + PG8_SA(b, h) + aoff + m * 2048 + k * 1024); } while (0)
; #define PG8_LDB(dst, b, h) do { _Pragma("unroll") for (int n = 0; n < 2; ++n) _Pragma("unroll") for (int k = 0; k < 2; ++k) dst[n][k] = *(const PG8_LAS bf16x8*)(lds + PG8_SB(b, h) + boff + n * 2048 + k * 1024); } while (0)
; #define PG8_MMA(ai, bj, At, Bt) do { __builtin_amdgcn_s_setprio(3); _Pragma("unroll") for (int m = 0; m < 4; ++m) _Pragma("unroll") for (int n = 0; n < 2; ++n) _Pragma("unroll") for (int k = 0; k < 2; ++k) \
;         acc[ai][bj][m][n] = __builtin_amdgcn_mfma_f32_16x16x32_bf16(Bt[n][k], At[m][k], acc[ai][bj][m][n], 0, 0, 0); __builtin_amdgcn_s_setprio(0); } while (0)
; #define PG8_WAIT_V(n) asm volatile("s_waitcnt vmcnt(" #n ")" ::: "memory")
; #define PG8_WAIT_L(n) asm volatile("s_waitcnt lgkmcnt(" #n ")" ::: "memory")
; #define PG8_BAR __builtin_amdgcn_s_barrier()
; #define PG8_SCHED __builtin_amdgcn_sched_barrier(0)
; template <class Epi, class Sched, bool ALIGN_EPI = false, bool SP2 = false>
; __device__ __forceinline__ void gemm_phase(PG8_LAS unsigned char* lds, const Gemm g, const Sched& S, const Epi& E) {
;     ...
;             PG8_LDB(B0, 0, 0); PG8_LDB(B1, 0, 1); PG8_SCHED; PG8_LDA(At, 0, 0); PG8_STAGE(PG8_SA(1, 1), a1 + hstep, voffA);
;             PG8_WAIT_V(8); PG8_WAIT_L(0); PG8_BAR; PG8_MMA(0, 0, At, B0); PG8_MMA(0, 1, At, B1); PG8_BAR; PG8_SCHED;
;             PG8_LDA(At, 0, 1); PG8_STAGE(PG8_SB(0, 0), b2, voffB); PG8_STAGE(PG8_SB(0, 1), b2 + hstep, voffB); PG8_STAGE(PG8_SA(0, 0), a2, voffA);
;             PG8_WAIT_V(8); PG8_WAIT_L(0); PG8_BAR; PG8_MMA(1, 0, At, B0); PG8_MMA(1, 1, At, B1); PG8_BAR; PG8_SCHED;
.LBB0_1013:
	ds_read_b128 v[148:151], v157
	ds_read_b128 v[152:155], v157 offset:1024
	ds_read_b128 v[160:163], v157 offset:2048
	ds_read_b128 v[168:171], v157 offset:3072
	ds_read_b128 v[172:175], v158
	ds_read_b128 v[176:179], v158 offset:1024
	ds_read_b128 v[180:183], v158 offset:2048
	ds_read_b128 v[184:187], v158 offset:3072
	s_add_i32 s79, s55, 2
	s_add_u32 s10, s56, 0xfff80080
	s_addc_u32 s11, s57, -1
	s_cmp_eq_u32 s9, s55
	s_cselect_b32 s61, s49, s11
	s_cselect_b32 s60, s48, s10
	s_cselect_b32 s59, s53, s51
	s_cselect_b32 s58, s52, s47
	v_lshl_add_u64 v[164:165], s[56:57], 0, v[138:139]
	s_add_i32 m0, s43, 0xc000
	ds_read_b128 v[188:191], v159
	ds_read_b128 v[192:195], v159 offset:1024
	ds_read_b128 v[196:199], v159 offset:2048
	ds_read_b128 v[200:203], v159 offset:3072
	ds_read_b128 v[204:207], v159 offset:4096
	ds_read_b128 v[208:211], v159 offset:5120
	ds_read_b128 v[212:215], v159 offset:6144
	ds_read_b128 v[216:219], v159 offset:7168
	global_load_lds_dwordx4 v[164:165], off
	v_lshl_add_u64 v[164:165], s[56:57], 0, v[142:143]
	s_add_i32 m0, s43, 0xe000
	s_nop 0
	global_load_lds_dwordx4 v[164:165], off
	s_waitcnt vmcnt(8)
	s_waitcnt lgkmcnt(0)
	s_barrier
	s_setprio 3
	s_waitcnt lgkmcnt(0)
	v_mfma_f32_16x16x32_bf16 v[126:129], v[148:151], v[188:191], v[126:129]
	v_mfma_f32_16x16x32_bf16 v[122:125], v[160:163], v[188:191], v[122:125]
	v_mfma_f32_16x16x32_bf16 v[114:117], v[148:151], v[196:199], v[114:117]
	v_mfma_f32_16x16x32_bf16 v[106:109], v[160:163], v[196:199], v[106:109]
	v_mfma_f32_16x16x32_bf16 v[98:101], v[148:151], v[204:207], v[98:101]
	v_mfma_f32_16x16x32_bf16 v[90:93], v[160:163], v[204:207], v[90:93]
	v_mfma_f32_16x16x32_bf16 v[82:85], v[148:151], v[212:215], v[82:85]
	v_mfma_f32_16x16x32_bf16 v[74:77], v[160:163], v[212:215], v[74:77]
	v_mfma_f32_16x16x32_bf16 v[126:129], v[152:155], v[192:195], v[126:129]
	v_mfma_f32_16x16x32_bf16 v[122:125], v[168:171], v[192:195], v[122:125]
	v_mfma_f32_16x16x32_bf16 v[114:117], v[152:155], v[200:203], v[114:117]
	v_mfma_f32_16x16x32_bf16 v[106:109], v[168:171], v[200:203], v[106:109]
	v_mfma_f32_16x16x32_bf16 v[98:101], v[152:155], v[208:211], v[98:101]
	v_mfma_f32_16x16x32_bf16 v[90:93], v[168:171], v[208:211], v[90:93]
	v_mfma_f32_16x16x32_bf16 v[82:85], v[152:155], v[216:219], v[82:85]
	v_mfma_f32_16x16x32_bf16 v[74:77], v[168:171], v[216:219], v[74:77]
	s_setprio 0
	s_setprio 3
	v_mfma_f32_16x16x32_bf16 v[118:121], v[172:175], v[188:191], v[118:121]
	v_mfma_f32_16x16x32_bf16 v[110:113], v[180:183], v[188:191], v[110:113]
	v_mfma_f32_16x16x32_bf16 v[102:105], v[172:175], v[196:199], v[102:105]
	v_mfma_f32_16x16x32_bf16 v[94:97], v[180:183], v[196:199], v[94:97]
	v_mfma_f32_16x16x32_bf16 v[86:89], v[172:175], v[204:207], v[86:89]
	v_mfma_f32_16x16x32_bf16 v[78:81], v[180:183], v[204:207], v[78:81]
	v_mfma_f32_16x16x32_bf16 v[70:73], v[172:175], v[212:215], v[70:73]
	v_mfma_f32_16x16x32_bf16 v[66:69], v[180:183], v[212:215], v[66:69]
	v_mfma_f32_16x16x32_bf16 v[118:121], v[176:179], v[192:195], v[118:121]
	v_mfma_f32_16x16x32_bf16 v[110:113], v[184:187], v[192:195], v[110:113]
	v_mfma_f32_16x16x32_bf16 v[102:105], v[176:179], v[200:203], v[102:105]
	v_mfma_f32_16x16x32_bf16 v[94:97], v[184:187], v[200:203], v[94:97]
	v_mfma_f32_16x16x32_bf16 v[86:89], v[176:179], v[208:211], v[86:89]
	v_mfma_f32_16x16x32_bf16 v[78:81], v[184:187], v[208:211], v[78:81]
	v_mfma_f32_16x16x32_bf16 v[70:73], v[176:179], v[216:219], v[70:73]
	s_barrier
	v_mfma_f32_16x16x32_bf16 v[66:69], v[184:187], v[216:219], v[66:69]
	s_setprio 0
	s_add_i32 s10, s72, s42
	v_lshl_add_u64 v[164:165], s[58:59], 0, v[132:133]
	s_mov_b32 m0, s10
	ds_read_b128 v[188:191], v159 offset:16384
	ds_read_b128 v[192:195], v159 offset:17408
	ds_read_b128 v[196:199], v159 offset:18432
	ds_read_b128 v[200:203], v159 offset:19456
	ds_read_b128 v[204:207], v159 offset:20480
	ds_read_b128 v[208:211], v159 offset:21504
	ds_read_b128 v[212:215], v159 offset:22528
	ds_read_b128 v[216:219], v159 offset:23552
	global_load_lds_dwordx4 v[164:165], off
	s_add_i32 m0, s10, 0x2000
	s_add_u32 s82, s58, 0x80000
	v_lshl_add_u64 v[220:221], s[58:59], 0, v[136:137]
	s_addc_u32 s83, s59, 0
	s_add_i32 s10, s73, s42
	global_load_lds_dwordx4 v[220:221], off
	v_lshl_add_u64 v[222:223], s[82:83], 0, v[132:133]
	s_mov_b32 m0, s10
	v_lshl_add_u64 v[224:225], s[60:61], 0, v[134:135]
	global_load_lds_dwordx4 v[222:223], off
	v_lshl_add_u64 v[222:223], s[82:83], 0, v[136:137]
	s_add_i32 m0, s10, 0x2000
	s_nop 0
	global_load_lds_dwordx4 v[222:223], off
	v_lshl_add_u64 v[222:223], s[60:61], 0, v[130:131]
	s_mov_b32 m0, s43
	s_nop 0
	global_load_lds_dwordx4 v[222:223], off
	s_mov_b32 m0, s62
	s_nop 0
	global_load_lds_dwordx4 v[224:225], off
	s_waitcnt vmcnt(8)
	s_waitcnt lgkmcnt(0)
	s_barrier
; #define PG8_STAGE(bufoff, gbase, voff) do { _Pragma("unroll") for (int _i = 0; _i < 2; ++_i) \
;         __builtin_amdgcn_global_load_lds((const unsigned*)((const char*)(gbase) + (voff)[_i]), (PG8_LAS unsigned*)(lds + (bufoff) + ldsw + _i * 8192), 16, 0, 0); } while (0)
; #define PG8_LDA(dst, b, h) do { _Pragma("unroll") for (int m = 0; m < 4; ++m) _Pragma("unroll") for (int k = 0; k < 2; ++k) dst[m][k] = *(const PG8_LAS bf16x8*)(lds + PG8_SA(b, h) + aoff + m * 2048 + k * 1024); } while (0)
; #define PG8_LDB(dst, b, h) do { _Pragma("unroll") for (int n = 0; n < 2; ++n) _Pragma("unroll") for (int k = 0; k < 2; ++k) dst[n][k] = *(const PG8_LAS bf16x8*)(lds + PG8_SB(b, h) + boff + n * 2048 + k * 1024); } while (0)
; #define PG8_MMA(ai, bj, At, Bt) do { __builtin_amdgcn_s_setprio(3); _Pragma("unroll") for (int m = 0; m < 4; ++m) _Pragma("unroll") for (int n = 0; n < 2; ++n) _Pragma("unroll") for (int k = 0; k < 2; ++k) \
;         acc[ai][bj][m][n] = __builtin_amdgcn_mfma_f32_16x16x32_bf16(Bt[n][k], At[m][k], acc[ai][bj][m][n], 0, 0, 0); __builtin_amdgcn_s_setprio(0); } while (0)
; #define PG8_WAIT_V(n) asm volatile("s_waitcnt vmcnt(" #n ")" ::: "memory")
; #define PG8_WAIT_L(n) asm volatile("s_waitcnt lgkmcnt(" #n ")" ::: "memory")
; #define PG8_BAR __builtin_amdgcn_s_barrier()
; #define PG8_SCHED __builtin_amdgcn_sched_barrier(0)
; template <class Epi, class Sched, bool ALIGN_EPI = false, bool SP2 = false>
; __device__ __forceinline__ void gemm_phase(PG8_LAS unsigned char* lds, const Gemm g, const Sched& S, const Epi& E) {
;     ...
;             PG8_WAIT_V(8); PG8_WAIT_L(0); PG8_BAR; PG8_MMA(1, 0, At, B0); PG8_MMA(1, 1, At, B1); PG8_BAR; PG8_SCHED;
;             PG8_LDB(B0, 1, 0); PG8_LDB(B1, 1, 1); PG8_SCHED; PG8_LDA(At, 1, 0); PG8_STAGE(PG8_SA(0, 1), a2 + hstep, voffA);
;             PG8_WAIT_V(8); PG8_WAIT_L(0); PG8_BAR; PG8_MMA(0, 0, At, B0); PG8_MMA(0, 1, At, B1); PG8_BAR; PG8_SCHED;
	s_setprio 3
	s_waitcnt lgkmcnt(0)
	v_mfma_f32_16x16x32_bf16 v[62:65], v[148:151], v[188:191], v[62:65]
	v_mfma_f32_16x16x32_bf16 v[58:61], v[160:163], v[188:191], v[58:61]
	v_mfma_f32_16x16x32_bf16 v[50:53], v[148:151], v[196:199], v[50:53]
	v_mfma_f32_16x16x32_bf16 v[42:45], v[160:163], v[196:199], v[42:45]
	v_mfma_f32_16x16x32_bf16 v[34:37], v[148:151], v[204:207], v[34:37]
	v_mfma_f32_16x16x32_bf16 v[26:29], v[160:163], v[204:207], v[26:29]
	v_mfma_f32_16x16x32_bf16 v[18:21], v[148:151], v[212:215], v[18:21]
	v_mfma_f32_16x16x32_bf16 v[10:13], v[160:163], v[212:215], v[10:13]
	v_mfma_f32_16x16x32_bf16 v[62:65], v[152:155], v[192:195], v[62:65]
	v_mfma_f32_16x16x32_bf16 v[58:61], v[168:171], v[192:195], v[58:61]
	v_mfma_f32_16x16x32_bf16 v[50:53], v[152:155], v[200:203], v[50:53]
	v_mfma_f32_16x16x32_bf16 v[42:45], v[168:171], v[200:203], v[42:45]
	v_mfma_f32_16x16x32_bf16 v[34:37], v[152:155], v[208:211], v[34:37]
	v_mfma_f32_16x16x32_bf16 v[26:29], v[168:171], v[208:211], v[26:29]
	v_mfma_f32_16x16x32_bf16 v[18:21], v[152:155], v[216:219], v[18:21]
	v_mfma_f32_16x16x32_bf16 v[10:13], v[168:171], v[216:219], v[10:13]
	s_setprio 0
	s_setprio 3
	v_mfma_f32_16x16x32_bf16 v[54:57], v[172:175], v[188:191], v[54:57]
	v_mfma_f32_16x16x32_bf16 v[46:49], v[180:183], v[188:191], v[46:49]
	v_mfma_f32_16x16x32_bf16 v[38:41], v[172:175], v[196:199], v[38:41]
	v_mfma_f32_16x16x32_bf16 v[30:33], v[180:183], v[196:199], v[30:33]
	v_mfma_f32_16x16x32_bf16 v[22:25], v[172:175], v[204:207], v[22:25]
	v_mfma_f32_16x16x32_bf16 v[14:17], v[180:183], v[204:207], v[14:17]
	v_mfma_f32_16x16x32_bf16 v[6:9], v[172:175], v[212:215], v[6:9]
	v_mfma_f32_16x16x32_bf16 v[2:5], v[180:183], v[212:215], v[2:5]
	v_mfma_f32_16x16x32_bf16 v[54:57], v[176:179], v[192:195], v[54:57]
	v_mfma_f32_16x16x32_bf16 v[46:49], v[184:187], v[192:195], v[46:49]
	v_mfma_f32_16x16x32_bf16 v[38:41], v[176:179], v[200:203], v[38:41]
	v_mfma_f32_16x16x32_bf16 v[30:33], v[184:187], v[200:203], v[30:33]
	v_mfma_f32_16x16x32_bf16 v[22:25], v[176:179], v[208:211], v[22:25]
	v_mfma_f32_16x16x32_bf16 v[14:17], v[184:187], v[208:211], v[14:17]
	v_mfma_f32_16x16x32_bf16 v[6:9], v[176:179], v[216:219], v[6:9]
	s_barrier
	v_mfma_f32_16x16x32_bf16 v[2:5], v[184:187], v[216:219], v[2:5]
	s_setprio 0
	s_add_i32 s10, 0, 0x18000
	v_add_u32_e32 v167, s10, v141
	s_add_i32 s11, 0, 0x1c000
	ds_read_b128 v[148:151], v167
	ds_read_b128 v[152:155], v167 offset:1024
	ds_read_b128 v[160:163], v167 offset:2048
	ds_read_b128 v[168:171], v167 offset:3072
	v_add_u32_e32 v167, s11, v141
	ds_read_b128 v[172:175], v167
	ds_read_b128 v[176:179], v167 offset:1024
	ds_read_b128 v[180:183], v167 offset:2048
	ds_read_b128 v[184:187], v167 offset:3072
	s_add_u32 s60, s60, 0x80000
	s_addc_u32 s61, s61, 0
	s_mov_b32 m0, s63
	v_lshl_add_u64 v[226:227], s[60:61], 0, v[130:131]
	ds_read_b128 v[188:191], v159 offset:32768
	ds_read_b128 v[192:195], v159 offset:33792
	ds_read_b128 v[196:199], v159 offset:34816
	ds_read_b128 v[200:203], v159 offset:35840
	ds_read_b128 v[204:207], v159 offset:36864
	ds_read_b128 v[208:211], v159 offset:37888
	ds_read_b128 v[212:215], v159 offset:38912
	ds_read_b128 v[216:219], v159 offset:39936
	global_load_lds_dwordx4 v[226:227], off
	v_lshl_add_u64 v[226:227], s[60:61], 0, v[134:135]
	s_mov_b32 m0, s64
	s_nop 0
	global_load_lds_dwordx4 v[226:227], off
	s_waitcnt vmcnt(8)
	s_waitcnt lgkmcnt(0)
	s_barrier
	s_setprio 3
	s_waitcnt lgkmcnt(0)
	v_mfma_f32_16x16x32_bf16 v[126:129], v[148:151], v[188:191], v[126:129]
	v_mfma_f32_16x16x32_bf16 v[122:125], v[160:163], v[188:191], v[122:125]
	v_mfma_f32_16x16x32_bf16 v[114:117], v[148:151], v[196:199], v[114:117]
	v_mfma_f32_16x16x32_bf16 v[106:109], v[160:163], v[196:199], v[106:109]
	v_mfma_f32_16x16x32_bf16 v[98:101], v[148:151], v[204:207], v[98:101]
	v_mfma_f32_16x16x32_bf16 v[90:93], v[160:163], v[204:207], v[90:93]
	v_mfma_f32_16x16x32_bf16 v[82:85], v[148:151], v[212:215], v[82:85]
	v_mfma_f32_16x16x32_bf16 v[74:77], v[160:163], v[212:215], v[74:77]
	v_mfma_f32_16x16x32_bf16 v[126:129], v[152:155], v[192:195], v[126:129]
	v_mfma_f32_16x16x32_bf16 v[122:125], v[168:171], v[192:195], v[122:125]
	v_mfma_f32_16x16x32_bf16 v[114:117], v[152:155], v[200:203], v[114:117]
	v_mfma_f32_16x16x32_bf16 v[106:109], v[168:171], v[200:203], v[106:109]
	v_mfma_f32_16x16x32_bf16 v[98:101], v[152:155], v[208:211], v[98:101]
	v_mfma_f32_16x16x32_bf16 v[90:93], v[168:171], v[208:211], v[90:93]
	v_mfma_f32_16x16x32_bf16 v[82:85], v[152:155], v[216:219], v[82:85]
	v_mfma_f32_16x16x32_bf16 v[74:77], v[168:171], v[216:219], v[74:77]
	s_setprio 0
	s_setprio 3
	v_mfma_f32_16x16x32_bf16 v[118:121], v[172:175], v[188:191], v[118:121]
	v_mfma_f32_16x16x32_bf16 v[110:113], v[180:183], v[188:191], v[110:113]
	v_mfma_f32_16x16x32_bf16 v[102:105], v[172:175], v[196:199], v[102:105]
	v_mfma_f32_16x16x32_bf16 v[94:97], v[180:183], v[196:199], v[94:97]
	v_mfma_f32_16x16x32_bf16 v[86:89], v[172:175], v[204:207], v[86:89]
	v_mfma_f32_16x16x32_bf16 v[78:81], v[180:183], v[204:207], v[78:81]
	v_mfma_f32_16x16x32_bf16 v[70:73], v[172:175], v[212:215], v[70:73]
	v_mfma_f32_16x16x32_bf16 v[66:69], v[180:183], v[212:215], v[66:69]
	v_mfma_f32_16x16x32_bf16 v[118:121], v[176:179], v[192:195], v[118:121]
	v_mfma_f32_16x16x32_bf16 v[110:113], v[184:187], v[192:195], v[110:113]
	v_mfma_f32_16x16x32_bf16 v[102:105], v[176:179], v[200:203], v[102:105]
	v_mfma_f32_16x16x32_bf16 v[94:97], v[184:187], v[200:203], v[94:97]
	v_mfma_f32_16x16x32_bf16 v[86:89], v[176:179], v[208:211], v[86:89]
	v_mfma_f32_16x16x32_bf16 v[78:81], v[184:187], v[208:211], v[78:81]
	v_mfma_f32_16x16x32_bf16 v[70:73], v[176:179], v[216:219], v[70:73]
	s_barrier
; #define PG8_STAGE(bufoff, gbase, voff) do { _Pragma("unroll") for (int _i = 0; _i < 2; ++_i) \
;         __builtin_amdgcn_global_load_lds((const unsigned*)((const char*)(gbase) + (voff)[_i]), (PG8_LAS unsigned*)(lds + (bufoff) + ldsw + _i * 8192), 16, 0, 0); } while (0)
; #define PG8_LDA(dst, b, h) do { _Pragma("unroll") for (int m = 0; m < 4; ++m) _Pragma("unroll") for (int k = 0; k < 2; ++k) dst[m][k] = *(const PG8_LAS bf16x8*)(lds + PG8_SA(b, h) + aoff + m * 2048 + k * 1024); } while (0)
; #define PG8_MMA(ai, bj, At, Bt) do { __builtin_amdgcn_s_setprio(3); _Pragma("unroll") for (int m = 0; m < 4; ++m) _Pragma("unroll") for (int n = 0; n < 2; ++n) _Pragma("unroll") for (int k = 0; k < 2; ++k) \
;         acc[ai][bj][m][n] = __builtin_amdgcn_mfma_f32_16x16x32_bf16(Bt[n][k], At[m][k], acc[ai][bj][m][n], 0, 0, 0); __builtin_amdgcn_s_setprio(0); } while (0)
; #define PG8_WAIT_V(n) asm volatile("s_waitcnt vmcnt(" #n ")" ::: "memory")
; #define PG8_WAIT_L(n) asm volatile("s_waitcnt lgkmcnt(" #n ")" ::: "memory")
; #define PG8_BAR __builtin_amdgcn_s_barrier()
; #define PG8_SCHED __builtin_amdgcn_sched_barrier(0)
; template <class Epi, class Sched, bool ALIGN_EPI = false, bool SP2 = false>
; __device__ __forceinline__ void gemm_phase(PG8_LAS unsigned char* lds, const Gemm g, const Sched& S, const Epi& E) {
;     ...
;             PG8_WAIT_V(8); PG8_WAIT_L(0); PG8_BAR; PG8_MMA(0, 0, At, B0); PG8_MMA(0, 1, At, B1); PG8_BAR; PG8_SCHED;
;             PG8_LDA(At, 1, 1); PG8_STAGE(PG8_SB(1, 0), b3, voffB); PG8_STAGE(PG8_SB(1, 1), b3 + hstep, voffB); PG8_STAGE(PG8_SA(1, 0), a3, voffA);
;             PG8_WAIT_V(8); PG8_WAIT_L(0); PG8_BAR; PG8_MMA(1, 0, At, B0); PG8_MMA(1, 1, At, B1); PG8_BAR; PG8_SCHED;
;     ...
;         if constexpr (ALIGN_EPI) { if (wr == 0) PG8_BAR; }
	v_mfma_f32_16x16x32_bf16 v[66:69], v[184:187], v[216:219], v[66:69]
	s_setprio 0
	s_add_i32 s10, s10, s42
	v_lshl_add_u64 v[164:165], v[164:165], 0, s[24:25]
	s_mov_b32 m0, s10
	ds_read_b128 v[188:191], v159 offset:49152
	ds_read_b128 v[192:195], v159 offset:50176
	ds_read_b128 v[196:199], v159 offset:51200
	ds_read_b128 v[200:203], v159 offset:52224
	ds_read_b128 v[204:207], v159 offset:53248
	ds_read_b128 v[208:211], v159 offset:54272
	ds_read_b128 v[212:215], v159 offset:55296
	ds_read_b128 v[216:219], v159 offset:56320
	global_load_lds_dwordx4 v[164:165], off
	s_add_i32 m0, s10, 0x2000
	s_add_u32 s58, s58, 0x80080
	v_lshl_add_u64 v[164:165], v[220:221], 0, s[24:25]
	s_addc_u32 s59, s59, 0
	s_add_i32 s10, s11, s42
	global_load_lds_dwordx4 v[164:165], off
	v_lshl_add_u64 v[164:165], s[58:59], 0, v[132:133]
	s_mov_b32 m0, s10
	s_nop 0
	global_load_lds_dwordx4 v[164:165], off
	v_lshl_add_u64 v[164:165], s[58:59], 0, v[136:137]
	s_add_i32 m0, s10, 0x2000
	s_nop 0
	global_load_lds_dwordx4 v[164:165], off
	v_lshl_add_u64 v[164:165], v[222:223], 0, s[24:25]
	s_mov_b32 m0, s69
	s_nop 0
	global_load_lds_dwordx4 v[164:165], off
	v_lshl_add_u64 v[164:165], v[224:225], 0, s[24:25]
	s_mov_b32 m0, s70
	s_nop 0
	global_load_lds_dwordx4 v[164:165], off
	s_waitcnt vmcnt(8)
	s_waitcnt lgkmcnt(0)
	s_barrier
	s_setprio 3
	s_waitcnt lgkmcnt(0)
	v_mfma_f32_16x16x32_bf16 v[62:65], v[148:151], v[188:191], v[62:65]
	v_mfma_f32_16x16x32_bf16 v[58:61], v[160:163], v[188:191], v[58:61]
	v_mfma_f32_16x16x32_bf16 v[50:53], v[148:151], v[196:199], v[50:53]
	v_mfma_f32_16x16x32_bf16 v[42:45], v[160:163], v[196:199], v[42:45]
	v_mfma_f32_16x16x32_bf16 v[34:37], v[148:151], v[204:207], v[34:37]
	v_mfma_f32_16x16x32_bf16 v[26:29], v[160:163], v[204:207], v[26:29]
	v_mfma_f32_16x16x32_bf16 v[18:21], v[148:151], v[212:215], v[18:21]
	v_mfma_f32_16x16x32_bf16 v[10:13], v[160:163], v[212:215], v[10:13]
	v_mfma_f32_16x16x32_bf16 v[62:65], v[152:155], v[192:195], v[62:65]
	v_mfma_f32_16x16x32_bf16 v[58:61], v[168:171], v[192:195], v[58:61]
	v_mfma_f32_16x16x32_bf16 v[50:53], v[152:155], v[200:203], v[50:53]
	v_mfma_f32_16x16x32_bf16 v[42:45], v[168:171], v[200:203], v[42:45]
	v_mfma_f32_16x16x32_bf16 v[34:37], v[152:155], v[208:211], v[34:37]
	v_mfma_f32_16x16x32_bf16 v[26:29], v[168:171], v[208:211], v[26:29]
	v_mfma_f32_16x16x32_bf16 v[18:21], v[152:155], v[216:219], v[18:21]
	v_mfma_f32_16x16x32_bf16 v[10:13], v[168:171], v[216:219], v[10:13]
	s_setprio 0
	s_setprio 3
	v_mfma_f32_16x16x32_bf16 v[54:57], v[172:175], v[188:191], v[54:57]
	v_mfma_f32_16x16x32_bf16 v[46:49], v[180:183], v[188:191], v[46:49]
	v_mfma_f32_16x16x32_bf16 v[38:41], v[172:175], v[196:199], v[38:41]
	v_mfma_f32_16x16x32_bf16 v[30:33], v[180:183], v[196:199], v[30:33]
	v_mfma_f32_16x16x32_bf16 v[22:25], v[172:175], v[204:207], v[22:25]
	v_mfma_f32_16x16x32_bf16 v[14:17], v[180:183], v[204:207], v[14:17]
	v_mfma_f32_16x16x32_bf16 v[6:9], v[172:175], v[212:215], v[6:9]
	v_mfma_f32_16x16x32_bf16 v[2:5], v[180:183], v[212:215], v[2:5]
	v_mfma_f32_16x16x32_bf16 v[54:57], v[176:179], v[192:195], v[54:57]
	v_mfma_f32_16x16x32_bf16 v[46:49], v[184:187], v[192:195], v[46:49]
	v_mfma_f32_16x16x32_bf16 v[38:41], v[176:179], v[200:203], v[38:41]
	v_mfma_f32_16x16x32_bf16 v[30:33], v[184:187], v[200:203], v[30:33]
	v_mfma_f32_16x16x32_bf16 v[22:25], v[176:179], v[208:211], v[22:25]
	v_mfma_f32_16x16x32_bf16 v[14:17], v[184:187], v[208:211], v[14:17]
	v_mfma_f32_16x16x32_bf16 v[6:9], v[176:179], v[216:219], v[6:9]
	s_barrier
	v_mfma_f32_16x16x32_bf16 v[2:5], v[184:187], v[216:219], v[2:5]
	s_setprio 0
	s_add_u32 s56, s56, 0x100
	s_addc_u32 s57, s57, 0
	s_add_u32 s47, s47, 0x100
	s_addc_u32 s51, s51, 0
	s_cmp_ge_u32 s79, s78
	s_mov_b32 s55, s79
	s_cbranch_scc0 .LBB0_1013
	s_and_b64 vcc, exec, s[26:27]
	s_cbranch_vccz .LBB0_1016
	s_barrier

; #define PG8_STAGE(bufoff, gbase, voff) do { _Pragma("unroll") for (int _i = 0; _i < 2; ++_i) \
;         __builtin_amdgcn_global_load_lds((const unsigned*)((const char*)(gbase) + (voff)[_i]), (PG8_LAS unsigned*)(lds + (bufoff) + ldsw + _i * 8192), 16, 0, 0); } while (0)
; #define PG8_LDA(dst, b, h) do { _Pragma("unroll") for (int m = 0; m < 4; ++m) _Pragma("unroll") for (int k = 0; k < 2; ++k) dst[m][k] = *(const PG8_LAS bf16x8*)(lds + PG8_SA(b, h) + aoff + m * 2048 + k * 1024); } while (0)
; #define PG8_LDB(dst, b, h) do { _Pragma("unroll") for (int n = 0; n < 2; ++n) _Pragma("unroll") for (int k = 0; k < 2; ++k) dst[n][k] = *(const PG8_LAS bf16x8*)(lds + PG8_SB(b, h) + boff + n * 2048 + k * 1024); } while (0)
; #define PG8_MMA(ai, bj, At, Bt) do { __builtin_amdgcn_s_setprio(3); _Pragma("unroll") for (int m = 0; m < 4; ++m) _Pragma("unroll") for (int n = 0; n < 2; ++n) _Pragma("unroll") for (int k = 0; k < 2; ++k) \
;         acc[ai][bj][m][n] = __builtin_amdgcn_mfma_f32_16x16x32_bf16(Bt[n][k], At[m][k], acc[ai][bj][m][n], 0, 0, 0); __builtin_amdgcn_s_setprio(0); } while (0)
; #define PG8_WAIT_V(n) asm volatile("s_waitcnt vmcnt(" #n ")" ::: "memory")
; #define PG8_BAR __builtin_amdgcn_s_barrier()
; template <class Epi, class Sched, bool ALIGN_EPI = false, bool SP2 = false>
; __device__ __forceinline__ void gemm_phase(PG8_LAS unsigned char* lds, const Gemm g, const Sched& S, const Epi& E) {
;     ...
;         for (int t = 0; t < nt; t += 2) {
;             const bool last = (t == nt - 2);
;             const char* a1 = cA + (size_t)(t + 1) * kstep;
;             const char* a2 = last ? nA : cA + (size_t)(t + 2) * kstep; const char* b2 = last ? nB : cB + (size_t)(t + 2) * kstep;
;             const char* a3 = a2 + kstep; const char* b3 = b2 + kstep;
;             if (last && has_next) S.a_ready(nxt);
;             if constexpr (SP2) {
;             PG8_LDB(B0, 0, 0); PG8_LDB(B1, 0, 1); PG8_SCHED; PG8_LDA(At, 0, 0); PG8_STAGE(PG8_SA(1, 1), a1 + hstep, voffA);
;             PG8_WAIT_V(8); PG8_WAIT_L(0); PG8_BAR; PG8_MMA(0, 0, At, B0); PG8_MMA(0, 1, At, B1); PG8_BAR; PG8_SCHED;
;             PG8_LDA(At, 0, 1); PG8_STAGE(PG8_SB(0, 0), b2, voffB); PG8_STAGE(PG8_SB(0, 1), b2 + hstep, voffB); PG8_STAGE(PG8_SA(0, 0), a2, voffA);
;             PG8_WAIT_V(8); PG8_WAIT_L(0); PG8_BAR; PG8_MMA(1, 0, At, B0); PG8_MMA(1, 1, At, B1); PG8_BAR; PG8_SCHED;
.LBB0_1218:
	ds_read_b128 v[148:151], v153
	ds_read_b128 v[156:159], v153 offset:1024
	ds_read_b128 v[160:163], v153 offset:2048
	ds_read_b128 v[168:171], v153 offset:3072
	ds_read_b128 v[172:175], v154
	ds_read_b128 v[176:179], v154 offset:1024
	ds_read_b128 v[180:183], v154 offset:2048
	ds_read_b128 v[184:187], v154 offset:3072
	s_add_u32 s10, s46, 0xfff80080
	s_addc_u32 s11, s47, -1
	s_cmp_eq_u32 s66, 28
	s_cselect_b32 s51, s27, s11
	s_cselect_b32 s50, s62, s10
	s_cselect_b32 s49, s25, s65
	s_cselect_b32 s48, s63, s64
	v_lshl_add_u64 v[164:165], s[46:47], 0, v[138:139]
	s_add_i32 m0, s42, 0xc000
	ds_read_b128 v[188:191], v155
	ds_read_b128 v[192:195], v155 offset:1024
	ds_read_b128 v[196:199], v155 offset:2048
	ds_read_b128 v[200:203], v155 offset:3072
	ds_read_b128 v[204:207], v155 offset:4096
	ds_read_b128 v[208:211], v155 offset:5120
	ds_read_b128 v[212:215], v155 offset:6144
	ds_read_b128 v[216:219], v155 offset:7168
	global_load_lds_dwordx4 v[164:165], off
	v_lshl_add_u64 v[164:165], s[46:47], 0, v[142:143]
	s_add_i32 m0, s42, 0xe000
	s_nop 0
	global_load_lds_dwordx4 v[164:165], off
	s_waitcnt vmcnt(8)
	s_waitcnt lgkmcnt(0)
	s_barrier
	s_setprio 3
	s_waitcnt lgkmcnt(0)
	v_mfma_f32_16x16x32_bf16 v[126:129], v[148:151], v[188:191], v[126:129]
	v_mfma_f32_16x16x32_bf16 v[118:121], v[160:163], v[188:191], v[118:121]
	v_mfma_f32_16x16x32_bf16 v[110:113], v[148:151], v[196:199], v[110:113]
	v_mfma_f32_16x16x32_bf16 v[102:105], v[160:163], v[196:199], v[102:105]
	v_mfma_f32_16x16x32_bf16 v[94:97], v[148:151], v[204:207], v[94:97]
	v_mfma_f32_16x16x32_bf16 v[86:89], v[160:163], v[204:207], v[86:89]
	v_mfma_f32_16x16x32_bf16 v[78:81], v[148:151], v[212:215], v[78:81]
	v_mfma_f32_16x16x32_bf16 v[70:73], v[160:163], v[212:215], v[70:73]
	v_mfma_f32_16x16x32_bf16 v[126:129], v[156:159], v[192:195], v[126:129]
	v_mfma_f32_16x16x32_bf16 v[118:121], v[168:171], v[192:195], v[118:121]
	v_mfma_f32_16x16x32_bf16 v[110:113], v[156:159], v[200:203], v[110:113]
	v_mfma_f32_16x16x32_bf16 v[102:105], v[168:171], v[200:203], v[102:105]
	v_mfma_f32_16x16x32_bf16 v[94:97], v[156:159], v[208:211], v[94:97]
	v_mfma_f32_16x16x32_bf16 v[86:89], v[168:171], v[208:211], v[86:89]
	v_mfma_f32_16x16x32_bf16 v[78:81], v[156:159], v[216:219], v[78:81]
	v_mfma_f32_16x16x32_bf16 v[70:73], v[168:171], v[216:219], v[70:73]
	s_setprio 0
	s_setprio 3
	v_mfma_f32_16x16x32_bf16 v[122:125], v[172:175], v[188:191], v[122:125]
	v_mfma_f32_16x16x32_bf16 v[114:117], v[180:183], v[188:191], v[114:117]
	v_mfma_f32_16x16x32_bf16 v[106:109], v[172:175], v[196:199], v[106:109]
	v_mfma_f32_16x16x32_bf16 v[98:101], v[180:183], v[196:199], v[98:101]
	v_mfma_f32_16x16x32_bf16 v[90:93], v[172:175], v[204:207], v[90:93]
	v_mfma_f32_16x16x32_bf16 v[82:85], v[180:183], v[204:207], v[82:85]
	v_mfma_f32_16x16x32_bf16 v[74:77], v[172:175], v[212:215], v[74:77]
	v_mfma_f32_16x16x32_bf16 v[66:69], v[180:183], v[212:215], v[66:69]
	v_mfma_f32_16x16x32_bf16 v[122:125], v[176:179], v[192:195], v[122:125]
	v_mfma_f32_16x16x32_bf16 v[114:117], v[184:187], v[192:195], v[114:117]
	v_mfma_f32_16x16x32_bf16 v[106:109], v[176:179], v[200:203], v[106:109]
	v_mfma_f32_16x16x32_bf16 v[98:101], v[184:187], v[200:203], v[98:101]
	v_mfma_f32_16x16x32_bf16 v[90:93], v[176:179], v[208:211], v[90:93]
	v_mfma_f32_16x16x32_bf16 v[82:85], v[184:187], v[208:211], v[82:85]
	v_mfma_f32_16x16x32_bf16 v[74:77], v[176:179], v[216:219], v[74:77]
	s_barrier
	v_mfma_f32_16x16x32_bf16 v[66:69], v[184:187], v[216:219], v[66:69]
	s_setprio 0
	s_add_i32 s10, s58, s35
	v_lshl_add_u64 v[164:165], s[48:49], 0, v[132:133]
	s_mov_b32 m0, s10
	ds_read_b128 v[188:191], v155 offset:16384
	ds_read_b128 v[192:195], v155 offset:17408
	ds_read_b128 v[196:199], v155 offset:18432
	ds_read_b128 v[200:203], v155 offset:19456
	ds_read_b128 v[204:207], v155 offset:20480
	ds_read_b128 v[208:211], v155 offset:21504
	ds_read_b128 v[212:215], v155 offset:22528
	ds_read_b128 v[216:219], v155 offset:23552
	global_load_lds_dwordx4 v[164:165], off
	s_add_i32 m0, s10, 0x2000
	s_add_u32 s68, s48, 0x80000
	v_lshl_add_u64 v[220:221], s[48:49], 0, v[136:137]
	s_addc_u32 s69, s49, 0
	s_add_i32 s10, s59, s35
	global_load_lds_dwordx4 v[220:221], off
	v_lshl_add_u64 v[222:223], s[68:69], 0, v[132:133]
	s_mov_b32 m0, s10
	v_lshl_add_u64 v[224:225], s[50:51], 0, v[134:135]
	global_load_lds_dwordx4 v[222:223], off
	v_lshl_add_u64 v[222:223], s[68:69], 0, v[136:137]
	s_add_i32 m0, s10, 0x2000
	s_nop 0
	global_load_lds_dwordx4 v[222:223], off
	v_lshl_add_u64 v[222:223], s[50:51], 0, v[130:131]
	s_mov_b32 m0, s42
	s_nop 0
	global_load_lds_dwordx4 v[222:223], off
	s_mov_b32 m0, s43
	s_nop 0
	global_load_lds_dwordx4 v[224:225], off
	s_waitcnt vmcnt(8)
	s_waitcnt lgkmcnt(0)
	s_barrier
; #define PG8_STAGE(bufoff, gbase, voff) do { _Pragma("unroll") for (int _i = 0; _i < 2; ++_i) \
;         __builtin_amdgcn_global_load_lds((const unsigned*)((const char*)(gbase) + (voff)[_i]), (PG8_LAS unsigned*)(lds + (bufoff) + ldsw + _i * 8192), 16, 0, 0); } while (0)
; #define PG8_LDA(dst, b, h) do { _Pragma("unroll") for (int m = 0; m < 4; ++m) _Pragma("unroll") for (int k = 0; k < 2; ++k) dst[m][k] = *(const PG8_LAS bf16x8*)(lds + PG8_SA(b, h) + aoff + m * 2048 + k * 1024); } while (0)
; #define PG8_LDB(dst, b, h) do { _Pragma("unroll") for (int n = 0; n < 2; ++n) _Pragma("unroll") for (int k = 0; k < 2; ++k) dst[n][k] = *(const PG8_LAS bf16x8*)(lds + PG8_SB(b, h) + boff + n * 2048 + k * 1024); } while (0)
; #define PG8_MMA(ai, bj, At, Bt) do { __builtin_amdgcn_s_setprio(3); _Pragma("unroll") for (int m = 0; m < 4; ++m) _Pragma("unroll") for (int n = 0; n < 2; ++n) _Pragma("unroll") for (int k = 0; k < 2; ++k) \
;         acc[ai][bj][m][n] = __builtin_amdgcn_mfma_f32_16x16x32_bf16(Bt[n][k], At[m][k], acc[ai][bj][m][n], 0, 0, 0); __builtin_amdgcn_s_setprio(0); } while (0)
; #define PG8_WAIT_V(n) asm volatile("s_waitcnt vmcnt(" #n ")" ::: "memory")
; #define PG8_WAIT_L(n) asm volatile("s_waitcnt lgkmcnt(" #n ")" ::: "memory")
; #define PG8_BAR __builtin_amdgcn_s_barrier()
; #define PG8_SCHED __builtin_amdgcn_sched_barrier(0)
; template <class Epi, class Sched, bool ALIGN_EPI = false, bool SP2 = false>
; __device__ __forceinline__ void gemm_phase(PG8_LAS unsigned char* lds, const Gemm g, const Sched& S, const Epi& E) {
;     ...
;             PG8_WAIT_V(8); PG8_WAIT_L(0); PG8_BAR; PG8_MMA(1, 0, At, B0); PG8_MMA(1, 1, At, B1); PG8_BAR; PG8_SCHED;
;             PG8_LDB(B0, 1, 0); PG8_LDB(B1, 1, 1); PG8_SCHED; PG8_LDA(At, 1, 0); PG8_STAGE(PG8_SA(0, 1), a2 + hstep, voffA);
;             PG8_WAIT_V(8); PG8_WAIT_L(0); PG8_BAR; PG8_MMA(0, 0, At, B0); PG8_MMA(0, 1, At, B1); PG8_BAR; PG8_SCHED;
	s_setprio 3
	s_waitcnt lgkmcnt(0)
	v_mfma_f32_16x16x32_bf16 v[62:65], v[148:151], v[188:191], v[62:65]
	v_mfma_f32_16x16x32_bf16 v[54:57], v[160:163], v[188:191], v[54:57]
	v_mfma_f32_16x16x32_bf16 v[46:49], v[148:151], v[196:199], v[46:49]
	v_mfma_f32_16x16x32_bf16 v[38:41], v[160:163], v[196:199], v[38:41]
	v_mfma_f32_16x16x32_bf16 v[30:33], v[148:151], v[204:207], v[30:33]
	v_mfma_f32_16x16x32_bf16 v[22:25], v[160:163], v[204:207], v[22:25]
	v_mfma_f32_16x16x32_bf16 v[14:17], v[148:151], v[212:215], v[14:17]
	v_mfma_f32_16x16x32_bf16 v[6:9], v[160:163], v[212:215], v[6:9]
	v_mfma_f32_16x16x32_bf16 v[62:65], v[156:159], v[192:195], v[62:65]
	v_mfma_f32_16x16x32_bf16 v[54:57], v[168:171], v[192:195], v[54:57]
	v_mfma_f32_16x16x32_bf16 v[46:49], v[156:159], v[200:203], v[46:49]
	v_mfma_f32_16x16x32_bf16 v[38:41], v[168:171], v[200:203], v[38:41]
	v_mfma_f32_16x16x32_bf16 v[30:33], v[156:159], v[208:211], v[30:33]
	v_mfma_f32_16x16x32_bf16 v[22:25], v[168:171], v[208:211], v[22:25]
	v_mfma_f32_16x16x32_bf16 v[14:17], v[156:159], v[216:219], v[14:17]
	v_mfma_f32_16x16x32_bf16 v[6:9], v[168:171], v[216:219], v[6:9]
	s_setprio 0
	s_setprio 3
	v_mfma_f32_16x16x32_bf16 v[58:61], v[172:175], v[188:191], v[58:61]
	v_mfma_f32_16x16x32_bf16 v[50:53], v[180:183], v[188:191], v[50:53]
	v_mfma_f32_16x16x32_bf16 v[42:45], v[172:175], v[196:199], v[42:45]
	v_mfma_f32_16x16x32_bf16 v[34:37], v[180:183], v[196:199], v[34:37]
	v_mfma_f32_16x16x32_bf16 v[26:29], v[172:175], v[204:207], v[26:29]
	v_mfma_f32_16x16x32_bf16 v[18:21], v[180:183], v[204:207], v[18:21]
	v_mfma_f32_16x16x32_bf16 v[10:13], v[172:175], v[212:215], v[10:13]
	v_mfma_f32_16x16x32_bf16 v[2:5], v[180:183], v[212:215], v[2:5]
	v_mfma_f32_16x16x32_bf16 v[58:61], v[176:179], v[192:195], v[58:61]
	v_mfma_f32_16x16x32_bf16 v[50:53], v[184:187], v[192:195], v[50:53]
	v_mfma_f32_16x16x32_bf16 v[42:45], v[176:179], v[200:203], v[42:45]
	v_mfma_f32_16x16x32_bf16 v[34:37], v[184:187], v[200:203], v[34:37]
	v_mfma_f32_16x16x32_bf16 v[26:29], v[176:179], v[208:211], v[26:29]
	v_mfma_f32_16x16x32_bf16 v[18:21], v[184:187], v[208:211], v[18:21]
	v_mfma_f32_16x16x32_bf16 v[10:13], v[176:179], v[216:219], v[10:13]
	s_barrier
	v_mfma_f32_16x16x32_bf16 v[2:5], v[184:187], v[216:219], v[2:5]
	s_setprio 0
	s_add_i32 s10, 0, 0x18000
	v_add_u32_e32 v167, s10, v141
	s_add_i32 s11, 0, 0x1c000
	ds_read_b128 v[148:151], v167
	ds_read_b128 v[156:159], v167 offset:1024
	ds_read_b128 v[160:163], v167 offset:2048
	ds_read_b128 v[168:171], v167 offset:3072
	v_add_u32_e32 v167, s11, v141
	ds_read_b128 v[172:175], v167
	ds_read_b128 v[176:179], v167 offset:1024
	ds_read_b128 v[180:183], v167 offset:2048
	ds_read_b128 v[184:187], v167 offset:3072
	s_add_u32 s50, s50, 0x80000
	s_addc_u32 s51, s51, 0
	s_mov_b32 m0, s45
	v_lshl_add_u64 v[226:227], s[50:51], 0, v[130:131]
	ds_read_b128 v[188:191], v155 offset:32768
	ds_read_b128 v[192:195], v155 offset:33792
	ds_read_b128 v[196:199], v155 offset:34816
	ds_read_b128 v[200:203], v155 offset:35840
	ds_read_b128 v[204:207], v155 offset:36864
	ds_read_b128 v[208:211], v155 offset:37888
	ds_read_b128 v[212:215], v155 offset:38912
	ds_read_b128 v[216:219], v155 offset:39936
	global_load_lds_dwordx4 v[226:227], off
	v_lshl_add_u64 v[226:227], s[50:51], 0, v[134:135]
	s_mov_b32 m0, s52
	s_nop 0
	global_load_lds_dwordx4 v[226:227], off
	s_waitcnt vmcnt(8)
	s_waitcnt lgkmcnt(0)
	s_barrier
	s_setprio 3
	s_waitcnt lgkmcnt(0)
	v_mfma_f32_16x16x32_bf16 v[126:129], v[148:151], v[188:191], v[126:129]
	v_mfma_f32_16x16x32_bf16 v[118:121], v[160:163], v[188:191], v[118:121]
	v_mfma_f32_16x16x32_bf16 v[110:113], v[148:151], v[196:199], v[110:113]
	v_mfma_f32_16x16x32_bf16 v[102:105], v[160:163], v[196:199], v[102:105]
	v_mfma_f32_16x16x32_bf16 v[94:97], v[148:151], v[204:207], v[94:97]
	v_mfma_f32_16x16x32_bf16 v[86:89], v[160:163], v[204:207], v[86:89]
	v_mfma_f32_16x16x32_bf16 v[78:81], v[148:151], v[212:215], v[78:81]
	v_mfma_f32_16x16x32_bf16 v[70:73], v[160:163], v[212:215], v[70:73]
	v_mfma_f32_16x16x32_bf16 v[126:129], v[156:159], v[192:195], v[126:129]
	v_mfma_f32_16x16x32_bf16 v[118:121], v[168:171], v[192:195], v[118:121]
	v_mfma_f32_16x16x32_bf16 v[110:113], v[156:159], v[200:203], v[110:113]
	v_mfma_f32_16x16x32_bf16 v[102:105], v[168:171], v[200:203], v[102:105]
	v_mfma_f32_16x16x32_bf16 v[94:97], v[156:159], v[208:211], v[94:97]
	v_mfma_f32_16x16x32_bf16 v[86:89], v[168:171], v[208:211], v[86:89]
	v_mfma_f32_16x16x32_bf16 v[78:81], v[156:159], v[216:219], v[78:81]
	v_mfma_f32_16x16x32_bf16 v[70:73], v[168:171], v[216:219], v[70:73]
	s_setprio 0
	s_setprio 3
	v_mfma_f32_16x16x32_bf16 v[122:125], v[172:175], v[188:191], v[122:125]
	v_mfma_f32_16x16x32_bf16 v[114:117], v[180:183], v[188:191], v[114:117]
	v_mfma_f32_16x16x32_bf16 v[106:109], v[172:175], v[196:199], v[106:109]
	v_mfma_f32_16x16x32_bf16 v[98:101], v[180:183], v[196:199], v[98:101]
	v_mfma_f32_16x16x32_bf16 v[90:93], v[172:175], v[204:207], v[90:93]
	v_mfma_f32_16x16x32_bf16 v[82:85], v[180:183], v[204:207], v[82:85]
	v_mfma_f32_16x16x32_bf16 v[74:77], v[172:175], v[212:215], v[74:77]
	v_mfma_f32_16x16x32_bf16 v[66:69], v[180:183], v[212:215], v[66:69]
	v_mfma_f32_16x16x32_bf16 v[122:125], v[176:179], v[192:195], v[122:125]
	v_mfma_f32_16x16x32_bf16 v[114:117], v[184:187], v[192:195], v[114:117]
	v_mfma_f32_16x16x32_bf16 v[106:109], v[176:179], v[200:203], v[106:109]
	v_mfma_f32_16x16x32_bf16 v[98:101], v[184:187], v[200:203], v[98:101]
	v_mfma_f32_16x16x32_bf16 v[90:93], v[176:179], v[208:211], v[90:93]
	v_mfma_f32_16x16x32_bf16 v[82:85], v[184:187], v[208:211], v[82:85]
	v_mfma_f32_16x16x32_bf16 v[74:77], v[176:179], v[216:219], v[74:77]
	s_barrier
; #define PG8_STAGE(bufoff, gbase, voff) do { _Pragma("unroll") for (int _i = 0; _i < 2; ++_i) \
;         __builtin_amdgcn_global_load_lds((const unsigned*)((const char*)(gbase) + (voff)[_i]), (PG8_LAS unsigned*)(lds + (bufoff) + ldsw + _i * 8192), 16, 0, 0); } while (0)
; #define PG8_LDA(dst, b, h) do { _Pragma("unroll") for (int m = 0; m < 4; ++m) _Pragma("unroll") for (int k = 0; k < 2; ++k) dst[m][k] = *(const PG8_LAS bf16x8*)(lds + PG8_SA(b, h) + aoff + m * 2048 + k * 1024); } while (0)
; #define PG8_MMA(ai, bj, At, Bt) do { __builtin_amdgcn_s_setprio(3); _Pragma("unroll") for (int m = 0; m < 4; ++m) _Pragma("unroll") for (int n = 0; n < 2; ++n) _Pragma("unroll") for (int k = 0; k < 2; ++k) \
;         acc[ai][bj][m][n] = __builtin_amdgcn_mfma_f32_16x16x32_bf16(Bt[n][k], At[m][k], acc[ai][bj][m][n], 0, 0, 0); __builtin_amdgcn_s_setprio(0); } while (0)
; #define PG8_WAIT_V(n) asm volatile("s_waitcnt vmcnt(" #n ")" ::: "memory")
; #define PG8_WAIT_L(n) asm volatile("s_waitcnt lgkmcnt(" #n ")" ::: "memory")
; #define PG8_BAR __builtin_amdgcn_s_barrier()
; #define PG8_SCHED __builtin_amdgcn_sched_barrier(0)
; template <class Epi, class Sched, bool ALIGN_EPI = false, bool SP2 = false>
; __device__ __forceinline__ void gemm_phase(PG8_LAS unsigned char* lds, const Gemm g, const Sched& S, const Epi& E) {
;     ...
;             PG8_WAIT_V(8); PG8_WAIT_L(0); PG8_BAR; PG8_MMA(0, 0, At, B0); PG8_MMA(0, 1, At, B1); PG8_BAR; PG8_SCHED;
;             PG8_LDA(At, 1, 1); PG8_STAGE(PG8_SB(1, 0), b3, voffB); PG8_STAGE(PG8_SB(1, 1), b3 + hstep, voffB); PG8_STAGE(PG8_SA(1, 0), a3, voffA);
;             PG8_WAIT_V(8); PG8_WAIT_L(0); PG8_BAR; PG8_MMA(1, 0, At, B0); PG8_MMA(1, 1, At, B1); PG8_BAR; PG8_SCHED;
;     ...
;         if constexpr (ALIGN_EPI) { if (wr == 0) PG8_BAR; }
	v_mfma_f32_16x16x32_bf16 v[66:69], v[184:187], v[216:219], v[66:69]
	s_setprio 0
	s_add_i32 s10, s10, s35
	v_lshl_add_u64 v[164:165], v[164:165], 0, s[16:17]
	s_mov_b32 m0, s10
	ds_read_b128 v[188:191], v155 offset:49152
	ds_read_b128 v[192:195], v155 offset:50176
	ds_read_b128 v[196:199], v155 offset:51200
	ds_read_b128 v[200:203], v155 offset:52224
	ds_read_b128 v[204:207], v155 offset:53248
	ds_read_b128 v[208:211], v155 offset:54272
	ds_read_b128 v[212:215], v155 offset:55296
	ds_read_b128 v[216:219], v155 offset:56320
	global_load_lds_dwordx4 v[164:165], off
	s_add_i32 m0, s10, 0x2000
	s_add_u32 s48, s48, 0x80080
	v_lshl_add_u64 v[164:165], v[220:221], 0, s[16:17]
	s_addc_u32 s49, s49, 0
	s_add_i32 s10, s11, s35
	global_load_lds_dwordx4 v[164:165], off
	v_lshl_add_u64 v[164:165], s[48:49], 0, v[132:133]
	s_mov_b32 m0, s10
	s_nop 0
	global_load_lds_dwordx4 v[164:165], off
	v_lshl_add_u64 v[164:165], s[48:49], 0, v[136:137]
	s_add_i32 m0, s10, 0x2000
	s_nop 0
	global_load_lds_dwordx4 v[164:165], off
	v_lshl_add_u64 v[164:165], v[222:223], 0, s[16:17]
	s_mov_b32 m0, s55
	s_nop 0
	global_load_lds_dwordx4 v[164:165], off
	v_lshl_add_u64 v[164:165], v[224:225], 0, s[16:17]
	s_mov_b32 m0, s56
	s_nop 0
	global_load_lds_dwordx4 v[164:165], off
	s_waitcnt vmcnt(8)
	s_waitcnt lgkmcnt(0)
	s_barrier
	s_setprio 3
	s_waitcnt lgkmcnt(0)
	v_mfma_f32_16x16x32_bf16 v[62:65], v[148:151], v[188:191], v[62:65]
	v_mfma_f32_16x16x32_bf16 v[54:57], v[160:163], v[188:191], v[54:57]
	v_mfma_f32_16x16x32_bf16 v[46:49], v[148:151], v[196:199], v[46:49]
	v_mfma_f32_16x16x32_bf16 v[38:41], v[160:163], v[196:199], v[38:41]
	v_mfma_f32_16x16x32_bf16 v[30:33], v[148:151], v[204:207], v[30:33]
	v_mfma_f32_16x16x32_bf16 v[22:25], v[160:163], v[204:207], v[22:25]
	v_mfma_f32_16x16x32_bf16 v[14:17], v[148:151], v[212:215], v[14:17]
	v_mfma_f32_16x16x32_bf16 v[6:9], v[160:163], v[212:215], v[6:9]
	v_mfma_f32_16x16x32_bf16 v[62:65], v[156:159], v[192:195], v[62:65]
	v_mfma_f32_16x16x32_bf16 v[54:57], v[168:171], v[192:195], v[54:57]
	v_mfma_f32_16x16x32_bf16 v[46:49], v[156:159], v[200:203], v[46:49]
	v_mfma_f32_16x16x32_bf16 v[38:41], v[168:171], v[200:203], v[38:41]
	v_mfma_f32_16x16x32_bf16 v[30:33], v[156:159], v[208:211], v[30:33]
	v_mfma_f32_16x16x32_bf16 v[22:25], v[168:171], v[208:211], v[22:25]
	v_mfma_f32_16x16x32_bf16 v[14:17], v[156:159], v[216:219], v[14:17]
	v_mfma_f32_16x16x32_bf16 v[6:9], v[168:171], v[216:219], v[6:9]
	s_setprio 0
	s_setprio 3
	v_mfma_f32_16x16x32_bf16 v[58:61], v[172:175], v[188:191], v[58:61]
	v_mfma_f32_16x16x32_bf16 v[50:53], v[180:183], v[188:191], v[50:53]
	v_mfma_f32_16x16x32_bf16 v[42:45], v[172:175], v[196:199], v[42:45]
	v_mfma_f32_16x16x32_bf16 v[34:37], v[180:183], v[196:199], v[34:37]
	v_mfma_f32_16x16x32_bf16 v[26:29], v[172:175], v[204:207], v[26:29]
	v_mfma_f32_16x16x32_bf16 v[18:21], v[180:183], v[204:207], v[18:21]
	v_mfma_f32_16x16x32_bf16 v[10:13], v[172:175], v[212:215], v[10:13]
	v_mfma_f32_16x16x32_bf16 v[2:5], v[180:183], v[212:215], v[2:5]
	v_mfma_f32_16x16x32_bf16 v[58:61], v[176:179], v[192:195], v[58:61]
	v_mfma_f32_16x16x32_bf16 v[50:53], v[184:187], v[192:195], v[50:53]
	v_mfma_f32_16x16x32_bf16 v[42:45], v[176:179], v[200:203], v[42:45]
	v_mfma_f32_16x16x32_bf16 v[34:37], v[184:187], v[200:203], v[34:37]
	v_mfma_f32_16x16x32_bf16 v[26:29], v[176:179], v[208:211], v[26:29]
	v_mfma_f32_16x16x32_bf16 v[18:21], v[184:187], v[208:211], v[18:21]
	v_mfma_f32_16x16x32_bf16 v[10:13], v[176:179], v[216:219], v[10:13]
	s_barrier
	v_mfma_f32_16x16x32_bf16 v[2:5], v[184:187], v[216:219], v[2:5]
	s_setprio 0
	s_add_i32 s66, s66, 2
	s_add_u32 s46, s46, 0x100
	s_addc_u32 s47, s47, 0
	s_add_u32 s64, s64, 0x100
	s_addc_u32 s65, s65, 0
	s_cmp_gt_u32 s66, 29
	s_cbranch_scc0 .LBB0_1218
	s_and_b64 vcc, exec, s[18:19]
	s_cbranch_vccz .LBB0_1221
	s_barrier

; #define PG8_STAGE(bufoff, gbase, voff) do { _Pragma("unroll") for (int _i = 0; _i < 2; ++_i) \
;         __builtin_amdgcn_global_load_lds((const unsigned*)((const char*)(gbase) + (voff)[_i]), (PG8_LAS unsigned*)(lds + (bufoff) + ldsw + _i * 8192), 16, 0, 0); } while (0)
; #define PG8_LDA(dst, b, h) do { _Pragma("unroll") for (int m = 0; m < 4; ++m) _Pragma("unroll") for (int k = 0; k < 2; ++k) dst[m][k] = *(const PG8_LAS bf16x8*)(lds + PG8_SA(b, h) + aoff + m * 2048 + k * 1024); } while (0)
; #define PG8_LDB(dst, b, h) do { _Pragma("unroll") for (int n = 0; n < 2; ++n) _Pragma("unroll") for (int k = 0; k < 2; ++k) dst[n][k] = *(const PG8_LAS bf16x8*)(lds + PG8_SB(b, h) + boff + n * 2048 + k * 1024); } while (0)
; #define PG8_MMA(ai, bj, At, Bt) do { __builtin_amdgcn_s_setprio(3); _Pragma("unroll") for (int m = 0; m < 4; ++m) _Pragma("unroll") for (int n = 0; n < 2; ++n) _Pragma("unroll") for (int k = 0; k < 2; ++k) \
;         acc[ai][bj][m][n] = __builtin_amdgcn_mfma_f32_16x16x32_bf16(Bt[n][k], At[m][k], acc[ai][bj][m][n], 0, 0, 0); __builtin_amdgcn_s_setprio(0); } while (0)
; #define PG8_WAIT_V(n) asm volatile("s_waitcnt vmcnt(" #n ")" ::: "memory")
; #define PG8_BAR __builtin_amdgcn_s_barrier()
; template <class Epi, class Sched, bool ALIGN_EPI = false, bool SP2 = false>
; __device__ __forceinline__ void gemm_phase(PG8_LAS unsigned char* lds, const Gemm g, const Sched& S, const Epi& E) {
;     ...
;         for (int t = 0; t < nt; t += 2) {
;             const bool last = (t == nt - 2);
;             const char* a1 = cA + (size_t)(t + 1) * kstep;
;             const char* a2 = last ? nA : cA + (size_t)(t + 2) * kstep; const char* b2 = last ? nB : cB + (size_t)(t + 2) * kstep;
;             const char* a3 = a2 + kstep; const char* b3 = b2 + kstep;
;             if (last && has_next) S.a_ready(nxt);
;             if constexpr (SP2) {
;             PG8_LDB(B0, 0, 0); PG8_LDB(B1, 0, 1); PG8_SCHED; PG8_LDA(At, 0, 0); PG8_STAGE(PG8_SA(1, 1), a1 + hstep, voffA);
;             PG8_WAIT_V(8); PG8_WAIT_L(0); PG8_BAR; PG8_MMA(0, 0, At, B0); PG8_MMA(0, 1, At, B1); PG8_BAR; PG8_SCHED;
;             PG8_LDA(At, 0, 1); PG8_STAGE(PG8_SB(0, 0), b2, voffB); PG8_STAGE(PG8_SB(0, 1), b2 + hstep, voffB); PG8_STAGE(PG8_SA(0, 0), a2, voffA);
;             PG8_WAIT_V(8); PG8_WAIT_L(0); PG8_BAR; PG8_MMA(1, 0, At, B0); PG8_MMA(1, 1, At, B1); PG8_BAR; PG8_SCHED;
.LBB0_1309:
	ds_read_b128 v[148:151], v157
	ds_read_b128 v[152:155], v157 offset:1024
	ds_read_b128 v[160:163], v157 offset:2048
	ds_read_b128 v[168:171], v157 offset:3072
	ds_read_b128 v[172:175], v158
	ds_read_b128 v[176:179], v158 offset:1024
	ds_read_b128 v[180:183], v158 offset:2048
	ds_read_b128 v[184:187], v158 offset:3072
	s_add_i32 s79, s50, 2
	s_add_u32 s10, s8, 0xffea8080
	s_addc_u32 s11, s9, -1
	s_cmp_eq_u32 s76, s50
	s_cselect_b32 s50, s48, s77
	s_cselect_b32 s53, s47, s11
	s_cselect_b32 s52, s46, s10
	s_cselect_b32 s51, s49, s78
	v_lshl_add_u64 v[164:165], s[8:9], 0, v[138:139]
	s_add_i32 m0, s43, 0xc000
	ds_read_b128 v[188:191], v159
	ds_read_b128 v[192:195], v159 offset:1024
	ds_read_b128 v[196:199], v159 offset:2048
	ds_read_b128 v[200:203], v159 offset:3072
	ds_read_b128 v[204:207], v159 offset:4096
	ds_read_b128 v[208:211], v159 offset:5120
	ds_read_b128 v[212:215], v159 offset:6144
	ds_read_b128 v[216:219], v159 offset:7168
	global_load_lds_dwordx4 v[164:165], off
	v_lshl_add_u64 v[164:165], s[8:9], 0, v[142:143]
	s_add_i32 m0, s43, 0xe000
	s_nop 0
	global_load_lds_dwordx4 v[164:165], off
	s_waitcnt vmcnt(8)
	s_waitcnt lgkmcnt(0)
	s_barrier
	s_setprio 3
	s_waitcnt lgkmcnt(0)
	v_mfma_f32_16x16x32_bf16 v[126:129], v[148:151], v[188:191], v[126:129]
	v_mfma_f32_16x16x32_bf16 v[122:125], v[160:163], v[188:191], v[122:125]
	v_mfma_f32_16x16x32_bf16 v[114:117], v[148:151], v[196:199], v[114:117]
	v_mfma_f32_16x16x32_bf16 v[106:109], v[160:163], v[196:199], v[106:109]
	v_mfma_f32_16x16x32_bf16 v[98:101], v[148:151], v[204:207], v[98:101]
	v_mfma_f32_16x16x32_bf16 v[90:93], v[160:163], v[204:207], v[90:93]
	v_mfma_f32_16x16x32_bf16 v[82:85], v[148:151], v[212:215], v[82:85]
	v_mfma_f32_16x16x32_bf16 v[74:77], v[160:163], v[212:215], v[74:77]
	v_mfma_f32_16x16x32_bf16 v[126:129], v[152:155], v[192:195], v[126:129]
	v_mfma_f32_16x16x32_bf16 v[122:125], v[168:171], v[192:195], v[122:125]
	v_mfma_f32_16x16x32_bf16 v[114:117], v[152:155], v[200:203], v[114:117]
	v_mfma_f32_16x16x32_bf16 v[106:109], v[168:171], v[200:203], v[106:109]
	v_mfma_f32_16x16x32_bf16 v[98:101], v[152:155], v[208:211], v[98:101]
	v_mfma_f32_16x16x32_bf16 v[90:93], v[168:171], v[208:211], v[90:93]
	v_mfma_f32_16x16x32_bf16 v[82:85], v[152:155], v[216:219], v[82:85]
	v_mfma_f32_16x16x32_bf16 v[74:77], v[168:171], v[216:219], v[74:77]
	s_setprio 0
	s_setprio 3
	v_mfma_f32_16x16x32_bf16 v[118:121], v[172:175], v[188:191], v[118:121]
	v_mfma_f32_16x16x32_bf16 v[110:113], v[180:183], v[188:191], v[110:113]
	v_mfma_f32_16x16x32_bf16 v[102:105], v[172:175], v[196:199], v[102:105]
	v_mfma_f32_16x16x32_bf16 v[94:97], v[180:183], v[196:199], v[94:97]
	v_mfma_f32_16x16x32_bf16 v[86:89], v[172:175], v[204:207], v[86:89]
	v_mfma_f32_16x16x32_bf16 v[78:81], v[180:183], v[204:207], v[78:81]
	v_mfma_f32_16x16x32_bf16 v[70:73], v[172:175], v[212:215], v[70:73]
	v_mfma_f32_16x16x32_bf16 v[66:69], v[180:183], v[212:215], v[66:69]
	v_mfma_f32_16x16x32_bf16 v[118:121], v[176:179], v[192:195], v[118:121]
	v_mfma_f32_16x16x32_bf16 v[110:113], v[184:187], v[192:195], v[110:113]
	v_mfma_f32_16x16x32_bf16 v[102:105], v[176:179], v[200:203], v[102:105]
	v_mfma_f32_16x16x32_bf16 v[94:97], v[184:187], v[200:203], v[94:97]
	v_mfma_f32_16x16x32_bf16 v[86:89], v[176:179], v[208:211], v[86:89]
	v_mfma_f32_16x16x32_bf16 v[78:81], v[184:187], v[208:211], v[78:81]
	v_mfma_f32_16x16x32_bf16 v[70:73], v[176:179], v[216:219], v[70:73]
	s_barrier
	v_mfma_f32_16x16x32_bf16 v[66:69], v[184:187], v[216:219], v[66:69]
	s_setprio 0
	s_add_i32 s10, s66, s42
	v_lshl_add_u64 v[164:165], s[50:51], 0, v[132:133]
	s_mov_b32 m0, s10
	ds_read_b128 v[188:191], v159 offset:16384
	ds_read_b128 v[192:195], v159 offset:17408
	ds_read_b128 v[196:199], v159 offset:18432
	ds_read_b128 v[200:203], v159 offset:19456
	ds_read_b128 v[204:207], v159 offset:20480
	ds_read_b128 v[208:211], v159 offset:21504
	ds_read_b128 v[212:215], v159 offset:22528
	ds_read_b128 v[216:219], v159 offset:23552
	global_load_lds_dwordx4 v[164:165], off
	s_add_i32 m0, s10, 0x2000
	s_add_u32 s82, s50, 0x158000
	v_lshl_add_u64 v[220:221], s[50:51], 0, v[136:137]
	s_addc_u32 s83, s51, 0
	s_add_i32 s10, s67, s42
	global_load_lds_dwordx4 v[220:221], off
	v_lshl_add_u64 v[222:223], s[82:83], 0, v[132:133]
	s_mov_b32 m0, s10
	v_lshl_add_u64 v[224:225], s[52:53], 0, v[134:135]
	global_load_lds_dwordx4 v[222:223], off
	v_lshl_add_u64 v[222:223], s[82:83], 0, v[136:137]
	s_add_i32 m0, s10, 0x2000
	s_nop 0
	global_load_lds_dwordx4 v[222:223], off
	v_lshl_add_u64 v[222:223], s[52:53], 0, v[130:131]
	s_mov_b32 m0, s43
	s_nop 0
	global_load_lds_dwordx4 v[222:223], off
	s_mov_b32 m0, s54
	s_nop 0
	global_load_lds_dwordx4 v[224:225], off
	s_waitcnt vmcnt(8)
	s_waitcnt lgkmcnt(0)
	s_barrier
; #define PG8_STAGE(bufoff, gbase, voff) do { _Pragma("unroll") for (int _i = 0; _i < 2; ++_i) \
;         __builtin_amdgcn_global_load_lds((const unsigned*)((const char*)(gbase) + (voff)[_i]), (PG8_LAS unsigned*)(lds + (bufoff) + ldsw + _i * 8192), 16, 0, 0); } while (0)
; #define PG8_LDA(dst, b, h) do { _Pragma("unroll") for (int m = 0; m < 4; ++m) _Pragma("unroll") for (int k = 0; k < 2; ++k) dst[m][k] = *(const PG8_LAS bf16x8*)(lds + PG8_SA(b, h) + aoff + m * 2048 + k * 1024); } while (0)
; #define PG8_LDB(dst, b, h) do { _Pragma("unroll") for (int n = 0; n < 2; ++n) _Pragma("unroll") for (int k = 0; k < 2; ++k) dst[n][k] = *(const PG8_LAS bf16x8*)(lds + PG8_SB(b, h) + boff + n * 2048 + k * 1024); } while (0)
; #define PG8_MMA(ai, bj, At, Bt) do { __builtin_amdgcn_s_setprio(3); _Pragma("unroll") for (int m = 0; m < 4; ++m) _Pragma("unroll") for (int n = 0; n < 2; ++n) _Pragma("unroll") for (int k = 0; k < 2; ++k) \
;         acc[ai][bj][m][n] = __builtin_amdgcn_mfma_f32_16x16x32_bf16(Bt[n][k], At[m][k], acc[ai][bj][m][n], 0, 0, 0); __builtin_amdgcn_s_setprio(0); } while (0)
; #define PG8_WAIT_V(n) asm volatile("s_waitcnt vmcnt(" #n ")" ::: "memory")
; #define PG8_WAIT_L(n) asm volatile("s_waitcnt lgkmcnt(" #n ")" ::: "memory")
; #define PG8_BAR __builtin_amdgcn_s_barrier()
; #define PG8_SCHED __builtin_amdgcn_sched_barrier(0)
; template <class Epi, class Sched, bool ALIGN_EPI = false, bool SP2 = false>
; __device__ __forceinline__ void gemm_phase(PG8_LAS unsigned char* lds, const Gemm g, const Sched& S, const Epi& E) {
;     ...
;             PG8_WAIT_V(8); PG8_WAIT_L(0); PG8_BAR; PG8_MMA(1, 0, At, B0); PG8_MMA(1, 1, At, B1); PG8_BAR; PG8_SCHED;
;             PG8_LDB(B0, 1, 0); PG8_LDB(B1, 1, 1); PG8_SCHED; PG8_LDA(At, 1, 0); PG8_STAGE(PG8_SA(0, 1), a2 + hstep, voffA);
;             PG8_WAIT_V(8); PG8_WAIT_L(0); PG8_BAR; PG8_MMA(0, 0, At, B0); PG8_MMA(0, 1, At, B1); PG8_BAR; PG8_SCHED;
	s_setprio 3
	s_waitcnt lgkmcnt(0)
	v_mfma_f32_16x16x32_bf16 v[62:65], v[148:151], v[188:191], v[62:65]
	v_mfma_f32_16x16x32_bf16 v[58:61], v[160:163], v[188:191], v[58:61]
	v_mfma_f32_16x16x32_bf16 v[50:53], v[148:151], v[196:199], v[50:53]
	v_mfma_f32_16x16x32_bf16 v[42:45], v[160:163], v[196:199], v[42:45]
	v_mfma_f32_16x16x32_bf16 v[34:37], v[148:151], v[204:207], v[34:37]
	v_mfma_f32_16x16x32_bf16 v[26:29], v[160:163], v[204:207], v[26:29]
	v_mfma_f32_16x16x32_bf16 v[18:21], v[148:151], v[212:215], v[18:21]
	v_mfma_f32_16x16x32_bf16 v[10:13], v[160:163], v[212:215], v[10:13]
	v_mfma_f32_16x16x32_bf16 v[62:65], v[152:155], v[192:195], v[62:65]
	v_mfma_f32_16x16x32_bf16 v[58:61], v[168:171], v[192:195], v[58:61]
	v_mfma_f32_16x16x32_bf16 v[50:53], v[152:155], v[200:203], v[50:53]
	v_mfma_f32_16x16x32_bf16 v[42:45], v[168:171], v[200:203], v[42:45]
	v_mfma_f32_16x16x32_bf16 v[34:37], v[152:155], v[208:211], v[34:37]
	v_mfma_f32_16x16x32_bf16 v[26:29], v[168:171], v[208:211], v[26:29]
	v_mfma_f32_16x16x32_bf16 v[18:21], v[152:155], v[216:219], v[18:21]
	v_mfma_f32_16x16x32_bf16 v[10:13], v[168:171], v[216:219], v[10:13]
	s_setprio 0
	s_setprio 3
	v_mfma_f32_16x16x32_bf16 v[54:57], v[172:175], v[188:191], v[54:57]
	v_mfma_f32_16x16x32_bf16 v[46:49], v[180:183], v[188:191], v[46:49]
	v_mfma_f32_16x16x32_bf16 v[38:41], v[172:175], v[196:199], v[38:41]
	v_mfma_f32_16x16x32_bf16 v[30:33], v[180:183], v[196:199], v[30:33]
	v_mfma_f32_16x16x32_bf16 v[22:25], v[172:175], v[204:207], v[22:25]
	v_mfma_f32_16x16x32_bf16 v[14:17], v[180:183], v[204:207], v[14:17]
	v_mfma_f32_16x16x32_bf16 v[6:9], v[172:175], v[212:215], v[6:9]
	v_mfma_f32_16x16x32_bf16 v[2:5], v[180:183], v[212:215], v[2:5]
	v_mfma_f32_16x16x32_bf16 v[54:57], v[176:179], v[192:195], v[54:57]
	v_mfma_f32_16x16x32_bf16 v[46:49], v[184:187], v[192:195], v[46:49]
	v_mfma_f32_16x16x32_bf16 v[38:41], v[176:179], v[200:203], v[38:41]
	v_mfma_f32_16x16x32_bf16 v[30:33], v[184:187], v[200:203], v[30:33]
	v_mfma_f32_16x16x32_bf16 v[22:25], v[176:179], v[208:211], v[22:25]
	v_mfma_f32_16x16x32_bf16 v[14:17], v[184:187], v[208:211], v[14:17]
	v_mfma_f32_16x16x32_bf16 v[6:9], v[176:179], v[216:219], v[6:9]
	s_barrier
	v_mfma_f32_16x16x32_bf16 v[2:5], v[184:187], v[216:219], v[2:5]
	s_setprio 0
	s_add_i32 s10, 0, 0x18000
	v_add_u32_e32 v167, s10, v141
	s_add_i32 s11, 0, 0x1c000
	ds_read_b128 v[148:151], v167
	ds_read_b128 v[152:155], v167 offset:1024
	ds_read_b128 v[160:163], v167 offset:2048
	ds_read_b128 v[168:171], v167 offset:3072
	v_add_u32_e32 v167, s11, v141
	ds_read_b128 v[172:175], v167
	ds_read_b128 v[176:179], v167 offset:1024
	ds_read_b128 v[180:183], v167 offset:2048
	ds_read_b128 v[184:187], v167 offset:3072
	s_add_u32 s52, s52, 0x158000
	s_addc_u32 s53, s53, 0
	s_mov_b32 m0, s55
	v_lshl_add_u64 v[226:227], s[52:53], 0, v[130:131]
	ds_read_b128 v[188:191], v159 offset:32768
	ds_read_b128 v[192:195], v159 offset:33792
	ds_read_b128 v[196:199], v159 offset:34816
	ds_read_b128 v[200:203], v159 offset:35840
	ds_read_b128 v[204:207], v159 offset:36864
	ds_read_b128 v[208:211], v159 offset:37888
	ds_read_b128 v[212:215], v159 offset:38912
	ds_read_b128 v[216:219], v159 offset:39936
	global_load_lds_dwordx4 v[226:227], off
	v_lshl_add_u64 v[226:227], s[52:53], 0, v[134:135]
	s_mov_b32 m0, s56
	s_nop 0
	global_load_lds_dwordx4 v[226:227], off
	s_waitcnt vmcnt(8)
	s_waitcnt lgkmcnt(0)
	s_barrier
	s_setprio 3
	s_waitcnt lgkmcnt(0)
	v_mfma_f32_16x16x32_bf16 v[126:129], v[148:151], v[188:191], v[126:129]
	v_mfma_f32_16x16x32_bf16 v[122:125], v[160:163], v[188:191], v[122:125]
	v_mfma_f32_16x16x32_bf16 v[114:117], v[148:151], v[196:199], v[114:117]
	v_mfma_f32_16x16x32_bf16 v[106:109], v[160:163], v[196:199], v[106:109]
	v_mfma_f32_16x16x32_bf16 v[98:101], v[148:151], v[204:207], v[98:101]
	v_mfma_f32_16x16x32_bf16 v[90:93], v[160:163], v[204:207], v[90:93]
	v_mfma_f32_16x16x32_bf16 v[82:85], v[148:151], v[212:215], v[82:85]
	v_mfma_f32_16x16x32_bf16 v[74:77], v[160:163], v[212:215], v[74:77]
	v_mfma_f32_16x16x32_bf16 v[126:129], v[152:155], v[192:195], v[126:129]
	v_mfma_f32_16x16x32_bf16 v[122:125], v[168:171], v[192:195], v[122:125]
	v_mfma_f32_16x16x32_bf16 v[114:117], v[152:155], v[200:203], v[114:117]
	v_mfma_f32_16x16x32_bf16 v[106:109], v[168:171], v[200:203], v[106:109]
	v_mfma_f32_16x16x32_bf16 v[98:101], v[152:155], v[208:211], v[98:101]
	v_mfma_f32_16x16x32_bf16 v[90:93], v[168:171], v[208:211], v[90:93]
	v_mfma_f32_16x16x32_bf16 v[82:85], v[152:155], v[216:219], v[82:85]
	v_mfma_f32_16x16x32_bf16 v[74:77], v[168:171], v[216:219], v[74:77]
	s_setprio 0
	s_setprio 3
	v_mfma_f32_16x16x32_bf16 v[118:121], v[172:175], v[188:191], v[118:121]
	v_mfma_f32_16x16x32_bf16 v[110:113], v[180:183], v[188:191], v[110:113]
	v_mfma_f32_16x16x32_bf16 v[102:105], v[172:175], v[196:199], v[102:105]
	v_mfma_f32_16x16x32_bf16 v[94:97], v[180:183], v[196:199], v[94:97]
	v_mfma_f32_16x16x32_bf16 v[86:89], v[172:175], v[204:207], v[86:89]
	v_mfma_f32_16x16x32_bf16 v[78:81], v[180:183], v[204:207], v[78:81]
	v_mfma_f32_16x16x32_bf16 v[70:73], v[172:175], v[212:215], v[70:73]
	v_mfma_f32_16x16x32_bf16 v[66:69], v[180:183], v[212:215], v[66:69]
	v_mfma_f32_16x16x32_bf16 v[118:121], v[176:179], v[192:195], v[118:121]
	v_mfma_f32_16x16x32_bf16 v[110:113], v[184:187], v[192:195], v[110:113]
	v_mfma_f32_16x16x32_bf16 v[102:105], v[176:179], v[200:203], v[102:105]
	v_mfma_f32_16x16x32_bf16 v[94:97], v[184:187], v[200:203], v[94:97]
	v_mfma_f32_16x16x32_bf16 v[86:89], v[176:179], v[208:211], v[86:89]
	v_mfma_f32_16x16x32_bf16 v[78:81], v[184:187], v[208:211], v[78:81]
	v_mfma_f32_16x16x32_bf16 v[70:73], v[176:179], v[216:219], v[70:73]
	s_barrier
; #define PG8_STAGE(bufoff, gbase, voff) do { _Pragma("unroll") for (int _i = 0; _i < 2; ++_i) \
;         __builtin_amdgcn_global_load_lds((const unsigned*)((const char*)(gbase) + (voff)[_i]), (PG8_LAS unsigned*)(lds + (bufoff) + ldsw + _i * 8192), 16, 0, 0); } while (0)
; #define PG8_LDA(dst, b, h) do { _Pragma("unroll") for (int m = 0; m < 4; ++m) _Pragma("unroll") for (int k = 0; k < 2; ++k) dst[m][k] = *(const PG8_LAS bf16x8*)(lds + PG8_SA(b, h) + aoff + m * 2048 + k * 1024); } while (0)
; #define PG8_MMA(ai, bj, At, Bt) do { __builtin_amdgcn_s_setprio(3); _Pragma("unroll") for (int m = 0; m < 4; ++m) _Pragma("unroll") for (int n = 0; n < 2; ++n) _Pragma("unroll") for (int k = 0; k < 2; ++k) \
;         acc[ai][bj][m][n] = __builtin_amdgcn_mfma_f32_16x16x32_bf16(Bt[n][k], At[m][k], acc[ai][bj][m][n], 0, 0, 0); __builtin_amdgcn_s_setprio(0); } while (0)
; #define PG8_WAIT_V(n) asm volatile("s_waitcnt vmcnt(" #n ")" ::: "memory")
; #define PG8_WAIT_L(n) asm volatile("s_waitcnt lgkmcnt(" #n ")" ::: "memory")
; #define PG8_BAR __builtin_amdgcn_s_barrier()
; #define PG8_SCHED __builtin_amdgcn_sched_barrier(0)
; template <class Epi, class Sched, bool ALIGN_EPI = false, bool SP2 = false>
; __device__ __forceinline__ void gemm_phase(PG8_LAS unsigned char* lds, const Gemm g, const Sched& S, const Epi& E) {
;     ...
;             PG8_WAIT_V(8); PG8_WAIT_L(0); PG8_BAR; PG8_MMA(0, 0, At, B0); PG8_MMA(0, 1, At, B1); PG8_BAR; PG8_SCHED;
;             PG8_LDA(At, 1, 1); PG8_STAGE(PG8_SB(1, 0), b3, voffB); PG8_STAGE(PG8_SB(1, 1), b3 + hstep, voffB); PG8_STAGE(PG8_SA(1, 0), a3, voffA);
;             PG8_WAIT_V(8); PG8_WAIT_L(0); PG8_BAR; PG8_MMA(1, 0, At, B0); PG8_MMA(1, 1, At, B1); PG8_BAR; PG8_SCHED;
;     ...
;         if constexpr (ALIGN_EPI) { if (wr == 0) PG8_BAR; }
	v_mfma_f32_16x16x32_bf16 v[66:69], v[184:187], v[216:219], v[66:69]
	s_setprio 0
	s_add_i32 s10, s10, s42
	v_lshl_add_u64 v[164:165], v[164:165], 0, s[18:19]
	s_mov_b32 m0, s10
	ds_read_b128 v[188:191], v159 offset:49152
	ds_read_b128 v[192:195], v159 offset:50176
	ds_read_b128 v[196:199], v159 offset:51200
	ds_read_b128 v[200:203], v159 offset:52224
	ds_read_b128 v[204:207], v159 offset:53248
	ds_read_b128 v[208:211], v159 offset:54272
	ds_read_b128 v[212:215], v159 offset:55296
	ds_read_b128 v[216:219], v159 offset:56320
	global_load_lds_dwordx4 v[164:165], off
	s_add_i32 m0, s10, 0x2000
	s_add_u32 s50, s50, 0x158080
	v_lshl_add_u64 v[164:165], v[220:221], 0, s[18:19]
	s_addc_u32 s51, s51, 0
	s_add_i32 s10, s11, s42
	global_load_lds_dwordx4 v[164:165], off
	v_lshl_add_u64 v[164:165], s[50:51], 0, v[132:133]
	s_mov_b32 m0, s10
	s_nop 0
	global_load_lds_dwordx4 v[164:165], off
	v_lshl_add_u64 v[164:165], s[50:51], 0, v[136:137]
	s_add_i32 m0, s10, 0x2000
	s_nop 0
	global_load_lds_dwordx4 v[164:165], off
	v_lshl_add_u64 v[164:165], v[222:223], 0, s[18:19]
	s_mov_b32 m0, s61
	s_nop 0
	global_load_lds_dwordx4 v[164:165], off
	v_lshl_add_u64 v[164:165], v[224:225], 0, s[18:19]
	s_mov_b32 m0, s62
	s_nop 0
	global_load_lds_dwordx4 v[164:165], off
	s_waitcnt vmcnt(8)
	s_waitcnt lgkmcnt(0)
	s_barrier
	s_setprio 3
	s_waitcnt lgkmcnt(0)
	v_mfma_f32_16x16x32_bf16 v[62:65], v[148:151], v[188:191], v[62:65]
	v_mfma_f32_16x16x32_bf16 v[58:61], v[160:163], v[188:191], v[58:61]
	v_mfma_f32_16x16x32_bf16 v[50:53], v[148:151], v[196:199], v[50:53]
	v_mfma_f32_16x16x32_bf16 v[42:45], v[160:163], v[196:199], v[42:45]
	v_mfma_f32_16x16x32_bf16 v[34:37], v[148:151], v[204:207], v[34:37]
	v_mfma_f32_16x16x32_bf16 v[26:29], v[160:163], v[204:207], v[26:29]
	v_mfma_f32_16x16x32_bf16 v[18:21], v[148:151], v[212:215], v[18:21]
	v_mfma_f32_16x16x32_bf16 v[10:13], v[160:163], v[212:215], v[10:13]
	v_mfma_f32_16x16x32_bf16 v[62:65], v[152:155], v[192:195], v[62:65]
	v_mfma_f32_16x16x32_bf16 v[58:61], v[168:171], v[192:195], v[58:61]
	v_mfma_f32_16x16x32_bf16 v[50:53], v[152:155], v[200:203], v[50:53]
	v_mfma_f32_16x16x32_bf16 v[42:45], v[168:171], v[200:203], v[42:45]
	v_mfma_f32_16x16x32_bf16 v[34:37], v[152:155], v[208:211], v[34:37]
	v_mfma_f32_16x16x32_bf16 v[26:29], v[168:171], v[208:211], v[26:29]
	v_mfma_f32_16x16x32_bf16 v[18:21], v[152:155], v[216:219], v[18:21]
	v_mfma_f32_16x16x32_bf16 v[10:13], v[168:171], v[216:219], v[10:13]
	s_setprio 0
	s_setprio 3
	v_mfma_f32_16x16x32_bf16 v[54:57], v[172:175], v[188:191], v[54:57]
	v_mfma_f32_16x16x32_bf16 v[46:49], v[180:183], v[188:191], v[46:49]
	v_mfma_f32_16x16x32_bf16 v[38:41], v[172:175], v[196:199], v[38:41]
	v_mfma_f32_16x16x32_bf16 v[30:33], v[180:183], v[196:199], v[30:33]
	v_mfma_f32_16x16x32_bf16 v[22:25], v[172:175], v[204:207], v[22:25]
	v_mfma_f32_16x16x32_bf16 v[14:17], v[180:183], v[204:207], v[14:17]
	v_mfma_f32_16x16x32_bf16 v[6:9], v[172:175], v[212:215], v[6:9]
	v_mfma_f32_16x16x32_bf16 v[2:5], v[180:183], v[212:215], v[2:5]
	v_mfma_f32_16x16x32_bf16 v[54:57], v[176:179], v[192:195], v[54:57]
	v_mfma_f32_16x16x32_bf16 v[46:49], v[184:187], v[192:195], v[46:49]
	v_mfma_f32_16x16x32_bf16 v[38:41], v[176:179], v[200:203], v[38:41]
	v_mfma_f32_16x16x32_bf16 v[30:33], v[184:187], v[200:203], v[30:33]
	v_mfma_f32_16x16x32_bf16 v[22:25], v[176:179], v[208:211], v[22:25]
	v_mfma_f32_16x16x32_bf16 v[14:17], v[184:187], v[208:211], v[14:17]
	v_mfma_f32_16x16x32_bf16 v[6:9], v[176:179], v[216:219], v[6:9]
	s_barrier
	v_mfma_f32_16x16x32_bf16 v[2:5], v[184:187], v[216:219], v[2:5]
	s_setprio 0
	s_add_u32 s8, s8, 0x100
	s_addc_u32 s9, s9, 0
	s_add_u32 s77, s77, 0x100
	s_addc_u32 s78, s78, 0
	s_cmp_ge_u32 s79, s75
	s_mov_b32 s50, s79
	s_cbranch_scc0 .LBB0_1309
	s_and_b64 vcc, exec, s[24:25]
	s_cbranch_vccz .LBB0_1312
	s_barrier
